# plus GEMM K-loops: the second, already-satisfied s_waitcnt lgkmcnt(0) between the phase barrier and the first MFMA removed
# baseline (speedup 1.0000x reference)
.LBB0_849:
	ds_read_b128 v[146:149], v155
	ds_read_b128 v[160:163], v155 offset:1024
	ds_read_b128 v[164:167], v155 offset:2048
	ds_read_b128 v[168:171], v155 offset:3072
	ds_read_b128 v[172:175], v156
	ds_read_b128 v[176:179], v156 offset:1024
	ds_read_b128 v[180:183], v156 offset:2048
	ds_read_b128 v[184:187], v156 offset:3072
	s_add_u32 s74, s72, 0xfff80080
	s_addc_u32 s75, s73, -1
	s_cmp_eq_u32 s85, 28
	s_cselect_b32 s77, s63, s75
	s_cselect_b32 s76, s69, s74
	s_cselect_b32 s75, s57, s84
	s_cselect_b32 s74, s71, s83
	v_lshl_add_u64 v[220:221], s[72:73], 0, v[138:139]
	s_add_i32 m0, s3, 0xc000
	ds_read_b128 v[188:191], v157
	ds_read_b128 v[192:195], v157 offset:1024
	ds_read_b128 v[196:199], v157 offset:2048
	ds_read_b128 v[200:203], v157 offset:3072
	ds_read_b128 v[204:207], v157 offset:4096
	ds_read_b128 v[208:211], v157 offset:5120
	ds_read_b128 v[212:215], v157 offset:6144
	ds_read_b128 v[216:219], v157 offset:7168
	global_load_lds_dwordx4 v[220:221], off
	v_lshl_add_u64 v[220:221], s[72:73], 0, v[140:141]
	s_add_i32 m0, s3, 0xe000
	s_nop 0
	global_load_lds_dwordx4 v[220:221], off
	s_waitcnt vmcnt(8)
	s_waitcnt lgkmcnt(0)
	s_barrier
	s_setprio 1
	v_mfma_f32_16x16x32_bf16 v[124:127], v[146:149], v[188:191], v[124:127]
	v_mfma_f32_16x16x32_bf16 v[120:123], v[164:167], v[188:191], v[120:123]
	v_mfma_f32_16x16x32_bf16 v[108:111], v[146:149], v[196:199], v[108:111]
	v_mfma_f32_16x16x32_bf16 v[104:107], v[164:167], v[196:199], v[104:107]
	v_mfma_f32_16x16x32_bf16 v[92:95], v[146:149], v[204:207], v[92:95]
	v_mfma_f32_16x16x32_bf16 v[88:91], v[164:167], v[204:207], v[88:91]
	v_mfma_f32_16x16x32_bf16 v[76:79], v[146:149], v[212:215], v[76:79]
	v_mfma_f32_16x16x32_bf16 v[72:75], v[164:167], v[212:215], v[72:75]
	v_mfma_f32_16x16x32_bf16 v[124:127], v[160:163], v[192:195], v[124:127]
	v_mfma_f32_16x16x32_bf16 v[120:123], v[168:171], v[192:195], v[120:123]
	v_mfma_f32_16x16x32_bf16 v[108:111], v[160:163], v[200:203], v[108:111]
	v_mfma_f32_16x16x32_bf16 v[104:107], v[168:171], v[200:203], v[104:107]
	v_mfma_f32_16x16x32_bf16 v[92:95], v[160:163], v[208:211], v[92:95]
	v_mfma_f32_16x16x32_bf16 v[88:91], v[168:171], v[208:211], v[88:91]
	v_mfma_f32_16x16x32_bf16 v[76:79], v[160:163], v[216:219], v[76:79]
	v_mfma_f32_16x16x32_bf16 v[72:75], v[168:171], v[216:219], v[72:75]
	v_mfma_f32_16x16x32_bf16 v[116:119], v[172:175], v[188:191], v[116:119]
	v_mfma_f32_16x16x32_bf16 v[112:115], v[180:183], v[188:191], v[112:115]
	v_mfma_f32_16x16x32_bf16 v[100:103], v[172:175], v[196:199], v[100:103]
	v_mfma_f32_16x16x32_bf16 v[96:99], v[180:183], v[196:199], v[96:99]
	v_mfma_f32_16x16x32_bf16 v[84:87], v[172:175], v[204:207], v[84:87]
	v_mfma_f32_16x16x32_bf16 v[80:83], v[180:183], v[204:207], v[80:83]
	v_mfma_f32_16x16x32_bf16 v[68:71], v[172:175], v[212:215], v[68:71]
	v_mfma_f32_16x16x32_bf16 v[64:67], v[180:183], v[212:215], v[64:67]
	v_mfma_f32_16x16x32_bf16 v[116:119], v[176:179], v[192:195], v[116:119]
	v_mfma_f32_16x16x32_bf16 v[112:115], v[184:187], v[192:195], v[112:115]
	v_mfma_f32_16x16x32_bf16 v[100:103], v[176:179], v[200:203], v[100:103]
	v_mfma_f32_16x16x32_bf16 v[96:99], v[184:187], v[200:203], v[96:99]
	v_mfma_f32_16x16x32_bf16 v[84:87], v[176:179], v[208:211], v[84:87]
	v_mfma_f32_16x16x32_bf16 v[80:83], v[184:187], v[208:211], v[80:83]
	v_mfma_f32_16x16x32_bf16 v[68:71], v[176:179], v[216:219], v[68:71]
	v_mfma_f32_16x16x32_bf16 v[64:67], v[184:187], v[216:219], v[64:67]
	s_setprio 0
	s_barrier
	s_add_i32 s86, s79, s94
	v_lshl_add_u64 v[220:221], s[74:75], 0, v[130:131]
	s_mov_b32 m0, s86
	ds_read_b128 v[188:191], v157 offset:16384
	ds_read_b128 v[192:195], v157 offset:17408
	ds_read_b128 v[196:199], v157 offset:18432
	ds_read_b128 v[200:203], v157 offset:19456
	ds_read_b128 v[204:207], v157 offset:20480
	ds_read_b128 v[208:211], v157 offset:21504
	ds_read_b128 v[212:215], v157 offset:22528
	ds_read_b128 v[216:219], v157 offset:23552
	global_load_lds_dwordx4 v[220:221], off
	s_add_i32 m0, s86, 0x2000
	s_add_u32 s86, s74, 0x80000
	v_lshl_add_u64 v[222:223], s[74:75], 0, v[134:135]
	s_addc_u32 s87, s75, 0
	s_add_i32 s88, s81, s94
	global_load_lds_dwordx4 v[222:223], off
	v_lshl_add_u64 v[224:225], s[86:87], 0, v[130:131]
	s_mov_b32 m0, s88
	v_lshl_add_u64 v[226:227], s[76:77], 0, v[132:133]
	global_load_lds_dwordx4 v[224:225], off
	v_lshl_add_u64 v[224:225], s[86:87], 0, v[134:135]
	s_add_i32 m0, s88, 0x2000
	s_nop 0
	global_load_lds_dwordx4 v[224:225], off
	v_lshl_add_u64 v[224:225], s[76:77], 0, v[128:129]
	s_mov_b32 m0, s3
	s_nop 0
	global_load_lds_dwordx4 v[224:225], off
	s_mov_b32 m0, s6
	s_nop 0
	global_load_lds_dwordx4 v[226:227], off
	s_waitcnt vmcnt(8)
	s_waitcnt lgkmcnt(0)
	s_barrier
	s_setprio 1
	v_mfma_f32_16x16x32_bf16 v[60:63], v[146:149], v[188:191], v[60:63]
	v_mfma_f32_16x16x32_bf16 v[56:59], v[164:167], v[188:191], v[56:59]
	v_mfma_f32_16x16x32_bf16 v[44:47], v[146:149], v[196:199], v[44:47]
	v_mfma_f32_16x16x32_bf16 v[40:43], v[164:167], v[196:199], v[40:43]
	v_mfma_f32_16x16x32_bf16 v[28:31], v[146:149], v[204:207], v[28:31]
	v_mfma_f32_16x16x32_bf16 v[24:27], v[164:167], v[204:207], v[24:27]
	v_mfma_f32_16x16x32_bf16 v[12:15], v[146:149], v[212:215], v[12:15]
	v_mfma_f32_16x16x32_bf16 v[8:11], v[164:167], v[212:215], v[8:11]
	v_mfma_f32_16x16x32_bf16 v[60:63], v[160:163], v[192:195], v[60:63]
	v_mfma_f32_16x16x32_bf16 v[56:59], v[168:171], v[192:195], v[56:59]
	v_mfma_f32_16x16x32_bf16 v[44:47], v[160:163], v[200:203], v[44:47]
	v_mfma_f32_16x16x32_bf16 v[40:43], v[168:171], v[200:203], v[40:43]
	v_mfma_f32_16x16x32_bf16 v[28:31], v[160:163], v[208:211], v[28:31]
	v_mfma_f32_16x16x32_bf16 v[24:27], v[168:171], v[208:211], v[24:27]
	v_mfma_f32_16x16x32_bf16 v[12:15], v[160:163], v[216:219], v[12:15]
	v_mfma_f32_16x16x32_bf16 v[8:11], v[168:171], v[216:219], v[8:11]
	v_mfma_f32_16x16x32_bf16 v[52:55], v[172:175], v[188:191], v[52:55]
	v_mfma_f32_16x16x32_bf16 v[48:51], v[180:183], v[188:191], v[48:51]
	v_mfma_f32_16x16x32_bf16 v[36:39], v[172:175], v[196:199], v[36:39]
	v_mfma_f32_16x16x32_bf16 v[32:35], v[180:183], v[196:199], v[32:35]
	v_mfma_f32_16x16x32_bf16 v[20:23], v[172:175], v[204:207], v[20:23]
	v_mfma_f32_16x16x32_bf16 v[16:19], v[180:183], v[204:207], v[16:19]
	v_mfma_f32_16x16x32_bf16 v[4:7], v[172:175], v[212:215], v[4:7]
	v_mfma_f32_16x16x32_bf16 v[0:3], v[180:183], v[212:215], v[0:3]
	v_mfma_f32_16x16x32_bf16 v[52:55], v[176:179], v[192:195], v[52:55]
	v_mfma_f32_16x16x32_bf16 v[48:51], v[184:187], v[192:195], v[48:51]
	v_mfma_f32_16x16x32_bf16 v[36:39], v[176:179], v[200:203], v[36:39]
	v_mfma_f32_16x16x32_bf16 v[32:35], v[184:187], v[200:203], v[32:35]
	v_mfma_f32_16x16x32_bf16 v[20:23], v[176:179], v[208:211], v[20:23]
	v_mfma_f32_16x16x32_bf16 v[16:19], v[184:187], v[208:211], v[16:19]
	v_mfma_f32_16x16x32_bf16 v[4:7], v[176:179], v[216:219], v[4:7]
	v_mfma_f32_16x16x32_bf16 v[0:3], v[184:187], v[216:219], v[0:3]
	s_setprio 0
	s_barrier
	s_add_i32 s86, 0, 0x18000
	v_add_u32_e32 v159, s86, v151
	s_add_i32 s87, 0, 0x1c000
	ds_read_b128 v[146:149], v159
	ds_read_b128 v[160:163], v159 offset:1024
	ds_read_b128 v[164:167], v159 offset:2048
	ds_read_b128 v[168:171], v159 offset:3072
	v_add_u32_e32 v159, s87, v151
	ds_read_b128 v[172:175], v159
	ds_read_b128 v[176:179], v159 offset:1024
	ds_read_b128 v[180:183], v159 offset:2048
	ds_read_b128 v[184:187], v159 offset:3072
	s_add_u32 s76, s76, 0x80000
	s_addc_u32 s77, s77, 0
	s_mov_b32 m0, s7
	v_lshl_add_u64 v[228:229], s[76:77], 0, v[128:129]
	ds_read_b128 v[188:191], v157 offset:32768
	ds_read_b128 v[192:195], v157 offset:33792
	ds_read_b128 v[196:199], v157 offset:34816
	ds_read_b128 v[200:203], v157 offset:35840
	ds_read_b128 v[204:207], v157 offset:36864
	ds_read_b128 v[208:211], v157 offset:37888
	ds_read_b128 v[212:215], v157 offset:38912
	ds_read_b128 v[216:219], v157 offset:39936
	global_load_lds_dwordx4 v[228:229], off
	v_lshl_add_u64 v[228:229], s[76:77], 0, v[132:133]
	s_mov_b32 m0, s29
	s_nop 0
	global_load_lds_dwordx4 v[228:229], off
	s_waitcnt vmcnt(8)
	s_waitcnt lgkmcnt(0)
	s_barrier
	s_setprio 1
	v_mfma_f32_16x16x32_bf16 v[124:127], v[146:149], v[188:191], v[124:127]
	v_mfma_f32_16x16x32_bf16 v[120:123], v[164:167], v[188:191], v[120:123]
	v_mfma_f32_16x16x32_bf16 v[108:111], v[146:149], v[196:199], v[108:111]
	v_mfma_f32_16x16x32_bf16 v[104:107], v[164:167], v[196:199], v[104:107]
	v_mfma_f32_16x16x32_bf16 v[92:95], v[146:149], v[204:207], v[92:95]
	v_mfma_f32_16x16x32_bf16 v[88:91], v[164:167], v[204:207], v[88:91]
	v_mfma_f32_16x16x32_bf16 v[76:79], v[146:149], v[212:215], v[76:79]
	v_mfma_f32_16x16x32_bf16 v[72:75], v[164:167], v[212:215], v[72:75]
	v_mfma_f32_16x16x32_bf16 v[124:127], v[160:163], v[192:195], v[124:127]
	v_mfma_f32_16x16x32_bf16 v[120:123], v[168:171], v[192:195], v[120:123]
	v_mfma_f32_16x16x32_bf16 v[108:111], v[160:163], v[200:203], v[108:111]
	v_mfma_f32_16x16x32_bf16 v[104:107], v[168:171], v[200:203], v[104:107]
	v_mfma_f32_16x16x32_bf16 v[92:95], v[160:163], v[208:211], v[92:95]
	v_mfma_f32_16x16x32_bf16 v[88:91], v[168:171], v[208:211], v[88:91]
	v_mfma_f32_16x16x32_bf16 v[76:79], v[160:163], v[216:219], v[76:79]
	v_mfma_f32_16x16x32_bf16 v[72:75], v[168:171], v[216:219], v[72:75]
	v_mfma_f32_16x16x32_bf16 v[116:119], v[172:175], v[188:191], v[116:119]
	v_mfma_f32_16x16x32_bf16 v[112:115], v[180:183], v[188:191], v[112:115]
	v_mfma_f32_16x16x32_bf16 v[100:103], v[172:175], v[196:199], v[100:103]
	v_mfma_f32_16x16x32_bf16 v[96:99], v[180:183], v[196:199], v[96:99]
	v_mfma_f32_16x16x32_bf16 v[84:87], v[172:175], v[204:207], v[84:87]
	v_mfma_f32_16x16x32_bf16 v[80:83], v[180:183], v[204:207], v[80:83]
	v_mfma_f32_16x16x32_bf16 v[68:71], v[172:175], v[212:215], v[68:71]
	v_mfma_f32_16x16x32_bf16 v[64:67], v[180:183], v[212:215], v[64:67]
	v_mfma_f32_16x16x32_bf16 v[116:119], v[176:179], v[192:195], v[116:119]
	v_mfma_f32_16x16x32_bf16 v[112:115], v[184:187], v[192:195], v[112:115]
	v_mfma_f32_16x16x32_bf16 v[100:103], v[176:179], v[200:203], v[100:103]
	v_mfma_f32_16x16x32_bf16 v[96:99], v[184:187], v[200:203], v[96:99]
	v_mfma_f32_16x16x32_bf16 v[84:87], v[176:179], v[208:211], v[84:87]
	v_mfma_f32_16x16x32_bf16 v[80:83], v[184:187], v[208:211], v[80:83]
	v_mfma_f32_16x16x32_bf16 v[68:71], v[176:179], v[216:219], v[68:71]
	v_mfma_f32_16x16x32_bf16 v[64:67], v[184:187], v[216:219], v[64:67]
	s_setprio 0
	s_barrier
	s_add_i32 s76, s86, s94
	v_lshl_add_u64 v[220:221], v[220:221], 0, s[18:19]
	s_mov_b32 m0, s76
	ds_read_b128 v[188:191], v157 offset:49152
	ds_read_b128 v[192:195], v157 offset:50176
	ds_read_b128 v[196:199], v157 offset:51200
	ds_read_b128 v[200:203], v157 offset:52224
	ds_read_b128 v[204:207], v157 offset:53248
	ds_read_b128 v[208:211], v157 offset:54272
	ds_read_b128 v[212:215], v157 offset:55296
	ds_read_b128 v[216:219], v157 offset:56320
	global_load_lds_dwordx4 v[220:221], off
	s_add_i32 m0, s76, 0x2000
	s_add_u32 s74, s74, 0x80080
	v_lshl_add_u64 v[220:221], v[222:223], 0, s[18:19]
	s_addc_u32 s75, s75, 0
	s_add_i32 s76, s87, s94
	global_load_lds_dwordx4 v[220:221], off
	v_lshl_add_u64 v[220:221], s[74:75], 0, v[130:131]
	s_mov_b32 m0, s76
	s_nop 0
	global_load_lds_dwordx4 v[220:221], off
	v_lshl_add_u64 v[220:221], s[74:75], 0, v[134:135]
	s_add_i32 m0, s76, 0x2000
	s_nop 0
	global_load_lds_dwordx4 v[220:221], off
	v_lshl_add_u64 v[220:221], v[224:225], 0, s[18:19]
	s_mov_b32 m0, s34
	s_nop 0
	global_load_lds_dwordx4 v[220:221], off
	v_lshl_add_u64 v[220:221], v[226:227], 0, s[18:19]
	s_mov_b32 m0, s35
	s_nop 0
	global_load_lds_dwordx4 v[220:221], off
	s_waitcnt vmcnt(8)
	s_waitcnt lgkmcnt(0)
	s_barrier
	s_setprio 1
	v_mfma_f32_16x16x32_bf16 v[60:63], v[146:149], v[188:191], v[60:63]
	v_mfma_f32_16x16x32_bf16 v[56:59], v[164:167], v[188:191], v[56:59]
	v_mfma_f32_16x16x32_bf16 v[44:47], v[146:149], v[196:199], v[44:47]
	v_mfma_f32_16x16x32_bf16 v[40:43], v[164:167], v[196:199], v[40:43]
	v_mfma_f32_16x16x32_bf16 v[28:31], v[146:149], v[204:207], v[28:31]
	v_mfma_f32_16x16x32_bf16 v[24:27], v[164:167], v[204:207], v[24:27]
	v_mfma_f32_16x16x32_bf16 v[12:15], v[146:149], v[212:215], v[12:15]
	v_mfma_f32_16x16x32_bf16 v[8:11], v[164:167], v[212:215], v[8:11]
	v_mfma_f32_16x16x32_bf16 v[60:63], v[160:163], v[192:195], v[60:63]
	v_mfma_f32_16x16x32_bf16 v[56:59], v[168:171], v[192:195], v[56:59]
	v_mfma_f32_16x16x32_bf16 v[44:47], v[160:163], v[200:203], v[44:47]
	v_mfma_f32_16x16x32_bf16 v[40:43], v[168:171], v[200:203], v[40:43]
	v_mfma_f32_16x16x32_bf16 v[28:31], v[160:163], v[208:211], v[28:31]
	v_mfma_f32_16x16x32_bf16 v[24:27], v[168:171], v[208:211], v[24:27]
	v_mfma_f32_16x16x32_bf16 v[12:15], v[160:163], v[216:219], v[12:15]
	v_mfma_f32_16x16x32_bf16 v[8:11], v[168:171], v[216:219], v[8:11]
	v_mfma_f32_16x16x32_bf16 v[52:55], v[172:175], v[188:191], v[52:55]
	v_mfma_f32_16x16x32_bf16 v[48:51], v[180:183], v[188:191], v[48:51]
	v_mfma_f32_16x16x32_bf16 v[36:39], v[172:175], v[196:199], v[36:39]
	v_mfma_f32_16x16x32_bf16 v[32:35], v[180:183], v[196:199], v[32:35]
	v_mfma_f32_16x16x32_bf16 v[20:23], v[172:175], v[204:207], v[20:23]
	v_mfma_f32_16x16x32_bf16 v[16:19], v[180:183], v[204:207], v[16:19]
	v_mfma_f32_16x16x32_bf16 v[4:7], v[172:175], v[212:215], v[4:7]
	v_mfma_f32_16x16x32_bf16 v[0:3], v[180:183], v[212:215], v[0:3]
	v_mfma_f32_16x16x32_bf16 v[52:55], v[176:179], v[192:195], v[52:55]
	v_mfma_f32_16x16x32_bf16 v[48:51], v[184:187], v[192:195], v[48:51]
	v_mfma_f32_16x16x32_bf16 v[36:39], v[176:179], v[200:203], v[36:39]
	v_mfma_f32_16x16x32_bf16 v[32:35], v[184:187], v[200:203], v[32:35]
	v_mfma_f32_16x16x32_bf16 v[20:23], v[176:179], v[208:211], v[20:23]
	v_mfma_f32_16x16x32_bf16 v[16:19], v[184:187], v[208:211], v[16:19]
	v_mfma_f32_16x16x32_bf16 v[4:7], v[176:179], v[216:219], v[4:7]
	v_mfma_f32_16x16x32_bf16 v[0:3], v[184:187], v[216:219], v[0:3]
	s_setprio 0
	s_barrier
	s_add_i32 s85, s85, 2
	s_add_u32 s72, s72, 0x100
	s_addc_u32 s73, s73, 0
	s_add_u32 s83, s83, 0x100
	s_addc_u32 s84, s84, 0
	s_cmp_gt_u32 s85, 29
	s_cbranch_scc0 .LBB0_849
	s_and_b64 vcc, exec, s[20:21]
	s_cbranch_vccz .LBB0_852
	s_barrier

.LBB0_946:
	ds_read_b128 v[148:151], v143
	ds_read_b128 v[152:155], v143 offset:1024
	ds_read_b128 v[156:159], v143 offset:2048
	ds_read_b128 v[160:163], v143 offset:3072
	ds_read_b128 v[164:167], v144
	ds_read_b128 v[168:171], v144 offset:1024
	ds_read_b128 v[172:175], v144 offset:2048
	ds_read_b128 v[176:179], v144 offset:3072
	s_add_u32 s18, s14, s16
	s_addc_u32 s19, s15, s17
	s_add_u32 s18, s18, 0x7498100
	s_addc_u32 s19, s19, 0
	s_add_u32 s20, s24, s16
	s_addc_u32 s21, s25, s17
	s_add_u32 s69, s20, 0x1308100
	s_addc_u32 s70, s21, 0
	s_cmpk_eq_i32 s16, 0xf00
	s_cselect_b32 s21, s11, s19
	s_cselect_b32 s20, s10, s18
	s_cselect_b32 s19, s9, s70
	s_cselect_b32 s18, s8, s69
	s_mov_b32 m0, s46
	v_lshl_add_u64 v[212:213], v[136:137], 0, s[16:17]
	ds_read_b128 v[180:183], v145
	ds_read_b128 v[184:187], v145 offset:1024
	ds_read_b128 v[188:191], v145 offset:2048
	ds_read_b128 v[192:195], v145 offset:3072
	ds_read_b128 v[196:199], v145 offset:4096
	ds_read_b128 v[200:203], v145 offset:5120
	ds_read_b128 v[204:207], v145 offset:6144
	ds_read_b128 v[208:211], v145 offset:7168
	global_load_lds_dwordx4 v[212:213], off
	v_lshl_add_u64 v[212:213], v[138:139], 0, s[16:17]
	s_mov_b32 m0, s56
	s_nop 0
	global_load_lds_dwordx4 v[212:213], off
	s_waitcnt vmcnt(8)
	s_waitcnt lgkmcnt(0)
	s_barrier
	s_setprio 1
	v_mfma_f32_16x16x32_bf16 v[124:127], v[148:151], v[180:183], v[124:127]
	v_mfma_f32_16x16x32_bf16 v[120:123], v[156:159], v[180:183], v[120:123]
	v_mfma_f32_16x16x32_bf16 v[108:111], v[148:151], v[188:191], v[108:111]
	v_mfma_f32_16x16x32_bf16 v[104:107], v[156:159], v[188:191], v[104:107]
	v_mfma_f32_16x16x32_bf16 v[92:95], v[148:151], v[196:199], v[92:95]
	v_mfma_f32_16x16x32_bf16 v[88:91], v[156:159], v[196:199], v[88:91]
	v_mfma_f32_16x16x32_bf16 v[76:79], v[148:151], v[204:207], v[76:79]
	v_mfma_f32_16x16x32_bf16 v[72:75], v[156:159], v[204:207], v[72:75]
	v_mfma_f32_16x16x32_bf16 v[124:127], v[152:155], v[184:187], v[124:127]
	v_mfma_f32_16x16x32_bf16 v[120:123], v[160:163], v[184:187], v[120:123]
	v_mfma_f32_16x16x32_bf16 v[108:111], v[152:155], v[192:195], v[108:111]
	v_mfma_f32_16x16x32_bf16 v[104:107], v[160:163], v[192:195], v[104:107]
	v_mfma_f32_16x16x32_bf16 v[92:95], v[152:155], v[200:203], v[92:95]
	v_mfma_f32_16x16x32_bf16 v[88:91], v[160:163], v[200:203], v[88:91]
	v_mfma_f32_16x16x32_bf16 v[76:79], v[152:155], v[208:211], v[76:79]
	v_mfma_f32_16x16x32_bf16 v[72:75], v[160:163], v[208:211], v[72:75]
	v_mfma_f32_16x16x32_bf16 v[116:119], v[164:167], v[180:183], v[116:119]
	v_mfma_f32_16x16x32_bf16 v[112:115], v[172:175], v[180:183], v[112:115]
	v_mfma_f32_16x16x32_bf16 v[100:103], v[164:167], v[188:191], v[100:103]
	v_mfma_f32_16x16x32_bf16 v[96:99], v[172:175], v[188:191], v[96:99]
	v_mfma_f32_16x16x32_bf16 v[84:87], v[164:167], v[196:199], v[84:87]
	v_mfma_f32_16x16x32_bf16 v[80:83], v[172:175], v[196:199], v[80:83]
	v_mfma_f32_16x16x32_bf16 v[68:71], v[164:167], v[204:207], v[68:71]
	v_mfma_f32_16x16x32_bf16 v[64:67], v[172:175], v[204:207], v[64:67]
	v_mfma_f32_16x16x32_bf16 v[116:119], v[168:171], v[184:187], v[116:119]
	v_mfma_f32_16x16x32_bf16 v[112:115], v[176:179], v[184:187], v[112:115]
	v_mfma_f32_16x16x32_bf16 v[100:103], v[168:171], v[192:195], v[100:103]
	v_mfma_f32_16x16x32_bf16 v[96:99], v[176:179], v[192:195], v[96:99]
	v_mfma_f32_16x16x32_bf16 v[84:87], v[168:171], v[200:203], v[84:87]
	v_mfma_f32_16x16x32_bf16 v[80:83], v[176:179], v[200:203], v[80:83]
	v_mfma_f32_16x16x32_bf16 v[68:71], v[168:171], v[208:211], v[68:71]
	v_mfma_f32_16x16x32_bf16 v[64:67], v[176:179], v[208:211], v[64:67]
	s_setprio 0
	s_barrier
	s_mov_b32 m0, s57
	v_lshl_add_u64 v[212:213], s[18:19], 0, v[132:133]
	s_add_u32 s70, s18, 0x80000
	ds_read_b128 v[180:183], v145 offset:16384
	ds_read_b128 v[184:187], v145 offset:17408
	ds_read_b128 v[188:191], v145 offset:18432
	ds_read_b128 v[192:195], v145 offset:19456
	ds_read_b128 v[196:199], v145 offset:20480
	ds_read_b128 v[200:203], v145 offset:21504
	ds_read_b128 v[204:207], v145 offset:22528
	ds_read_b128 v[208:211], v145 offset:23552
	global_load_lds_dwordx4 v[212:213], off
	v_lshl_add_u64 v[214:215], s[18:19], 0, v[128:129]
	s_mov_b32 m0, s62
	s_addc_u32 s71, s19, 0
	global_load_lds_dwordx4 v[214:215], off
	v_lshl_add_u64 v[216:217], s[70:71], 0, v[132:133]
	s_mov_b32 m0, s63
	v_lshl_add_u64 v[218:219], s[20:21], 0, v[130:131]
	global_load_lds_dwordx4 v[216:217], off
	v_lshl_add_u64 v[216:217], s[70:71], 0, v[128:129]
	s_mov_b32 m0, s64
	s_nop 0
	global_load_lds_dwordx4 v[216:217], off
	v_lshl_add_u64 v[216:217], s[20:21], 0, v[134:135]
	s_mov_b32 m0, s3
	s_nop 0
	global_load_lds_dwordx4 v[216:217], off
	s_mov_b32 m0, s6
	s_nop 0
	global_load_lds_dwordx4 v[218:219], off
	s_waitcnt vmcnt(8)
	s_waitcnt lgkmcnt(0)
	s_barrier
	s_setprio 1
	v_mfma_f32_16x16x32_bf16 v[60:63], v[148:151], v[180:183], v[60:63]
	v_mfma_f32_16x16x32_bf16 v[56:59], v[156:159], v[180:183], v[56:59]
	v_mfma_f32_16x16x32_bf16 v[44:47], v[148:151], v[188:191], v[44:47]
	v_mfma_f32_16x16x32_bf16 v[40:43], v[156:159], v[188:191], v[40:43]
	v_mfma_f32_16x16x32_bf16 v[28:31], v[148:151], v[196:199], v[28:31]
	v_mfma_f32_16x16x32_bf16 v[24:27], v[156:159], v[196:199], v[24:27]
	v_mfma_f32_16x16x32_bf16 v[12:15], v[148:151], v[204:207], v[12:15]
	v_mfma_f32_16x16x32_bf16 v[8:11], v[156:159], v[204:207], v[8:11]
	v_mfma_f32_16x16x32_bf16 v[60:63], v[152:155], v[184:187], v[60:63]
	v_mfma_f32_16x16x32_bf16 v[56:59], v[160:163], v[184:187], v[56:59]
	v_mfma_f32_16x16x32_bf16 v[44:47], v[152:155], v[192:195], v[44:47]
	v_mfma_f32_16x16x32_bf16 v[40:43], v[160:163], v[192:195], v[40:43]
	v_mfma_f32_16x16x32_bf16 v[28:31], v[152:155], v[200:203], v[28:31]
	v_mfma_f32_16x16x32_bf16 v[24:27], v[160:163], v[200:203], v[24:27]
	v_mfma_f32_16x16x32_bf16 v[12:15], v[152:155], v[208:211], v[12:15]
	v_mfma_f32_16x16x32_bf16 v[8:11], v[160:163], v[208:211], v[8:11]
	v_mfma_f32_16x16x32_bf16 v[52:55], v[164:167], v[180:183], v[52:55]
	v_mfma_f32_16x16x32_bf16 v[48:51], v[172:175], v[180:183], v[48:51]
	v_mfma_f32_16x16x32_bf16 v[36:39], v[164:167], v[188:191], v[36:39]
	v_mfma_f32_16x16x32_bf16 v[32:35], v[172:175], v[188:191], v[32:35]
	v_mfma_f32_16x16x32_bf16 v[20:23], v[164:167], v[196:199], v[20:23]
	v_mfma_f32_16x16x32_bf16 v[16:19], v[172:175], v[196:199], v[16:19]
	v_mfma_f32_16x16x32_bf16 v[4:7], v[164:167], v[204:207], v[4:7]
	v_mfma_f32_16x16x32_bf16 v[0:3], v[172:175], v[204:207], v[0:3]
	v_mfma_f32_16x16x32_bf16 v[52:55], v[168:171], v[184:187], v[52:55]
	v_mfma_f32_16x16x32_bf16 v[48:51], v[176:179], v[184:187], v[48:51]
	v_mfma_f32_16x16x32_bf16 v[36:39], v[168:171], v[192:195], v[36:39]
	v_mfma_f32_16x16x32_bf16 v[32:35], v[176:179], v[192:195], v[32:35]
	v_mfma_f32_16x16x32_bf16 v[20:23], v[168:171], v[200:203], v[20:23]
	v_mfma_f32_16x16x32_bf16 v[16:19], v[176:179], v[200:203], v[16:19]
	v_mfma_f32_16x16x32_bf16 v[4:7], v[168:171], v[208:211], v[4:7]
	v_mfma_f32_16x16x32_bf16 v[0:3], v[176:179], v[208:211], v[0:3]
	s_setprio 0
	s_barrier
	ds_read_b128 v[148:151], v146
	ds_read_b128 v[152:155], v146 offset:1024
	ds_read_b128 v[156:159], v146 offset:2048
	ds_read_b128 v[160:163], v146 offset:3072
	ds_read_b128 v[164:167], v147
	ds_read_b128 v[168:171], v147 offset:1024
	ds_read_b128 v[172:175], v147 offset:2048
	ds_read_b128 v[176:179], v147 offset:3072
	s_add_u32 s20, s20, 0x80000
	s_addc_u32 s21, s21, 0
	s_mov_b32 m0, s7
	v_lshl_add_u64 v[220:221], s[20:21], 0, v[134:135]
	ds_read_b128 v[180:183], v145 offset:32768
	ds_read_b128 v[184:187], v145 offset:33792
	ds_read_b128 v[188:191], v145 offset:34816
	ds_read_b128 v[192:195], v145 offset:35840
	ds_read_b128 v[196:199], v145 offset:36864
	ds_read_b128 v[200:203], v145 offset:37888
	ds_read_b128 v[204:207], v145 offset:38912
	ds_read_b128 v[208:211], v145 offset:39936
	global_load_lds_dwordx4 v[220:221], off
	v_lshl_add_u64 v[220:221], s[20:21], 0, v[130:131]
	s_mov_b32 m0, s29
	s_nop 0
	global_load_lds_dwordx4 v[220:221], off
	s_waitcnt vmcnt(8)
	s_waitcnt lgkmcnt(0)
	s_barrier
	s_setprio 1
	v_mfma_f32_16x16x32_bf16 v[124:127], v[148:151], v[180:183], v[124:127]
	v_mfma_f32_16x16x32_bf16 v[120:123], v[156:159], v[180:183], v[120:123]
	v_mfma_f32_16x16x32_bf16 v[108:111], v[148:151], v[188:191], v[108:111]
	v_mfma_f32_16x16x32_bf16 v[104:107], v[156:159], v[188:191], v[104:107]
	v_mfma_f32_16x16x32_bf16 v[92:95], v[148:151], v[196:199], v[92:95]
	v_mfma_f32_16x16x32_bf16 v[88:91], v[156:159], v[196:199], v[88:91]
	v_mfma_f32_16x16x32_bf16 v[76:79], v[148:151], v[204:207], v[76:79]
	v_mfma_f32_16x16x32_bf16 v[72:75], v[156:159], v[204:207], v[72:75]
	v_mfma_f32_16x16x32_bf16 v[124:127], v[152:155], v[184:187], v[124:127]
	v_mfma_f32_16x16x32_bf16 v[120:123], v[160:163], v[184:187], v[120:123]
	v_mfma_f32_16x16x32_bf16 v[108:111], v[152:155], v[192:195], v[108:111]
	v_mfma_f32_16x16x32_bf16 v[104:107], v[160:163], v[192:195], v[104:107]
	v_mfma_f32_16x16x32_bf16 v[92:95], v[152:155], v[200:203], v[92:95]
	v_mfma_f32_16x16x32_bf16 v[88:91], v[160:163], v[200:203], v[88:91]
	v_mfma_f32_16x16x32_bf16 v[76:79], v[152:155], v[208:211], v[76:79]
	v_mfma_f32_16x16x32_bf16 v[72:75], v[160:163], v[208:211], v[72:75]
	v_mfma_f32_16x16x32_bf16 v[116:119], v[164:167], v[180:183], v[116:119]
	v_mfma_f32_16x16x32_bf16 v[112:115], v[172:175], v[180:183], v[112:115]
	v_mfma_f32_16x16x32_bf16 v[100:103], v[164:167], v[188:191], v[100:103]
	v_mfma_f32_16x16x32_bf16 v[96:99], v[172:175], v[188:191], v[96:99]
	v_mfma_f32_16x16x32_bf16 v[84:87], v[164:167], v[196:199], v[84:87]
	v_mfma_f32_16x16x32_bf16 v[80:83], v[172:175], v[196:199], v[80:83]
	v_mfma_f32_16x16x32_bf16 v[68:71], v[164:167], v[204:207], v[68:71]
	v_mfma_f32_16x16x32_bf16 v[64:67], v[172:175], v[204:207], v[64:67]
	v_mfma_f32_16x16x32_bf16 v[116:119], v[168:171], v[184:187], v[116:119]
	v_mfma_f32_16x16x32_bf16 v[112:115], v[176:179], v[184:187], v[112:115]
	v_mfma_f32_16x16x32_bf16 v[100:103], v[168:171], v[192:195], v[100:103]
	v_mfma_f32_16x16x32_bf16 v[96:99], v[176:179], v[192:195], v[96:99]
	v_mfma_f32_16x16x32_bf16 v[84:87], v[168:171], v[200:203], v[84:87]
	v_mfma_f32_16x16x32_bf16 v[80:83], v[176:179], v[200:203], v[80:83]
	v_mfma_f32_16x16x32_bf16 v[68:71], v[168:171], v[208:211], v[68:71]
	v_mfma_f32_16x16x32_bf16 v[64:67], v[176:179], v[208:211], v[64:67]
	s_setprio 0
	s_barrier
	s_mov_b32 m0, s65
	v_lshl_add_u64 v[212:213], v[212:213], 0, s[12:13]
	s_add_u32 s18, s18, 0x80080
	ds_read_b128 v[180:183], v145 offset:49152
	ds_read_b128 v[184:187], v145 offset:50176
	ds_read_b128 v[188:191], v145 offset:51200
	ds_read_b128 v[192:195], v145 offset:52224
	ds_read_b128 v[196:199], v145 offset:53248
	ds_read_b128 v[200:203], v145 offset:54272
	ds_read_b128 v[204:207], v145 offset:55296
	ds_read_b128 v[208:211], v145 offset:56320
	global_load_lds_dwordx4 v[212:213], off
	v_lshl_add_u64 v[212:213], v[214:215], 0, s[12:13]
	s_mov_b32 m0, s66
	s_addc_u32 s19, s19, 0
	global_load_lds_dwordx4 v[212:213], off
	v_lshl_add_u64 v[212:213], s[18:19], 0, v[132:133]
	s_mov_b32 m0, s67
	s_nop 0
	global_load_lds_dwordx4 v[212:213], off
	v_lshl_add_u64 v[212:213], s[18:19], 0, v[128:129]
	s_mov_b32 m0, s68
	s_nop 0
	global_load_lds_dwordx4 v[212:213], off
	v_lshl_add_u64 v[212:213], v[216:217], 0, s[12:13]
	s_mov_b32 m0, s30
	s_nop 0
	global_load_lds_dwordx4 v[212:213], off
	v_lshl_add_u64 v[212:213], v[218:219], 0, s[12:13]
	s_mov_b32 m0, s34
	s_nop 0
	global_load_lds_dwordx4 v[212:213], off
	s_waitcnt vmcnt(8)
	s_waitcnt lgkmcnt(0)
	s_barrier
	s_setprio 1
	v_mfma_f32_16x16x32_bf16 v[60:63], v[148:151], v[180:183], v[60:63]
	v_mfma_f32_16x16x32_bf16 v[56:59], v[156:159], v[180:183], v[56:59]
	v_mfma_f32_16x16x32_bf16 v[44:47], v[148:151], v[188:191], v[44:47]
	v_mfma_f32_16x16x32_bf16 v[40:43], v[156:159], v[188:191], v[40:43]
	v_mfma_f32_16x16x32_bf16 v[28:31], v[148:151], v[196:199], v[28:31]
	v_mfma_f32_16x16x32_bf16 v[24:27], v[156:159], v[196:199], v[24:27]
	v_mfma_f32_16x16x32_bf16 v[12:15], v[148:151], v[204:207], v[12:15]
	v_mfma_f32_16x16x32_bf16 v[8:11], v[156:159], v[204:207], v[8:11]
	v_mfma_f32_16x16x32_bf16 v[60:63], v[152:155], v[184:187], v[60:63]
	v_mfma_f32_16x16x32_bf16 v[56:59], v[160:163], v[184:187], v[56:59]
	v_mfma_f32_16x16x32_bf16 v[44:47], v[152:155], v[192:195], v[44:47]
	v_mfma_f32_16x16x32_bf16 v[40:43], v[160:163], v[192:195], v[40:43]
	v_mfma_f32_16x16x32_bf16 v[28:31], v[152:155], v[200:203], v[28:31]
	v_mfma_f32_16x16x32_bf16 v[24:27], v[160:163], v[200:203], v[24:27]
	v_mfma_f32_16x16x32_bf16 v[12:15], v[152:155], v[208:211], v[12:15]
	v_mfma_f32_16x16x32_bf16 v[8:11], v[160:163], v[208:211], v[8:11]
	v_mfma_f32_16x16x32_bf16 v[52:55], v[164:167], v[180:183], v[52:55]
	v_mfma_f32_16x16x32_bf16 v[48:51], v[172:175], v[180:183], v[48:51]
	v_mfma_f32_16x16x32_bf16 v[36:39], v[164:167], v[188:191], v[36:39]
	v_mfma_f32_16x16x32_bf16 v[32:35], v[172:175], v[188:191], v[32:35]
	v_mfma_f32_16x16x32_bf16 v[20:23], v[164:167], v[196:199], v[20:23]
	v_mfma_f32_16x16x32_bf16 v[16:19], v[172:175], v[196:199], v[16:19]
	v_mfma_f32_16x16x32_bf16 v[4:7], v[164:167], v[204:207], v[4:7]
	v_mfma_f32_16x16x32_bf16 v[0:3], v[172:175], v[204:207], v[0:3]
	v_mfma_f32_16x16x32_bf16 v[52:55], v[168:171], v[184:187], v[52:55]
	v_mfma_f32_16x16x32_bf16 v[48:51], v[176:179], v[184:187], v[48:51]
	v_mfma_f32_16x16x32_bf16 v[36:39], v[168:171], v[192:195], v[36:39]
	v_mfma_f32_16x16x32_bf16 v[32:35], v[176:179], v[192:195], v[32:35]
	v_mfma_f32_16x16x32_bf16 v[20:23], v[168:171], v[200:203], v[20:23]
	v_mfma_f32_16x16x32_bf16 v[16:19], v[176:179], v[200:203], v[16:19]
	v_mfma_f32_16x16x32_bf16 v[4:7], v[168:171], v[208:211], v[4:7]
	v_mfma_f32_16x16x32_bf16 v[0:3], v[176:179], v[208:211], v[0:3]
	s_setprio 0
	s_barrier
	s_add_i32 s35, s35, 2
	s_add_u32 s16, s16, 0x100
	s_addc_u32 s17, s17, 0
	s_cmp_gt_u32 s35, 29
	s_cbranch_scc0 .LBB0_946
	s_cmpk_lt_u32 s80, 0x100
	s_cbranch_scc0 .LBB0_949
	s_barrier

.LBB0_1693:
	ds_read_b128 v[140:143], v149
	ds_read_b128 v[152:155], v149 offset:1024
	ds_read_b128 v[156:159], v149 offset:2048
	ds_read_b128 v[160:163], v149 offset:3072
	ds_read_b128 v[164:167], v150
	ds_read_b128 v[168:171], v150 offset:1024
	ds_read_b128 v[172:175], v150 offset:2048
	ds_read_b128 v[176:179], v150 offset:3072
	s_add_u32 s76, s74, 0xfff80080
	s_addc_u32 s77, s75, -1
	s_cmp_eq_u32 s86, 28
	s_cselect_b32 s79, s67, s77
	s_cselect_b32 s78, s73, s76
	s_cselect_b32 s77, s65, s85
	s_cselect_b32 s76, s83, s84
	v_lshl_add_u64 v[212:213], s[74:75], 0, v[132:133]
	s_add_i32 m0, s6, 0xc000
	ds_read_b128 v[180:183], v151
	ds_read_b128 v[184:187], v151 offset:1024
	ds_read_b128 v[188:191], v151 offset:2048
	ds_read_b128 v[192:195], v151 offset:3072
	ds_read_b128 v[196:199], v151 offset:4096
	ds_read_b128 v[200:203], v151 offset:5120
	ds_read_b128 v[204:207], v151 offset:6144
	ds_read_b128 v[208:211], v151 offset:7168
	global_load_lds_dwordx4 v[212:213], off
	v_lshl_add_u64 v[212:213], s[74:75], 0, v[134:135]
	s_add_i32 m0, s6, 0xe000
	s_nop 0
	global_load_lds_dwordx4 v[212:213], off
	s_waitcnt vmcnt(8)
	s_waitcnt lgkmcnt(0)
	s_barrier
	s_setprio 1
	v_mfma_f32_16x16x32_bf16 v[124:127], v[140:143], v[180:183], v[124:127]
	v_mfma_f32_16x16x32_bf16 v[120:123], v[156:159], v[180:183], v[120:123]
	v_mfma_f32_16x16x32_bf16 v[108:111], v[140:143], v[188:191], v[108:111]
	v_mfma_f32_16x16x32_bf16 v[104:107], v[156:159], v[188:191], v[104:107]
	v_mfma_f32_16x16x32_bf16 v[92:95], v[140:143], v[196:199], v[92:95]
	v_mfma_f32_16x16x32_bf16 v[88:91], v[156:159], v[196:199], v[88:91]
	v_mfma_f32_16x16x32_bf16 v[76:79], v[140:143], v[204:207], v[76:79]
	v_mfma_f32_16x16x32_bf16 v[72:75], v[156:159], v[204:207], v[72:75]
	v_mfma_f32_16x16x32_bf16 v[124:127], v[152:155], v[184:187], v[124:127]
	v_mfma_f32_16x16x32_bf16 v[120:123], v[160:163], v[184:187], v[120:123]
	v_mfma_f32_16x16x32_bf16 v[108:111], v[152:155], v[192:195], v[108:111]
	v_mfma_f32_16x16x32_bf16 v[104:107], v[160:163], v[192:195], v[104:107]
	v_mfma_f32_16x16x32_bf16 v[92:95], v[152:155], v[200:203], v[92:95]
	v_mfma_f32_16x16x32_bf16 v[88:91], v[160:163], v[200:203], v[88:91]
	v_mfma_f32_16x16x32_bf16 v[76:79], v[152:155], v[208:211], v[76:79]
	v_mfma_f32_16x16x32_bf16 v[72:75], v[160:163], v[208:211], v[72:75]
	v_mfma_f32_16x16x32_bf16 v[116:119], v[164:167], v[180:183], v[116:119]
	v_mfma_f32_16x16x32_bf16 v[112:115], v[172:175], v[180:183], v[112:115]
	v_mfma_f32_16x16x32_bf16 v[100:103], v[164:167], v[188:191], v[100:103]
	v_mfma_f32_16x16x32_bf16 v[96:99], v[172:175], v[188:191], v[96:99]
	v_mfma_f32_16x16x32_bf16 v[84:87], v[164:167], v[196:199], v[84:87]
	v_mfma_f32_16x16x32_bf16 v[80:83], v[172:175], v[196:199], v[80:83]
	v_mfma_f32_16x16x32_bf16 v[68:71], v[164:167], v[204:207], v[68:71]
	v_mfma_f32_16x16x32_bf16 v[64:67], v[172:175], v[204:207], v[64:67]
	v_mfma_f32_16x16x32_bf16 v[116:119], v[168:171], v[184:187], v[116:119]
	v_mfma_f32_16x16x32_bf16 v[112:115], v[176:179], v[184:187], v[112:115]
	v_mfma_f32_16x16x32_bf16 v[100:103], v[168:171], v[192:195], v[100:103]
	v_mfma_f32_16x16x32_bf16 v[96:99], v[176:179], v[192:195], v[96:99]
	v_mfma_f32_16x16x32_bf16 v[84:87], v[168:171], v[200:203], v[84:87]
	v_mfma_f32_16x16x32_bf16 v[80:83], v[176:179], v[200:203], v[80:83]
	v_mfma_f32_16x16x32_bf16 v[68:71], v[168:171], v[208:211], v[68:71]
	v_mfma_f32_16x16x32_bf16 v[64:67], v[176:179], v[208:211], v[64:67]
	s_setprio 0
	s_barrier
	s_add_i32 s87, s57, s94
	v_lshl_add_u64 v[212:213], s[76:77], 0, v[128:129]
	s_mov_b32 m0, s87
	ds_read_b128 v[180:183], v151 offset:16384
	ds_read_b128 v[184:187], v151 offset:17408
	ds_read_b128 v[188:191], v151 offset:18432
	ds_read_b128 v[192:195], v151 offset:19456
	ds_read_b128 v[196:199], v151 offset:20480
	ds_read_b128 v[200:203], v151 offset:21504
	ds_read_b128 v[204:207], v151 offset:22528
	ds_read_b128 v[208:211], v151 offset:23552
	global_load_lds_dwordx4 v[212:213], off
	s_add_i32 m0, s87, 0x2000
	s_add_u32 s88, s76, 0x80000
	v_lshl_add_u64 v[214:215], s[76:77], 0, v[130:131]
	s_addc_u32 s89, s77, 0
	s_add_i32 s87, s81, s94
	global_load_lds_dwordx4 v[214:215], off
	v_lshl_add_u64 v[216:217], s[88:89], 0, v[128:129]
	s_mov_b32 m0, s87
	v_lshl_add_u64 v[218:219], s[78:79], 0, v[130:131]
	global_load_lds_dwordx4 v[216:217], off
	v_lshl_add_u64 v[216:217], s[88:89], 0, v[130:131]
	s_add_i32 m0, s87, 0x2000
	s_nop 0
	global_load_lds_dwordx4 v[216:217], off
	v_lshl_add_u64 v[216:217], s[78:79], 0, v[128:129]
	s_mov_b32 m0, s6
	s_nop 0
	global_load_lds_dwordx4 v[216:217], off
	s_mov_b32 m0, s7
	s_nop 0
	global_load_lds_dwordx4 v[218:219], off
	s_waitcnt vmcnt(8)
	s_waitcnt lgkmcnt(0)
	s_barrier
	s_setprio 1
	v_mfma_f32_16x16x32_bf16 v[60:63], v[140:143], v[180:183], v[60:63]
	v_mfma_f32_16x16x32_bf16 v[56:59], v[156:159], v[180:183], v[56:59]
	v_mfma_f32_16x16x32_bf16 v[44:47], v[140:143], v[188:191], v[44:47]
	v_mfma_f32_16x16x32_bf16 v[40:43], v[156:159], v[188:191], v[40:43]
	v_mfma_f32_16x16x32_bf16 v[28:31], v[140:143], v[196:199], v[28:31]
	v_mfma_f32_16x16x32_bf16 v[24:27], v[156:159], v[196:199], v[24:27]
	v_mfma_f32_16x16x32_bf16 v[12:15], v[140:143], v[204:207], v[12:15]
	v_mfma_f32_16x16x32_bf16 v[8:11], v[156:159], v[204:207], v[8:11]
	v_mfma_f32_16x16x32_bf16 v[60:63], v[152:155], v[184:187], v[60:63]
	v_mfma_f32_16x16x32_bf16 v[56:59], v[160:163], v[184:187], v[56:59]
	v_mfma_f32_16x16x32_bf16 v[44:47], v[152:155], v[192:195], v[44:47]
	v_mfma_f32_16x16x32_bf16 v[40:43], v[160:163], v[192:195], v[40:43]
	v_mfma_f32_16x16x32_bf16 v[28:31], v[152:155], v[200:203], v[28:31]
	v_mfma_f32_16x16x32_bf16 v[24:27], v[160:163], v[200:203], v[24:27]
	v_mfma_f32_16x16x32_bf16 v[12:15], v[152:155], v[208:211], v[12:15]
	v_mfma_f32_16x16x32_bf16 v[8:11], v[160:163], v[208:211], v[8:11]
	v_mfma_f32_16x16x32_bf16 v[52:55], v[164:167], v[180:183], v[52:55]
	v_mfma_f32_16x16x32_bf16 v[48:51], v[172:175], v[180:183], v[48:51]
	v_mfma_f32_16x16x32_bf16 v[36:39], v[164:167], v[188:191], v[36:39]
	v_mfma_f32_16x16x32_bf16 v[32:35], v[172:175], v[188:191], v[32:35]
	v_mfma_f32_16x16x32_bf16 v[20:23], v[164:167], v[196:199], v[20:23]
	v_mfma_f32_16x16x32_bf16 v[16:19], v[172:175], v[196:199], v[16:19]
	v_mfma_f32_16x16x32_bf16 v[4:7], v[164:167], v[204:207], v[4:7]
	v_mfma_f32_16x16x32_bf16 v[0:3], v[172:175], v[204:207], v[0:3]
	v_mfma_f32_16x16x32_bf16 v[52:55], v[168:171], v[184:187], v[52:55]
	v_mfma_f32_16x16x32_bf16 v[48:51], v[176:179], v[184:187], v[48:51]
	v_mfma_f32_16x16x32_bf16 v[36:39], v[168:171], v[192:195], v[36:39]
	v_mfma_f32_16x16x32_bf16 v[32:35], v[176:179], v[192:195], v[32:35]
	v_mfma_f32_16x16x32_bf16 v[20:23], v[168:171], v[200:203], v[20:23]
	v_mfma_f32_16x16x32_bf16 v[16:19], v[176:179], v[200:203], v[16:19]
	v_mfma_f32_16x16x32_bf16 v[4:7], v[168:171], v[208:211], v[4:7]
	v_mfma_f32_16x16x32_bf16 v[0:3], v[176:179], v[208:211], v[0:3]
	s_setprio 0
	s_barrier
	s_add_i32 s87, 0, 0x18000
	s_add_i32 s88, 0, 0x1c000
	v_add_u32_e32 v160, s87, v145
	v_add_u32_e32 v176, s88, v145
	ds_read_b128 v[140:143], v160
	ds_read_b128 v[152:155], v160 offset:1024
	ds_read_b128 v[156:159], v160 offset:2048
	ds_read_b128 v[160:163], v160 offset:3072
	ds_read_b128 v[164:167], v176
	ds_read_b128 v[168:171], v176 offset:1024
	ds_read_b128 v[172:175], v176 offset:2048
	ds_read_b128 v[176:179], v176 offset:3072
	s_add_u32 s78, s78, 0x80000
	s_addc_u32 s79, s79, 0
	s_mov_b32 m0, s29
	v_lshl_add_u64 v[220:221], s[78:79], 0, v[128:129]
	ds_read_b128 v[180:183], v151 offset:32768
	ds_read_b128 v[184:187], v151 offset:33792
	ds_read_b128 v[188:191], v151 offset:34816
	ds_read_b128 v[192:195], v151 offset:35840
	ds_read_b128 v[196:199], v151 offset:36864
	ds_read_b128 v[200:203], v151 offset:37888
	ds_read_b128 v[204:207], v151 offset:38912
	ds_read_b128 v[208:211], v151 offset:39936
	global_load_lds_dwordx4 v[220:221], off
	v_lshl_add_u64 v[220:221], s[78:79], 0, v[130:131]
	s_mov_b32 m0, s30
	s_nop 0
	global_load_lds_dwordx4 v[220:221], off
	s_waitcnt vmcnt(8)
	s_waitcnt lgkmcnt(0)
	s_barrier
	s_setprio 1
	v_mfma_f32_16x16x32_bf16 v[124:127], v[140:143], v[180:183], v[124:127]
	v_mfma_f32_16x16x32_bf16 v[120:123], v[156:159], v[180:183], v[120:123]
	v_mfma_f32_16x16x32_bf16 v[108:111], v[140:143], v[188:191], v[108:111]
	v_mfma_f32_16x16x32_bf16 v[104:107], v[156:159], v[188:191], v[104:107]
	v_mfma_f32_16x16x32_bf16 v[92:95], v[140:143], v[196:199], v[92:95]
	v_mfma_f32_16x16x32_bf16 v[88:91], v[156:159], v[196:199], v[88:91]
	v_mfma_f32_16x16x32_bf16 v[76:79], v[140:143], v[204:207], v[76:79]
	v_mfma_f32_16x16x32_bf16 v[72:75], v[156:159], v[204:207], v[72:75]
	v_mfma_f32_16x16x32_bf16 v[124:127], v[152:155], v[184:187], v[124:127]
	v_mfma_f32_16x16x32_bf16 v[120:123], v[160:163], v[184:187], v[120:123]
	v_mfma_f32_16x16x32_bf16 v[108:111], v[152:155], v[192:195], v[108:111]
	v_mfma_f32_16x16x32_bf16 v[104:107], v[160:163], v[192:195], v[104:107]
	v_mfma_f32_16x16x32_bf16 v[92:95], v[152:155], v[200:203], v[92:95]
	v_mfma_f32_16x16x32_bf16 v[88:91], v[160:163], v[200:203], v[88:91]
	v_mfma_f32_16x16x32_bf16 v[76:79], v[152:155], v[208:211], v[76:79]
	v_mfma_f32_16x16x32_bf16 v[72:75], v[160:163], v[208:211], v[72:75]
	v_mfma_f32_16x16x32_bf16 v[116:119], v[164:167], v[180:183], v[116:119]
	v_mfma_f32_16x16x32_bf16 v[112:115], v[172:175], v[180:183], v[112:115]
	v_mfma_f32_16x16x32_bf16 v[100:103], v[164:167], v[188:191], v[100:103]
	v_mfma_f32_16x16x32_bf16 v[96:99], v[172:175], v[188:191], v[96:99]
	v_mfma_f32_16x16x32_bf16 v[84:87], v[164:167], v[196:199], v[84:87]
	v_mfma_f32_16x16x32_bf16 v[80:83], v[172:175], v[196:199], v[80:83]
	v_mfma_f32_16x16x32_bf16 v[68:71], v[164:167], v[204:207], v[68:71]
	v_mfma_f32_16x16x32_bf16 v[64:67], v[172:175], v[204:207], v[64:67]
	v_mfma_f32_16x16x32_bf16 v[116:119], v[168:171], v[184:187], v[116:119]
	v_mfma_f32_16x16x32_bf16 v[112:115], v[176:179], v[184:187], v[112:115]
	v_mfma_f32_16x16x32_bf16 v[100:103], v[168:171], v[192:195], v[100:103]
	v_mfma_f32_16x16x32_bf16 v[96:99], v[176:179], v[192:195], v[96:99]
	v_mfma_f32_16x16x32_bf16 v[84:87], v[168:171], v[200:203], v[84:87]
	v_mfma_f32_16x16x32_bf16 v[80:83], v[176:179], v[200:203], v[80:83]
	v_mfma_f32_16x16x32_bf16 v[68:71], v[168:171], v[208:211], v[68:71]
	v_mfma_f32_16x16x32_bf16 v[64:67], v[176:179], v[208:211], v[64:67]
	s_setprio 0
	s_barrier
	s_add_i32 s78, s87, s94
	v_lshl_add_u64 v[212:213], v[212:213], 0, s[58:59]
	s_mov_b32 m0, s78
	ds_read_b128 v[180:183], v151 offset:49152
	ds_read_b128 v[184:187], v151 offset:50176
	ds_read_b128 v[188:191], v151 offset:51200
	ds_read_b128 v[192:195], v151 offset:52224
	ds_read_b128 v[196:199], v151 offset:53248
	ds_read_b128 v[200:203], v151 offset:54272
	ds_read_b128 v[204:207], v151 offset:55296
	ds_read_b128 v[208:211], v151 offset:56320
	global_load_lds_dwordx4 v[212:213], off
	s_add_i32 m0, s78, 0x2000
	s_add_u32 s76, s76, 0x80080
	v_lshl_add_u64 v[212:213], v[214:215], 0, s[58:59]
	s_addc_u32 s77, s77, 0
	s_add_i32 s78, s88, s94
	global_load_lds_dwordx4 v[212:213], off
	v_lshl_add_u64 v[212:213], s[76:77], 0, v[128:129]
	s_mov_b32 m0, s78
	s_nop 0
	global_load_lds_dwordx4 v[212:213], off
	v_lshl_add_u64 v[212:213], s[76:77], 0, v[130:131]
	s_add_i32 m0, s78, 0x2000
	s_nop 0
	global_load_lds_dwordx4 v[212:213], off
	v_lshl_add_u64 v[212:213], v[216:217], 0, s[58:59]
	s_mov_b32 m0, s34
	s_nop 0
	global_load_lds_dwordx4 v[212:213], off
	v_lshl_add_u64 v[212:213], v[218:219], 0, s[58:59]
	s_mov_b32 m0, s35
	s_nop 0
	global_load_lds_dwordx4 v[212:213], off
	s_waitcnt vmcnt(8)
	s_waitcnt lgkmcnt(0)
	s_barrier
	s_setprio 1
	v_mfma_f32_16x16x32_bf16 v[60:63], v[140:143], v[180:183], v[60:63]
	v_mfma_f32_16x16x32_bf16 v[56:59], v[156:159], v[180:183], v[56:59]
	v_mfma_f32_16x16x32_bf16 v[44:47], v[140:143], v[188:191], v[44:47]
	v_mfma_f32_16x16x32_bf16 v[40:43], v[156:159], v[188:191], v[40:43]
	v_mfma_f32_16x16x32_bf16 v[28:31], v[140:143], v[196:199], v[28:31]
	v_mfma_f32_16x16x32_bf16 v[24:27], v[156:159], v[196:199], v[24:27]
	v_mfma_f32_16x16x32_bf16 v[12:15], v[140:143], v[204:207], v[12:15]
	v_mfma_f32_16x16x32_bf16 v[8:11], v[156:159], v[204:207], v[8:11]
	v_mfma_f32_16x16x32_bf16 v[60:63], v[152:155], v[184:187], v[60:63]
	v_mfma_f32_16x16x32_bf16 v[56:59], v[160:163], v[184:187], v[56:59]
	v_mfma_f32_16x16x32_bf16 v[44:47], v[152:155], v[192:195], v[44:47]
	v_mfma_f32_16x16x32_bf16 v[40:43], v[160:163], v[192:195], v[40:43]
	v_mfma_f32_16x16x32_bf16 v[28:31], v[152:155], v[200:203], v[28:31]
	v_mfma_f32_16x16x32_bf16 v[24:27], v[160:163], v[200:203], v[24:27]
	v_mfma_f32_16x16x32_bf16 v[12:15], v[152:155], v[208:211], v[12:15]
	v_mfma_f32_16x16x32_bf16 v[8:11], v[160:163], v[208:211], v[8:11]
	v_mfma_f32_16x16x32_bf16 v[52:55], v[164:167], v[180:183], v[52:55]
	v_mfma_f32_16x16x32_bf16 v[48:51], v[172:175], v[180:183], v[48:51]
	v_mfma_f32_16x16x32_bf16 v[36:39], v[164:167], v[188:191], v[36:39]
	v_mfma_f32_16x16x32_bf16 v[32:35], v[172:175], v[188:191], v[32:35]
	v_mfma_f32_16x16x32_bf16 v[20:23], v[164:167], v[196:199], v[20:23]
	v_mfma_f32_16x16x32_bf16 v[16:19], v[172:175], v[196:199], v[16:19]
	v_mfma_f32_16x16x32_bf16 v[4:7], v[164:167], v[204:207], v[4:7]
	v_mfma_f32_16x16x32_bf16 v[0:3], v[172:175], v[204:207], v[0:3]
	v_mfma_f32_16x16x32_bf16 v[52:55], v[168:171], v[184:187], v[52:55]
	v_mfma_f32_16x16x32_bf16 v[48:51], v[176:179], v[184:187], v[48:51]
	v_mfma_f32_16x16x32_bf16 v[36:39], v[168:171], v[192:195], v[36:39]
	v_mfma_f32_16x16x32_bf16 v[32:35], v[176:179], v[192:195], v[32:35]
	v_mfma_f32_16x16x32_bf16 v[20:23], v[168:171], v[200:203], v[20:23]
	v_mfma_f32_16x16x32_bf16 v[16:19], v[176:179], v[200:203], v[16:19]
	v_mfma_f32_16x16x32_bf16 v[4:7], v[168:171], v[208:211], v[4:7]
	v_mfma_f32_16x16x32_bf16 v[0:3], v[176:179], v[208:211], v[0:3]
	s_setprio 0
	s_barrier
	s_add_i32 s86, s86, 2
	s_add_u32 s74, s74, 0x100
	s_addc_u32 s75, s75, 0
	s_add_u32 s84, s84, 0x100
	s_addc_u32 s85, s85, 0
	s_cmp_gt_u32 s86, 29
	s_cbranch_scc0 .LBB0_1693
	s_and_b64 vcc, exec, s[60:61]
	s_cbranch_vccz .LBB0_1696
	s_barrier

.LBB0_1785:
	ds_read_b128 v[146:149], v155
	ds_read_b128 v[160:163], v155 offset:1024
	ds_read_b128 v[164:167], v155 offset:2048
	ds_read_b128 v[168:171], v155 offset:3072
	ds_read_b128 v[172:175], v156
	ds_read_b128 v[176:179], v156 offset:1024
	ds_read_b128 v[180:183], v156 offset:2048
	ds_read_b128 v[184:187], v156 offset:3072
	s_add_u32 s60, s72, 0xfff80080
	s_addc_u32 s61, s73, -1
	s_cmp_eq_u32 s78, 28
	s_cselect_b32 s77, s56, s61
	s_cselect_b32 s76, s57, s60
	s_cselect_b32 s75, s23, s71
	s_cselect_b32 s74, s63, s69
	v_lshl_add_u64 v[220:221], s[72:73], 0, v[138:139]
	s_add_i32 m0, s6, 0xc000
	ds_read_b128 v[188:191], v157
	ds_read_b128 v[192:195], v157 offset:1024
	ds_read_b128 v[196:199], v157 offset:2048
	ds_read_b128 v[200:203], v157 offset:3072
	ds_read_b128 v[204:207], v157 offset:4096
	ds_read_b128 v[208:211], v157 offset:5120
	ds_read_b128 v[212:215], v157 offset:6144
	ds_read_b128 v[216:219], v157 offset:7168
	global_load_lds_dwordx4 v[220:221], off
	v_lshl_add_u64 v[220:221], s[72:73], 0, v[140:141]
	s_add_i32 m0, s6, 0xe000
	s_nop 0
	global_load_lds_dwordx4 v[220:221], off
	s_waitcnt vmcnt(8)
	s_waitcnt lgkmcnt(0)
	s_barrier
	s_setprio 1
	v_mfma_f32_16x16x32_bf16 v[124:127], v[146:149], v[188:191], v[124:127]
	v_mfma_f32_16x16x32_bf16 v[120:123], v[164:167], v[188:191], v[120:123]
	v_mfma_f32_16x16x32_bf16 v[108:111], v[146:149], v[196:199], v[108:111]
	v_mfma_f32_16x16x32_bf16 v[104:107], v[164:167], v[196:199], v[104:107]
	v_mfma_f32_16x16x32_bf16 v[92:95], v[146:149], v[204:207], v[92:95]
	v_mfma_f32_16x16x32_bf16 v[88:91], v[164:167], v[204:207], v[88:91]
	v_mfma_f32_16x16x32_bf16 v[76:79], v[146:149], v[212:215], v[76:79]
	v_mfma_f32_16x16x32_bf16 v[72:75], v[164:167], v[212:215], v[72:75]
	v_mfma_f32_16x16x32_bf16 v[124:127], v[160:163], v[192:195], v[124:127]
	v_mfma_f32_16x16x32_bf16 v[120:123], v[168:171], v[192:195], v[120:123]
	v_mfma_f32_16x16x32_bf16 v[108:111], v[160:163], v[200:203], v[108:111]
	v_mfma_f32_16x16x32_bf16 v[104:107], v[168:171], v[200:203], v[104:107]
	v_mfma_f32_16x16x32_bf16 v[92:95], v[160:163], v[208:211], v[92:95]
	v_mfma_f32_16x16x32_bf16 v[88:91], v[168:171], v[208:211], v[88:91]
	v_mfma_f32_16x16x32_bf16 v[76:79], v[160:163], v[216:219], v[76:79]
	v_mfma_f32_16x16x32_bf16 v[72:75], v[168:171], v[216:219], v[72:75]
	v_mfma_f32_16x16x32_bf16 v[116:119], v[172:175], v[188:191], v[116:119]
	v_mfma_f32_16x16x32_bf16 v[112:115], v[180:183], v[188:191], v[112:115]
	v_mfma_f32_16x16x32_bf16 v[100:103], v[172:175], v[196:199], v[100:103]
	v_mfma_f32_16x16x32_bf16 v[96:99], v[180:183], v[196:199], v[96:99]
	v_mfma_f32_16x16x32_bf16 v[84:87], v[172:175], v[204:207], v[84:87]
	v_mfma_f32_16x16x32_bf16 v[80:83], v[180:183], v[204:207], v[80:83]
	v_mfma_f32_16x16x32_bf16 v[68:71], v[172:175], v[212:215], v[68:71]
	v_mfma_f32_16x16x32_bf16 v[64:67], v[180:183], v[212:215], v[64:67]
	v_mfma_f32_16x16x32_bf16 v[116:119], v[176:179], v[192:195], v[116:119]
	v_mfma_f32_16x16x32_bf16 v[112:115], v[184:187], v[192:195], v[112:115]
	v_mfma_f32_16x16x32_bf16 v[100:103], v[176:179], v[200:203], v[100:103]
	v_mfma_f32_16x16x32_bf16 v[96:99], v[184:187], v[200:203], v[96:99]
	v_mfma_f32_16x16x32_bf16 v[84:87], v[176:179], v[208:211], v[84:87]
	v_mfma_f32_16x16x32_bf16 v[80:83], v[184:187], v[208:211], v[80:83]
	v_mfma_f32_16x16x32_bf16 v[68:71], v[176:179], v[216:219], v[68:71]
	v_mfma_f32_16x16x32_bf16 v[64:67], v[184:187], v[216:219], v[64:67]
	s_setprio 0
	s_barrier
	s_add_i32 s60, s35, s94
	v_lshl_add_u64 v[220:221], s[74:75], 0, v[130:131]
	s_mov_b32 m0, s60
	ds_read_b128 v[188:191], v157 offset:16384
	ds_read_b128 v[192:195], v157 offset:17408
	ds_read_b128 v[196:199], v157 offset:18432
	ds_read_b128 v[200:203], v157 offset:19456
	ds_read_b128 v[204:207], v157 offset:20480
	ds_read_b128 v[208:211], v157 offset:21504
	ds_read_b128 v[212:215], v157 offset:22528
	ds_read_b128 v[216:219], v157 offset:23552
	global_load_lds_dwordx4 v[220:221], off
	s_add_i32 m0, s60, 0x2000
	s_add_u32 s80, s74, 0x80000
	v_lshl_add_u64 v[222:223], s[74:75], 0, v[134:135]
	s_addc_u32 s81, s75, 0
	s_add_i32 s60, s46, s94
	global_load_lds_dwordx4 v[222:223], off
	v_lshl_add_u64 v[224:225], s[80:81], 0, v[130:131]
	s_mov_b32 m0, s60
	v_lshl_add_u64 v[226:227], s[76:77], 0, v[132:133]
	global_load_lds_dwordx4 v[224:225], off
	v_lshl_add_u64 v[224:225], s[80:81], 0, v[134:135]
	s_add_i32 m0, s60, 0x2000
	s_nop 0
	global_load_lds_dwordx4 v[224:225], off
	v_lshl_add_u64 v[224:225], s[76:77], 0, v[128:129]
	s_mov_b32 m0, s6
	s_nop 0
	global_load_lds_dwordx4 v[224:225], off
	s_mov_b32 m0, s7
	s_nop 0
	global_load_lds_dwordx4 v[226:227], off
	s_waitcnt vmcnt(8)
	s_waitcnt lgkmcnt(0)
	s_barrier
	s_setprio 1
	v_mfma_f32_16x16x32_bf16 v[60:63], v[146:149], v[188:191], v[60:63]
	v_mfma_f32_16x16x32_bf16 v[56:59], v[164:167], v[188:191], v[56:59]
	v_mfma_f32_16x16x32_bf16 v[44:47], v[146:149], v[196:199], v[44:47]
	v_mfma_f32_16x16x32_bf16 v[40:43], v[164:167], v[196:199], v[40:43]
	v_mfma_f32_16x16x32_bf16 v[28:31], v[146:149], v[204:207], v[28:31]
	v_mfma_f32_16x16x32_bf16 v[24:27], v[164:167], v[204:207], v[24:27]
	v_mfma_f32_16x16x32_bf16 v[12:15], v[146:149], v[212:215], v[12:15]
	v_mfma_f32_16x16x32_bf16 v[8:11], v[164:167], v[212:215], v[8:11]
	v_mfma_f32_16x16x32_bf16 v[60:63], v[160:163], v[192:195], v[60:63]
	v_mfma_f32_16x16x32_bf16 v[56:59], v[168:171], v[192:195], v[56:59]
	v_mfma_f32_16x16x32_bf16 v[44:47], v[160:163], v[200:203], v[44:47]
	v_mfma_f32_16x16x32_bf16 v[40:43], v[168:171], v[200:203], v[40:43]
	v_mfma_f32_16x16x32_bf16 v[28:31], v[160:163], v[208:211], v[28:31]
	v_mfma_f32_16x16x32_bf16 v[24:27], v[168:171], v[208:211], v[24:27]
	v_mfma_f32_16x16x32_bf16 v[12:15], v[160:163], v[216:219], v[12:15]
	v_mfma_f32_16x16x32_bf16 v[8:11], v[168:171], v[216:219], v[8:11]
	v_mfma_f32_16x16x32_bf16 v[52:55], v[172:175], v[188:191], v[52:55]
	v_mfma_f32_16x16x32_bf16 v[48:51], v[180:183], v[188:191], v[48:51]
	v_mfma_f32_16x16x32_bf16 v[36:39], v[172:175], v[196:199], v[36:39]
	v_mfma_f32_16x16x32_bf16 v[32:35], v[180:183], v[196:199], v[32:35]
	v_mfma_f32_16x16x32_bf16 v[20:23], v[172:175], v[204:207], v[20:23]
	v_mfma_f32_16x16x32_bf16 v[16:19], v[180:183], v[204:207], v[16:19]
	v_mfma_f32_16x16x32_bf16 v[4:7], v[172:175], v[212:215], v[4:7]
	v_mfma_f32_16x16x32_bf16 v[0:3], v[180:183], v[212:215], v[0:3]
	v_mfma_f32_16x16x32_bf16 v[52:55], v[176:179], v[192:195], v[52:55]
	v_mfma_f32_16x16x32_bf16 v[48:51], v[184:187], v[192:195], v[48:51]
	v_mfma_f32_16x16x32_bf16 v[36:39], v[176:179], v[200:203], v[36:39]
	v_mfma_f32_16x16x32_bf16 v[32:35], v[184:187], v[200:203], v[32:35]
	v_mfma_f32_16x16x32_bf16 v[20:23], v[176:179], v[208:211], v[20:23]
	v_mfma_f32_16x16x32_bf16 v[16:19], v[184:187], v[208:211], v[16:19]
	v_mfma_f32_16x16x32_bf16 v[4:7], v[176:179], v[216:219], v[4:7]
	v_mfma_f32_16x16x32_bf16 v[0:3], v[184:187], v[216:219], v[0:3]
	s_setprio 0
	s_barrier
	s_add_i32 s60, 0, 0x18000
	v_add_u32_e32 v159, s60, v151
	s_add_i32 s61, 0, 0x1c000
	ds_read_b128 v[146:149], v159
	ds_read_b128 v[160:163], v159 offset:1024
	ds_read_b128 v[164:167], v159 offset:2048
	ds_read_b128 v[168:171], v159 offset:3072
	v_add_u32_e32 v159, s61, v151
	ds_read_b128 v[172:175], v159
	ds_read_b128 v[176:179], v159 offset:1024
	ds_read_b128 v[180:183], v159 offset:2048
	ds_read_b128 v[184:187], v159 offset:3072
	s_add_u32 s76, s76, 0x80000
	s_addc_u32 s77, s77, 0
	s_mov_b32 m0, s12
	v_lshl_add_u64 v[228:229], s[76:77], 0, v[128:129]
	ds_read_b128 v[188:191], v157 offset:32768
	ds_read_b128 v[192:195], v157 offset:33792
	ds_read_b128 v[196:199], v157 offset:34816
	ds_read_b128 v[200:203], v157 offset:35840
	ds_read_b128 v[204:207], v157 offset:36864
	ds_read_b128 v[208:211], v157 offset:37888
	ds_read_b128 v[212:215], v157 offset:38912
	ds_read_b128 v[216:219], v157 offset:39936
	global_load_lds_dwordx4 v[228:229], off
	v_lshl_add_u64 v[228:229], s[76:77], 0, v[132:133]
	s_mov_b32 m0, s13
	s_nop 0
	global_load_lds_dwordx4 v[228:229], off
	s_waitcnt vmcnt(8)
	s_waitcnt lgkmcnt(0)
	s_barrier
	s_setprio 1
	v_mfma_f32_16x16x32_bf16 v[124:127], v[146:149], v[188:191], v[124:127]
	v_mfma_f32_16x16x32_bf16 v[120:123], v[164:167], v[188:191], v[120:123]
	v_mfma_f32_16x16x32_bf16 v[108:111], v[146:149], v[196:199], v[108:111]
	v_mfma_f32_16x16x32_bf16 v[104:107], v[164:167], v[196:199], v[104:107]
	v_mfma_f32_16x16x32_bf16 v[92:95], v[146:149], v[204:207], v[92:95]
	v_mfma_f32_16x16x32_bf16 v[88:91], v[164:167], v[204:207], v[88:91]
	v_mfma_f32_16x16x32_bf16 v[76:79], v[146:149], v[212:215], v[76:79]
	v_mfma_f32_16x16x32_bf16 v[72:75], v[164:167], v[212:215], v[72:75]
	v_mfma_f32_16x16x32_bf16 v[124:127], v[160:163], v[192:195], v[124:127]
	v_mfma_f32_16x16x32_bf16 v[120:123], v[168:171], v[192:195], v[120:123]
	v_mfma_f32_16x16x32_bf16 v[108:111], v[160:163], v[200:203], v[108:111]
	v_mfma_f32_16x16x32_bf16 v[104:107], v[168:171], v[200:203], v[104:107]
	v_mfma_f32_16x16x32_bf16 v[92:95], v[160:163], v[208:211], v[92:95]
	v_mfma_f32_16x16x32_bf16 v[88:91], v[168:171], v[208:211], v[88:91]
	v_mfma_f32_16x16x32_bf16 v[76:79], v[160:163], v[216:219], v[76:79]
	v_mfma_f32_16x16x32_bf16 v[72:75], v[168:171], v[216:219], v[72:75]
	v_mfma_f32_16x16x32_bf16 v[116:119], v[172:175], v[188:191], v[116:119]
	v_mfma_f32_16x16x32_bf16 v[112:115], v[180:183], v[188:191], v[112:115]
	v_mfma_f32_16x16x32_bf16 v[100:103], v[172:175], v[196:199], v[100:103]
	v_mfma_f32_16x16x32_bf16 v[96:99], v[180:183], v[196:199], v[96:99]
	v_mfma_f32_16x16x32_bf16 v[84:87], v[172:175], v[204:207], v[84:87]
	v_mfma_f32_16x16x32_bf16 v[80:83], v[180:183], v[204:207], v[80:83]
	v_mfma_f32_16x16x32_bf16 v[68:71], v[172:175], v[212:215], v[68:71]
	v_mfma_f32_16x16x32_bf16 v[64:67], v[180:183], v[212:215], v[64:67]
	v_mfma_f32_16x16x32_bf16 v[116:119], v[176:179], v[192:195], v[116:119]
	v_mfma_f32_16x16x32_bf16 v[112:115], v[184:187], v[192:195], v[112:115]
	v_mfma_f32_16x16x32_bf16 v[100:103], v[176:179], v[200:203], v[100:103]
	v_mfma_f32_16x16x32_bf16 v[96:99], v[184:187], v[200:203], v[96:99]
	v_mfma_f32_16x16x32_bf16 v[84:87], v[176:179], v[208:211], v[84:87]
	v_mfma_f32_16x16x32_bf16 v[80:83], v[184:187], v[208:211], v[80:83]
	v_mfma_f32_16x16x32_bf16 v[68:71], v[176:179], v[216:219], v[68:71]
	v_mfma_f32_16x16x32_bf16 v[64:67], v[184:187], v[216:219], v[64:67]
	s_setprio 0
	s_barrier
	s_add_i32 s60, s60, s94
	v_lshl_add_u64 v[220:221], v[220:221], 0, s[20:21]
	s_mov_b32 m0, s60
	ds_read_b128 v[188:191], v157 offset:49152
	ds_read_b128 v[192:195], v157 offset:50176
	ds_read_b128 v[196:199], v157 offset:51200
	ds_read_b128 v[200:203], v157 offset:52224
	ds_read_b128 v[204:207], v157 offset:53248
	ds_read_b128 v[208:211], v157 offset:54272
	ds_read_b128 v[212:215], v157 offset:55296
	ds_read_b128 v[216:219], v157 offset:56320
	global_load_lds_dwordx4 v[220:221], off
	s_add_i32 m0, s60, 0x2000
	s_add_u32 s74, s74, 0x80080
	v_lshl_add_u64 v[220:221], v[222:223], 0, s[20:21]
	s_addc_u32 s75, s75, 0
	s_add_i32 s60, s61, s94
	global_load_lds_dwordx4 v[220:221], off
	v_lshl_add_u64 v[220:221], s[74:75], 0, v[130:131]
	s_mov_b32 m0, s60
	s_nop 0
	global_load_lds_dwordx4 v[220:221], off
	v_lshl_add_u64 v[220:221], s[74:75], 0, v[134:135]
	s_add_i32 m0, s60, 0x2000
	s_nop 0
	global_load_lds_dwordx4 v[220:221], off
	v_lshl_add_u64 v[220:221], v[224:225], 0, s[20:21]
	s_mov_b32 m0, s30
	s_nop 0
	global_load_lds_dwordx4 v[220:221], off
	v_lshl_add_u64 v[220:221], v[226:227], 0, s[20:21]
	s_mov_b32 m0, s34
	s_nop 0
	global_load_lds_dwordx4 v[220:221], off
	s_waitcnt vmcnt(8)
	s_waitcnt lgkmcnt(0)
	s_barrier
	s_setprio 1
	v_mfma_f32_16x16x32_bf16 v[60:63], v[146:149], v[188:191], v[60:63]
	v_mfma_f32_16x16x32_bf16 v[56:59], v[164:167], v[188:191], v[56:59]
	v_mfma_f32_16x16x32_bf16 v[44:47], v[146:149], v[196:199], v[44:47]
	v_mfma_f32_16x16x32_bf16 v[40:43], v[164:167], v[196:199], v[40:43]
	v_mfma_f32_16x16x32_bf16 v[28:31], v[146:149], v[204:207], v[28:31]
	v_mfma_f32_16x16x32_bf16 v[24:27], v[164:167], v[204:207], v[24:27]
	v_mfma_f32_16x16x32_bf16 v[12:15], v[146:149], v[212:215], v[12:15]
	v_mfma_f32_16x16x32_bf16 v[8:11], v[164:167], v[212:215], v[8:11]
	v_mfma_f32_16x16x32_bf16 v[60:63], v[160:163], v[192:195], v[60:63]
	v_mfma_f32_16x16x32_bf16 v[56:59], v[168:171], v[192:195], v[56:59]
	v_mfma_f32_16x16x32_bf16 v[44:47], v[160:163], v[200:203], v[44:47]
	v_mfma_f32_16x16x32_bf16 v[40:43], v[168:171], v[200:203], v[40:43]
	v_mfma_f32_16x16x32_bf16 v[28:31], v[160:163], v[208:211], v[28:31]
	v_mfma_f32_16x16x32_bf16 v[24:27], v[168:171], v[208:211], v[24:27]
	v_mfma_f32_16x16x32_bf16 v[12:15], v[160:163], v[216:219], v[12:15]
	v_mfma_f32_16x16x32_bf16 v[8:11], v[168:171], v[216:219], v[8:11]
	v_mfma_f32_16x16x32_bf16 v[52:55], v[172:175], v[188:191], v[52:55]
	v_mfma_f32_16x16x32_bf16 v[48:51], v[180:183], v[188:191], v[48:51]
	v_mfma_f32_16x16x32_bf16 v[36:39], v[172:175], v[196:199], v[36:39]
	v_mfma_f32_16x16x32_bf16 v[32:35], v[180:183], v[196:199], v[32:35]
	v_mfma_f32_16x16x32_bf16 v[20:23], v[172:175], v[204:207], v[20:23]
	v_mfma_f32_16x16x32_bf16 v[16:19], v[180:183], v[204:207], v[16:19]
	v_mfma_f32_16x16x32_bf16 v[4:7], v[172:175], v[212:215], v[4:7]
	v_mfma_f32_16x16x32_bf16 v[0:3], v[180:183], v[212:215], v[0:3]
	v_mfma_f32_16x16x32_bf16 v[52:55], v[176:179], v[192:195], v[52:55]
	v_mfma_f32_16x16x32_bf16 v[48:51], v[184:187], v[192:195], v[48:51]
	v_mfma_f32_16x16x32_bf16 v[36:39], v[176:179], v[200:203], v[36:39]
	v_mfma_f32_16x16x32_bf16 v[32:35], v[184:187], v[200:203], v[32:35]
	v_mfma_f32_16x16x32_bf16 v[20:23], v[176:179], v[208:211], v[20:23]
	v_mfma_f32_16x16x32_bf16 v[16:19], v[184:187], v[208:211], v[16:19]
	v_mfma_f32_16x16x32_bf16 v[4:7], v[176:179], v[216:219], v[4:7]
	v_mfma_f32_16x16x32_bf16 v[0:3], v[184:187], v[216:219], v[0:3]
	s_setprio 0
	s_barrier
	s_add_i32 s78, s78, 2
	s_add_u32 s72, s72, 0x100
	s_addc_u32 s73, s73, 0
	s_add_u32 s69, s69, 0x100
	s_addc_u32 s71, s71, 0
	s_cmp_gt_u32 s78, 29
	s_cbranch_scc0 .LBB0_1785
	s_and_b64 vcc, exec, s[58:59]
	s_cbranch_vccz .LBB0_1788
	s_barrier

.LBB0_1897:
	ds_read_b128 v[140:143], v149
	ds_read_b128 v[152:155], v149 offset:1024
	ds_read_b128 v[156:159], v149 offset:2048
	ds_read_b128 v[160:163], v149 offset:3072
	ds_read_b128 v[164:167], v150
	ds_read_b128 v[168:171], v150 offset:1024
	ds_read_b128 v[172:175], v150 offset:2048
	ds_read_b128 v[176:179], v150 offset:3072
	s_add_u32 s60, s72, 0xffe00080
	s_addc_u32 s61, s73, -1
	s_cmpk_eq_i32 s79, 0x7c
	s_cselect_b32 s77, s56, s61
	s_cselect_b32 s76, s57, s60
	s_cselect_b32 s75, s63, s78
	s_cselect_b32 s74, s65, s71
	v_lshl_add_u64 v[212:213], s[72:73], 0, v[132:133]
	s_add_i32 m0, s6, 0xc000
	ds_read_b128 v[180:183], v151
	ds_read_b128 v[184:187], v151 offset:1024
	ds_read_b128 v[188:191], v151 offset:2048
	ds_read_b128 v[192:195], v151 offset:3072
	ds_read_b128 v[196:199], v151 offset:4096
	ds_read_b128 v[200:203], v151 offset:5120
	ds_read_b128 v[204:207], v151 offset:6144
	ds_read_b128 v[208:211], v151 offset:7168
	global_load_lds_dwordx4 v[212:213], off
	v_lshl_add_u64 v[212:213], s[72:73], 0, v[134:135]
	s_add_i32 m0, s6, 0xe000
	s_nop 0
	global_load_lds_dwordx4 v[212:213], off
	s_waitcnt vmcnt(8)
	s_waitcnt lgkmcnt(0)
	s_barrier
	s_setprio 1
	v_mfma_f32_16x16x32_bf16 v[124:127], v[140:143], v[180:183], v[124:127]
	v_mfma_f32_16x16x32_bf16 v[120:123], v[156:159], v[180:183], v[120:123]
	v_mfma_f32_16x16x32_bf16 v[108:111], v[140:143], v[188:191], v[108:111]
	v_mfma_f32_16x16x32_bf16 v[104:107], v[156:159], v[188:191], v[104:107]
	v_mfma_f32_16x16x32_bf16 v[92:95], v[140:143], v[196:199], v[92:95]
	v_mfma_f32_16x16x32_bf16 v[88:91], v[156:159], v[196:199], v[88:91]
	v_mfma_f32_16x16x32_bf16 v[76:79], v[140:143], v[204:207], v[76:79]
	v_mfma_f32_16x16x32_bf16 v[72:75], v[156:159], v[204:207], v[72:75]
	v_mfma_f32_16x16x32_bf16 v[124:127], v[152:155], v[184:187], v[124:127]
	v_mfma_f32_16x16x32_bf16 v[120:123], v[160:163], v[184:187], v[120:123]
	v_mfma_f32_16x16x32_bf16 v[108:111], v[152:155], v[192:195], v[108:111]
	v_mfma_f32_16x16x32_bf16 v[104:107], v[160:163], v[192:195], v[104:107]
	v_mfma_f32_16x16x32_bf16 v[92:95], v[152:155], v[200:203], v[92:95]
	v_mfma_f32_16x16x32_bf16 v[88:91], v[160:163], v[200:203], v[88:91]
	v_mfma_f32_16x16x32_bf16 v[76:79], v[152:155], v[208:211], v[76:79]
	v_mfma_f32_16x16x32_bf16 v[72:75], v[160:163], v[208:211], v[72:75]
	v_mfma_f32_16x16x32_bf16 v[116:119], v[164:167], v[180:183], v[116:119]
	v_mfma_f32_16x16x32_bf16 v[112:115], v[172:175], v[180:183], v[112:115]
	v_mfma_f32_16x16x32_bf16 v[100:103], v[164:167], v[188:191], v[100:103]
	v_mfma_f32_16x16x32_bf16 v[96:99], v[172:175], v[188:191], v[96:99]
	v_mfma_f32_16x16x32_bf16 v[84:87], v[164:167], v[196:199], v[84:87]
	v_mfma_f32_16x16x32_bf16 v[80:83], v[172:175], v[196:199], v[80:83]
	v_mfma_f32_16x16x32_bf16 v[68:71], v[164:167], v[204:207], v[68:71]
	v_mfma_f32_16x16x32_bf16 v[64:67], v[172:175], v[204:207], v[64:67]
	v_mfma_f32_16x16x32_bf16 v[116:119], v[168:171], v[184:187], v[116:119]
	v_mfma_f32_16x16x32_bf16 v[112:115], v[176:179], v[184:187], v[112:115]
	v_mfma_f32_16x16x32_bf16 v[100:103], v[168:171], v[192:195], v[100:103]
	v_mfma_f32_16x16x32_bf16 v[96:99], v[176:179], v[192:195], v[96:99]
	v_mfma_f32_16x16x32_bf16 v[84:87], v[168:171], v[200:203], v[84:87]
	v_mfma_f32_16x16x32_bf16 v[80:83], v[176:179], v[200:203], v[80:83]
	v_mfma_f32_16x16x32_bf16 v[68:71], v[168:171], v[208:211], v[68:71]
	v_mfma_f32_16x16x32_bf16 v[64:67], v[176:179], v[208:211], v[64:67]
	s_setprio 0
	s_barrier
	s_add_i32 s60, s34, s94
	v_lshl_add_u64 v[212:213], s[74:75], 0, v[128:129]
	s_mov_b32 m0, s60
	ds_read_b128 v[180:183], v151 offset:16384
	ds_read_b128 v[184:187], v151 offset:17408
	ds_read_b128 v[188:191], v151 offset:18432
	ds_read_b128 v[192:195], v151 offset:19456
	ds_read_b128 v[196:199], v151 offset:20480
	ds_read_b128 v[200:203], v151 offset:21504
	ds_read_b128 v[204:207], v151 offset:22528
	ds_read_b128 v[208:211], v151 offset:23552
	global_load_lds_dwordx4 v[212:213], off
	s_add_i32 m0, s60, 0x2000
	s_add_u32 s80, s74, 0x200000
	v_lshl_add_u64 v[214:215], s[74:75], 0, v[130:131]
	s_addc_u32 s81, s75, 0
	s_add_i32 s60, s35, s94
	global_load_lds_dwordx4 v[214:215], off
	v_lshl_add_u64 v[216:217], s[80:81], 0, v[128:129]
	s_mov_b32 m0, s60
	v_lshl_add_u64 v[218:219], s[76:77], 0, v[130:131]
	global_load_lds_dwordx4 v[216:217], off
	v_lshl_add_u64 v[216:217], s[80:81], 0, v[130:131]
	s_add_i32 m0, s60, 0x2000
	s_nop 0
	global_load_lds_dwordx4 v[216:217], off
	v_lshl_add_u64 v[216:217], s[76:77], 0, v[128:129]
	s_mov_b32 m0, s6
	s_nop 0
	global_load_lds_dwordx4 v[216:217], off
	s_mov_b32 m0, s7
	s_nop 0
	global_load_lds_dwordx4 v[218:219], off
	s_waitcnt vmcnt(8)
	s_waitcnt lgkmcnt(0)
	s_barrier
	s_setprio 1
	v_mfma_f32_16x16x32_bf16 v[60:63], v[140:143], v[180:183], v[60:63]
	v_mfma_f32_16x16x32_bf16 v[56:59], v[156:159], v[180:183], v[56:59]
	v_mfma_f32_16x16x32_bf16 v[44:47], v[140:143], v[188:191], v[44:47]
	v_mfma_f32_16x16x32_bf16 v[40:43], v[156:159], v[188:191], v[40:43]
	v_mfma_f32_16x16x32_bf16 v[28:31], v[140:143], v[196:199], v[28:31]
	v_mfma_f32_16x16x32_bf16 v[24:27], v[156:159], v[196:199], v[24:27]
	v_mfma_f32_16x16x32_bf16 v[12:15], v[140:143], v[204:207], v[12:15]
	v_mfma_f32_16x16x32_bf16 v[8:11], v[156:159], v[204:207], v[8:11]
	v_mfma_f32_16x16x32_bf16 v[60:63], v[152:155], v[184:187], v[60:63]
	v_mfma_f32_16x16x32_bf16 v[56:59], v[160:163], v[184:187], v[56:59]
	v_mfma_f32_16x16x32_bf16 v[44:47], v[152:155], v[192:195], v[44:47]
	v_mfma_f32_16x16x32_bf16 v[40:43], v[160:163], v[192:195], v[40:43]
	v_mfma_f32_16x16x32_bf16 v[28:31], v[152:155], v[200:203], v[28:31]
	v_mfma_f32_16x16x32_bf16 v[24:27], v[160:163], v[200:203], v[24:27]
	v_mfma_f32_16x16x32_bf16 v[12:15], v[152:155], v[208:211], v[12:15]
	v_mfma_f32_16x16x32_bf16 v[8:11], v[160:163], v[208:211], v[8:11]
	v_mfma_f32_16x16x32_bf16 v[52:55], v[164:167], v[180:183], v[52:55]
	v_mfma_f32_16x16x32_bf16 v[48:51], v[172:175], v[180:183], v[48:51]
	v_mfma_f32_16x16x32_bf16 v[36:39], v[164:167], v[188:191], v[36:39]
	v_mfma_f32_16x16x32_bf16 v[32:35], v[172:175], v[188:191], v[32:35]
	v_mfma_f32_16x16x32_bf16 v[20:23], v[164:167], v[196:199], v[20:23]
	v_mfma_f32_16x16x32_bf16 v[16:19], v[172:175], v[196:199], v[16:19]
	v_mfma_f32_16x16x32_bf16 v[4:7], v[164:167], v[204:207], v[4:7]
	v_mfma_f32_16x16x32_bf16 v[0:3], v[172:175], v[204:207], v[0:3]
	v_mfma_f32_16x16x32_bf16 v[52:55], v[168:171], v[184:187], v[52:55]
	v_mfma_f32_16x16x32_bf16 v[48:51], v[176:179], v[184:187], v[48:51]
	v_mfma_f32_16x16x32_bf16 v[36:39], v[168:171], v[192:195], v[36:39]
	v_mfma_f32_16x16x32_bf16 v[32:35], v[176:179], v[192:195], v[32:35]
	v_mfma_f32_16x16x32_bf16 v[20:23], v[168:171], v[200:203], v[20:23]
	v_mfma_f32_16x16x32_bf16 v[16:19], v[176:179], v[200:203], v[16:19]
	v_mfma_f32_16x16x32_bf16 v[4:7], v[168:171], v[208:211], v[4:7]
	v_mfma_f32_16x16x32_bf16 v[0:3], v[176:179], v[208:211], v[0:3]
	s_setprio 0
	s_barrier
	s_add_i32 s60, 0, 0x18000
	s_add_i32 s61, 0, 0x1c000
	v_add_u32_e32 v160, s60, v145
	v_add_u32_e32 v176, s61, v145
	ds_read_b128 v[140:143], v160
	ds_read_b128 v[152:155], v160 offset:1024
	ds_read_b128 v[156:159], v160 offset:2048
	ds_read_b128 v[160:163], v160 offset:3072
	ds_read_b128 v[164:167], v176
	ds_read_b128 v[168:171], v176 offset:1024
	ds_read_b128 v[172:175], v176 offset:2048
	ds_read_b128 v[176:179], v176 offset:3072
	s_add_u32 s76, s76, 0x200000
	s_addc_u32 s77, s77, 0
	s_mov_b32 m0, s12
	v_lshl_add_u64 v[220:221], s[76:77], 0, v[128:129]
	ds_read_b128 v[180:183], v151 offset:32768
	ds_read_b128 v[184:187], v151 offset:33792
	ds_read_b128 v[188:191], v151 offset:34816
	ds_read_b128 v[192:195], v151 offset:35840
	ds_read_b128 v[196:199], v151 offset:36864
	ds_read_b128 v[200:203], v151 offset:37888
	ds_read_b128 v[204:207], v151 offset:38912
	ds_read_b128 v[208:211], v151 offset:39936
	global_load_lds_dwordx4 v[220:221], off
	v_lshl_add_u64 v[220:221], s[76:77], 0, v[130:131]
	s_mov_b32 m0, s13
	s_nop 0
	global_load_lds_dwordx4 v[220:221], off
	s_waitcnt vmcnt(8)
	s_waitcnt lgkmcnt(0)
	s_barrier
	s_setprio 1
	v_mfma_f32_16x16x32_bf16 v[124:127], v[140:143], v[180:183], v[124:127]
	v_mfma_f32_16x16x32_bf16 v[120:123], v[156:159], v[180:183], v[120:123]
	v_mfma_f32_16x16x32_bf16 v[108:111], v[140:143], v[188:191], v[108:111]
	v_mfma_f32_16x16x32_bf16 v[104:107], v[156:159], v[188:191], v[104:107]
	v_mfma_f32_16x16x32_bf16 v[92:95], v[140:143], v[196:199], v[92:95]
	v_mfma_f32_16x16x32_bf16 v[88:91], v[156:159], v[196:199], v[88:91]
	v_mfma_f32_16x16x32_bf16 v[76:79], v[140:143], v[204:207], v[76:79]
	v_mfma_f32_16x16x32_bf16 v[72:75], v[156:159], v[204:207], v[72:75]
	v_mfma_f32_16x16x32_bf16 v[124:127], v[152:155], v[184:187], v[124:127]
	v_mfma_f32_16x16x32_bf16 v[120:123], v[160:163], v[184:187], v[120:123]
	v_mfma_f32_16x16x32_bf16 v[108:111], v[152:155], v[192:195], v[108:111]
	v_mfma_f32_16x16x32_bf16 v[104:107], v[160:163], v[192:195], v[104:107]
	v_mfma_f32_16x16x32_bf16 v[92:95], v[152:155], v[200:203], v[92:95]
	v_mfma_f32_16x16x32_bf16 v[88:91], v[160:163], v[200:203], v[88:91]
	v_mfma_f32_16x16x32_bf16 v[76:79], v[152:155], v[208:211], v[76:79]
	v_mfma_f32_16x16x32_bf16 v[72:75], v[160:163], v[208:211], v[72:75]
	v_mfma_f32_16x16x32_bf16 v[116:119], v[164:167], v[180:183], v[116:119]
	v_mfma_f32_16x16x32_bf16 v[112:115], v[172:175], v[180:183], v[112:115]
	v_mfma_f32_16x16x32_bf16 v[100:103], v[164:167], v[188:191], v[100:103]
	v_mfma_f32_16x16x32_bf16 v[96:99], v[172:175], v[188:191], v[96:99]
	v_mfma_f32_16x16x32_bf16 v[84:87], v[164:167], v[196:199], v[84:87]
	v_mfma_f32_16x16x32_bf16 v[80:83], v[172:175], v[196:199], v[80:83]
	v_mfma_f32_16x16x32_bf16 v[68:71], v[164:167], v[204:207], v[68:71]
	v_mfma_f32_16x16x32_bf16 v[64:67], v[172:175], v[204:207], v[64:67]
	v_mfma_f32_16x16x32_bf16 v[116:119], v[168:171], v[184:187], v[116:119]
	v_mfma_f32_16x16x32_bf16 v[112:115], v[176:179], v[184:187], v[112:115]
	v_mfma_f32_16x16x32_bf16 v[100:103], v[168:171], v[192:195], v[100:103]
	v_mfma_f32_16x16x32_bf16 v[96:99], v[176:179], v[192:195], v[96:99]
	v_mfma_f32_16x16x32_bf16 v[84:87], v[168:171], v[200:203], v[84:87]
	v_mfma_f32_16x16x32_bf16 v[80:83], v[176:179], v[200:203], v[80:83]
	v_mfma_f32_16x16x32_bf16 v[68:71], v[168:171], v[208:211], v[68:71]
	v_mfma_f32_16x16x32_bf16 v[64:67], v[176:179], v[208:211], v[64:67]
	s_setprio 0
	s_barrier
	s_add_i32 s60, s60, s94
	v_lshl_add_u64 v[212:213], v[212:213], 0, s[22:23]
	s_mov_b32 m0, s60
	ds_read_b128 v[180:183], v151 offset:49152
	ds_read_b128 v[184:187], v151 offset:50176
	ds_read_b128 v[188:191], v151 offset:51200
	ds_read_b128 v[192:195], v151 offset:52224
	ds_read_b128 v[196:199], v151 offset:53248
	ds_read_b128 v[200:203], v151 offset:54272
	ds_read_b128 v[204:207], v151 offset:55296
	ds_read_b128 v[208:211], v151 offset:56320
	global_load_lds_dwordx4 v[212:213], off
	s_add_i32 m0, s60, 0x2000
	s_add_u32 s74, s74, 0x200080
	v_lshl_add_u64 v[212:213], v[214:215], 0, s[22:23]
	s_addc_u32 s75, s75, 0
	s_add_i32 s60, s61, s94
	global_load_lds_dwordx4 v[212:213], off
	v_lshl_add_u64 v[212:213], s[74:75], 0, v[128:129]
	s_mov_b32 m0, s60
	s_nop 0
	global_load_lds_dwordx4 v[212:213], off
	v_lshl_add_u64 v[212:213], s[74:75], 0, v[130:131]
	s_add_i32 m0, s60, 0x2000
	s_nop 0
	global_load_lds_dwordx4 v[212:213], off
	v_lshl_add_u64 v[212:213], v[216:217], 0, s[22:23]
	s_mov_b32 m0, s29
	s_nop 0
	global_load_lds_dwordx4 v[212:213], off
	v_lshl_add_u64 v[212:213], v[218:219], 0, s[22:23]
	s_mov_b32 m0, s30
	s_nop 0
	global_load_lds_dwordx4 v[212:213], off
	s_waitcnt vmcnt(8)
	s_waitcnt lgkmcnt(0)
	s_barrier
	s_setprio 1
	v_mfma_f32_16x16x32_bf16 v[60:63], v[140:143], v[180:183], v[60:63]
	v_mfma_f32_16x16x32_bf16 v[56:59], v[156:159], v[180:183], v[56:59]
	v_mfma_f32_16x16x32_bf16 v[44:47], v[140:143], v[188:191], v[44:47]
	v_mfma_f32_16x16x32_bf16 v[40:43], v[156:159], v[188:191], v[40:43]
	v_mfma_f32_16x16x32_bf16 v[28:31], v[140:143], v[196:199], v[28:31]
	v_mfma_f32_16x16x32_bf16 v[24:27], v[156:159], v[196:199], v[24:27]
	v_mfma_f32_16x16x32_bf16 v[12:15], v[140:143], v[204:207], v[12:15]
	v_mfma_f32_16x16x32_bf16 v[8:11], v[156:159], v[204:207], v[8:11]
	v_mfma_f32_16x16x32_bf16 v[60:63], v[152:155], v[184:187], v[60:63]
	v_mfma_f32_16x16x32_bf16 v[56:59], v[160:163], v[184:187], v[56:59]
	v_mfma_f32_16x16x32_bf16 v[44:47], v[152:155], v[192:195], v[44:47]
	v_mfma_f32_16x16x32_bf16 v[40:43], v[160:163], v[192:195], v[40:43]
	v_mfma_f32_16x16x32_bf16 v[28:31], v[152:155], v[200:203], v[28:31]
	v_mfma_f32_16x16x32_bf16 v[24:27], v[160:163], v[200:203], v[24:27]
	v_mfma_f32_16x16x32_bf16 v[12:15], v[152:155], v[208:211], v[12:15]
	v_mfma_f32_16x16x32_bf16 v[8:11], v[160:163], v[208:211], v[8:11]
	v_mfma_f32_16x16x32_bf16 v[52:55], v[164:167], v[180:183], v[52:55]
	v_mfma_f32_16x16x32_bf16 v[48:51], v[172:175], v[180:183], v[48:51]
	v_mfma_f32_16x16x32_bf16 v[36:39], v[164:167], v[188:191], v[36:39]
	v_mfma_f32_16x16x32_bf16 v[32:35], v[172:175], v[188:191], v[32:35]
	v_mfma_f32_16x16x32_bf16 v[20:23], v[164:167], v[196:199], v[20:23]
	v_mfma_f32_16x16x32_bf16 v[16:19], v[172:175], v[196:199], v[16:19]
	v_mfma_f32_16x16x32_bf16 v[4:7], v[164:167], v[204:207], v[4:7]
	v_mfma_f32_16x16x32_bf16 v[0:3], v[172:175], v[204:207], v[0:3]
	v_mfma_f32_16x16x32_bf16 v[52:55], v[168:171], v[184:187], v[52:55]
	v_mfma_f32_16x16x32_bf16 v[48:51], v[176:179], v[184:187], v[48:51]
	v_mfma_f32_16x16x32_bf16 v[36:39], v[168:171], v[192:195], v[36:39]
	v_mfma_f32_16x16x32_bf16 v[32:35], v[176:179], v[192:195], v[32:35]
	v_mfma_f32_16x16x32_bf16 v[20:23], v[168:171], v[200:203], v[20:23]
	v_mfma_f32_16x16x32_bf16 v[16:19], v[176:179], v[200:203], v[16:19]
	v_mfma_f32_16x16x32_bf16 v[4:7], v[168:171], v[208:211], v[4:7]
	v_mfma_f32_16x16x32_bf16 v[0:3], v[176:179], v[208:211], v[0:3]
	s_setprio 0
	s_barrier
	s_add_i32 s79, s79, 2
	s_add_u32 s72, s72, 0x100
	s_addc_u32 s73, s73, 0
	s_add_u32 s71, s71, 0x100
	s_addc_u32 s78, s78, 0
	s_cmpk_gt_u32 s79, 0x7d
	s_cbranch_scc0 .LBB0_1897
	s_and_b64 vcc, exec, s[58:59]
	s_cbranch_vccz .LBB0_1900
	s_barrier

.LBB0_2128:
	ds_read_b128 v[148:151], v179
	ds_read_b128 v[152:155], v179 offset:1024
	ds_read_b128 v[156:159], v179 offset:2048
	ds_read_b128 v[160:163], v179 offset:3072
	ds_read_b128 v[164:167], v180
	ds_read_b128 v[168:171], v180 offset:1024
	ds_read_b128 v[184:187], v180 offset:2048
	ds_read_b128 v[188:191], v180 offset:3072
	s_add_u32 s60, s84, 0xfff80080
	s_addc_u32 s61, s85, -1
	s_cmp_eq_u32 s95, 28
	s_cselect_b32 s89, s23, s61
	s_cselect_b32 s88, s79, s60
	s_cselect_b32 s87, s77, s97
	s_cselect_b32 s86, vcc_lo, vcc_hi
	v_lshl_add_u64 v[172:173], s[84:85], 0, v[140:141]
	s_add_i32 m0, s6, 0xc000
	ds_read_b128 v[192:195], v181
	ds_read_b128 v[196:199], v181 offset:1024
	ds_read_b128 v[200:203], v181 offset:2048
	ds_read_b128 v[204:207], v181 offset:3072
	ds_read_b128 v[208:211], v181 offset:4096
	ds_read_b128 v[212:215], v181 offset:5120
	ds_read_b128 v[216:219], v181 offset:6144
	ds_read_b128 v[220:223], v181 offset:7168
	global_load_lds_dwordx4 v[172:173], off
	v_lshl_add_u64 v[172:173], s[84:85], 0, v[142:143]
	s_add_i32 m0, s6, 0xe000
	s_nop 0
	global_load_lds_dwordx4 v[172:173], off
	s_waitcnt vmcnt(8)
	s_waitcnt lgkmcnt(0)
	s_barrier
	s_setprio 1
	v_mfma_f32_16x16x32_bf16 v[124:127], v[148:151], v[192:195], v[124:127]
	v_mfma_f32_16x16x32_bf16 v[120:123], v[156:159], v[192:195], v[120:123]
	v_mfma_f32_16x16x32_bf16 v[108:111], v[148:151], v[200:203], v[108:111]
	v_mfma_f32_16x16x32_bf16 v[104:107], v[156:159], v[200:203], v[104:107]
	v_mfma_f32_16x16x32_bf16 v[92:95], v[148:151], v[208:211], v[92:95]
	v_mfma_f32_16x16x32_bf16 v[88:91], v[156:159], v[208:211], v[88:91]
	v_mfma_f32_16x16x32_bf16 v[76:79], v[148:151], v[216:219], v[76:79]
	v_mfma_f32_16x16x32_bf16 v[72:75], v[156:159], v[216:219], v[72:75]
	v_mfma_f32_16x16x32_bf16 v[124:127], v[152:155], v[196:199], v[124:127]
	v_mfma_f32_16x16x32_bf16 v[120:123], v[160:163], v[196:199], v[120:123]
	v_mfma_f32_16x16x32_bf16 v[108:111], v[152:155], v[204:207], v[108:111]
	v_mfma_f32_16x16x32_bf16 v[104:107], v[160:163], v[204:207], v[104:107]
	v_mfma_f32_16x16x32_bf16 v[92:95], v[152:155], v[212:215], v[92:95]
	v_mfma_f32_16x16x32_bf16 v[88:91], v[160:163], v[212:215], v[88:91]
	v_mfma_f32_16x16x32_bf16 v[76:79], v[152:155], v[220:223], v[76:79]
	v_mfma_f32_16x16x32_bf16 v[72:75], v[160:163], v[220:223], v[72:75]
	v_mfma_f32_16x16x32_bf16 v[116:119], v[164:167], v[192:195], v[116:119]
	v_mfma_f32_16x16x32_bf16 v[112:115], v[184:187], v[192:195], v[112:115]
	v_mfma_f32_16x16x32_bf16 v[100:103], v[164:167], v[200:203], v[100:103]
	v_mfma_f32_16x16x32_bf16 v[96:99], v[184:187], v[200:203], v[96:99]
	v_mfma_f32_16x16x32_bf16 v[84:87], v[164:167], v[208:211], v[84:87]
	v_mfma_f32_16x16x32_bf16 v[80:83], v[184:187], v[208:211], v[80:83]
	v_mfma_f32_16x16x32_bf16 v[68:71], v[164:167], v[216:219], v[68:71]
	v_mfma_f32_16x16x32_bf16 v[64:67], v[184:187], v[216:219], v[64:67]
	v_mfma_f32_16x16x32_bf16 v[116:119], v[168:171], v[196:199], v[116:119]
	v_mfma_f32_16x16x32_bf16 v[112:115], v[188:191], v[196:199], v[112:115]
	v_mfma_f32_16x16x32_bf16 v[100:103], v[168:171], v[204:207], v[100:103]
	v_mfma_f32_16x16x32_bf16 v[96:99], v[188:191], v[204:207], v[96:99]
	v_mfma_f32_16x16x32_bf16 v[84:87], v[168:171], v[212:215], v[84:87]
	v_mfma_f32_16x16x32_bf16 v[80:83], v[188:191], v[212:215], v[80:83]
	v_mfma_f32_16x16x32_bf16 v[68:71], v[168:171], v[220:223], v[68:71]
	v_mfma_f32_16x16x32_bf16 v[64:67], v[188:191], v[220:223], v[64:67]
	s_setprio 0
	s_barrier
	s_add_i32 s60, s12, s94
	v_lshl_add_u64 v[172:173], s[86:87], 0, v[130:131]
	s_mov_b32 m0, s60
	ds_read_b128 v[192:195], v181 offset:16384
	ds_read_b128 v[196:199], v181 offset:17408
	ds_read_b128 v[200:203], v181 offset:18432
	ds_read_b128 v[204:207], v181 offset:19456
	ds_read_b128 v[208:211], v181 offset:20480
	ds_read_b128 v[212:215], v181 offset:21504
	ds_read_b128 v[216:219], v181 offset:22528
	ds_read_b128 v[220:223], v181 offset:23552
	global_load_lds_dwordx4 v[172:173], off
	s_add_i32 m0, s60, 0x2000
	s_add_u32 s60, s86, 0x80000
	v_lshl_add_u64 v[224:225], s[86:87], 0, v[134:135]
	s_addc_u32 s61, s87, 0
	s_add_i32 s96, s13, s94
	global_load_lds_dwordx4 v[224:225], off
	v_lshl_add_u64 v[226:227], s[60:61], 0, v[130:131]
	s_mov_b32 m0, s96
	v_lshl_add_u64 v[228:229], s[88:89], 0, v[132:133]
	global_load_lds_dwordx4 v[226:227], off
	v_lshl_add_u64 v[226:227], s[60:61], 0, v[134:135]
	s_add_i32 m0, s96, 0x2000
	s_nop 0
	global_load_lds_dwordx4 v[226:227], off
	v_lshl_add_u64 v[226:227], s[88:89], 0, v[128:129]
	s_mov_b32 m0, s6
	s_nop 0
	global_load_lds_dwordx4 v[226:227], off
	s_mov_b32 m0, s7
	s_nop 0
	global_load_lds_dwordx4 v[228:229], off
	s_waitcnt vmcnt(8)
	s_waitcnt lgkmcnt(0)
	s_barrier
	s_setprio 1
	v_mfma_f32_16x16x32_bf16 v[60:63], v[148:151], v[192:195], v[60:63]
	v_mfma_f32_16x16x32_bf16 v[56:59], v[156:159], v[192:195], v[56:59]
	v_mfma_f32_16x16x32_bf16 v[44:47], v[148:151], v[200:203], v[44:47]
	v_mfma_f32_16x16x32_bf16 v[40:43], v[156:159], v[200:203], v[40:43]
	v_mfma_f32_16x16x32_bf16 v[28:31], v[148:151], v[208:211], v[28:31]
	v_mfma_f32_16x16x32_bf16 v[24:27], v[156:159], v[208:211], v[24:27]
	v_mfma_f32_16x16x32_bf16 v[12:15], v[148:151], v[216:219], v[12:15]
	v_mfma_f32_16x16x32_bf16 v[8:11], v[156:159], v[216:219], v[8:11]
	v_mfma_f32_16x16x32_bf16 v[60:63], v[152:155], v[196:199], v[60:63]
	v_mfma_f32_16x16x32_bf16 v[56:59], v[160:163], v[196:199], v[56:59]
	v_mfma_f32_16x16x32_bf16 v[44:47], v[152:155], v[204:207], v[44:47]
	v_mfma_f32_16x16x32_bf16 v[40:43], v[160:163], v[204:207], v[40:43]
	v_mfma_f32_16x16x32_bf16 v[28:31], v[152:155], v[212:215], v[28:31]
	v_mfma_f32_16x16x32_bf16 v[24:27], v[160:163], v[212:215], v[24:27]
	v_mfma_f32_16x16x32_bf16 v[12:15], v[152:155], v[220:223], v[12:15]
	v_mfma_f32_16x16x32_bf16 v[8:11], v[160:163], v[220:223], v[8:11]
	v_mfma_f32_16x16x32_bf16 v[52:55], v[164:167], v[192:195], v[52:55]
	v_mfma_f32_16x16x32_bf16 v[48:51], v[184:187], v[192:195], v[48:51]
	v_mfma_f32_16x16x32_bf16 v[36:39], v[164:167], v[200:203], v[36:39]
	v_mfma_f32_16x16x32_bf16 v[32:35], v[184:187], v[200:203], v[32:35]
	v_mfma_f32_16x16x32_bf16 v[20:23], v[164:167], v[208:211], v[20:23]
	v_mfma_f32_16x16x32_bf16 v[16:19], v[184:187], v[208:211], v[16:19]
	v_mfma_f32_16x16x32_bf16 v[4:7], v[164:167], v[216:219], v[4:7]
	v_mfma_f32_16x16x32_bf16 v[0:3], v[184:187], v[216:219], v[0:3]
	v_mfma_f32_16x16x32_bf16 v[52:55], v[168:171], v[196:199], v[52:55]
	v_mfma_f32_16x16x32_bf16 v[48:51], v[188:191], v[196:199], v[48:51]
	v_mfma_f32_16x16x32_bf16 v[36:39], v[168:171], v[204:207], v[36:39]
	v_mfma_f32_16x16x32_bf16 v[32:35], v[188:191], v[204:207], v[32:35]
	v_mfma_f32_16x16x32_bf16 v[20:23], v[168:171], v[212:215], v[20:23]
	v_mfma_f32_16x16x32_bf16 v[16:19], v[188:191], v[212:215], v[16:19]
	v_mfma_f32_16x16x32_bf16 v[4:7], v[168:171], v[220:223], v[4:7]
	v_mfma_f32_16x16x32_bf16 v[0:3], v[188:191], v[220:223], v[0:3]
	s_setprio 0
	s_barrier
	s_add_i32 s96, 0, 0x18000
	v_add_u32_e32 v136, s96, v175
	s_add_i32 s8, 0, 0x1c000
	ds_read_b128 v[148:151], v136
	ds_read_b128 v[152:155], v136 offset:1024
	ds_read_b128 v[156:159], v136 offset:2048
	ds_read_b128 v[160:163], v136 offset:3072
	v_add_u32_e32 v136, s8, v175
	ds_read_b128 v[164:167], v136
	ds_read_b128 v[168:171], v136 offset:1024
	ds_read_b128 v[184:187], v136 offset:2048
	ds_read_b128 v[188:191], v136 offset:3072
	s_add_u32 s60, s88, 0x80000
	s_addc_u32 s61, s89, 0
	s_mov_b32 m0, s34
	v_lshl_add_u64 v[230:231], s[60:61], 0, v[128:129]
	ds_read_b128 v[192:195], v181 offset:32768
	ds_read_b128 v[196:199], v181 offset:33792
	ds_read_b128 v[200:203], v181 offset:34816
	ds_read_b128 v[204:207], v181 offset:35840
	ds_read_b128 v[208:211], v181 offset:36864
	ds_read_b128 v[212:215], v181 offset:37888
	ds_read_b128 v[216:219], v181 offset:38912
	ds_read_b128 v[220:223], v181 offset:39936
	global_load_lds_dwordx4 v[230:231], off
	v_lshl_add_u64 v[230:231], s[60:61], 0, v[132:133]
	s_mov_b32 m0, s46
	s_nop 0
	global_load_lds_dwordx4 v[230:231], off
	s_waitcnt vmcnt(8)
	s_waitcnt lgkmcnt(0)
	s_barrier
	s_setprio 1
	v_mfma_f32_16x16x32_bf16 v[124:127], v[148:151], v[192:195], v[124:127]
	v_mfma_f32_16x16x32_bf16 v[120:123], v[156:159], v[192:195], v[120:123]
	v_mfma_f32_16x16x32_bf16 v[108:111], v[148:151], v[200:203], v[108:111]
	v_mfma_f32_16x16x32_bf16 v[104:107], v[156:159], v[200:203], v[104:107]
	v_mfma_f32_16x16x32_bf16 v[92:95], v[148:151], v[208:211], v[92:95]
	v_mfma_f32_16x16x32_bf16 v[88:91], v[156:159], v[208:211], v[88:91]
	v_mfma_f32_16x16x32_bf16 v[76:79], v[148:151], v[216:219], v[76:79]
	v_mfma_f32_16x16x32_bf16 v[72:75], v[156:159], v[216:219], v[72:75]
	v_mfma_f32_16x16x32_bf16 v[124:127], v[152:155], v[196:199], v[124:127]
	v_mfma_f32_16x16x32_bf16 v[120:123], v[160:163], v[196:199], v[120:123]
	v_mfma_f32_16x16x32_bf16 v[108:111], v[152:155], v[204:207], v[108:111]
	v_mfma_f32_16x16x32_bf16 v[104:107], v[160:163], v[204:207], v[104:107]
	v_mfma_f32_16x16x32_bf16 v[92:95], v[152:155], v[212:215], v[92:95]
	v_mfma_f32_16x16x32_bf16 v[88:91], v[160:163], v[212:215], v[88:91]
	v_mfma_f32_16x16x32_bf16 v[76:79], v[152:155], v[220:223], v[76:79]
	v_mfma_f32_16x16x32_bf16 v[72:75], v[160:163], v[220:223], v[72:75]
	v_mfma_f32_16x16x32_bf16 v[116:119], v[164:167], v[192:195], v[116:119]
	v_mfma_f32_16x16x32_bf16 v[112:115], v[184:187], v[192:195], v[112:115]
	v_mfma_f32_16x16x32_bf16 v[100:103], v[164:167], v[200:203], v[100:103]
	v_mfma_f32_16x16x32_bf16 v[96:99], v[184:187], v[200:203], v[96:99]
	v_mfma_f32_16x16x32_bf16 v[84:87], v[164:167], v[208:211], v[84:87]
	v_mfma_f32_16x16x32_bf16 v[80:83], v[184:187], v[208:211], v[80:83]
	v_mfma_f32_16x16x32_bf16 v[68:71], v[164:167], v[216:219], v[68:71]
	v_mfma_f32_16x16x32_bf16 v[64:67], v[184:187], v[216:219], v[64:67]
	v_mfma_f32_16x16x32_bf16 v[116:119], v[168:171], v[196:199], v[116:119]
	v_mfma_f32_16x16x32_bf16 v[112:115], v[188:191], v[196:199], v[112:115]
	v_mfma_f32_16x16x32_bf16 v[100:103], v[168:171], v[204:207], v[100:103]
	v_mfma_f32_16x16x32_bf16 v[96:99], v[188:191], v[204:207], v[96:99]
	v_mfma_f32_16x16x32_bf16 v[84:87], v[168:171], v[212:215], v[84:87]
	v_mfma_f32_16x16x32_bf16 v[80:83], v[188:191], v[212:215], v[80:83]
	v_mfma_f32_16x16x32_bf16 v[68:71], v[168:171], v[220:223], v[68:71]
	v_mfma_f32_16x16x32_bf16 v[64:67], v[188:191], v[220:223], v[64:67]
	s_setprio 0
	s_barrier
	s_add_i32 s9, s96, s94
	v_lshl_add_u64 v[172:173], v[172:173], 0, s[74:75]
	s_mov_b32 m0, s9
	ds_read_b128 v[192:195], v181 offset:49152
	ds_read_b128 v[196:199], v181 offset:50176
	ds_read_b128 v[200:203], v181 offset:51200
	ds_read_b128 v[204:207], v181 offset:52224
	ds_read_b128 v[208:211], v181 offset:53248
	ds_read_b128 v[212:215], v181 offset:54272
	ds_read_b128 v[216:219], v181 offset:55296
	ds_read_b128 v[220:223], v181 offset:56320
	global_load_lds_dwordx4 v[172:173], off
	s_add_i32 m0, s9, 0x2000
	s_add_u32 s60, s86, 0x80080
	v_lshl_add_u64 v[172:173], v[224:225], 0, s[74:75]
	s_addc_u32 s61, s87, 0
	s_add_i32 s8, s8, s94
	global_load_lds_dwordx4 v[172:173], off
	v_lshl_add_u64 v[172:173], s[60:61], 0, v[130:131]
	s_mov_b32 m0, s8
	s_nop 0
	global_load_lds_dwordx4 v[172:173], off
	v_lshl_add_u64 v[172:173], s[60:61], 0, v[134:135]
	s_add_i32 m0, s8, 0x2000
	s_nop 0
	global_load_lds_dwordx4 v[172:173], off
	v_lshl_add_u64 v[172:173], v[226:227], 0, s[74:75]
	s_mov_b32 m0, s56
	s_nop 0
	global_load_lds_dwordx4 v[172:173], off
	v_lshl_add_u64 v[172:173], v[228:229], 0, s[74:75]
	s_mov_b32 m0, s57
	s_nop 0
	global_load_lds_dwordx4 v[172:173], off
	s_waitcnt vmcnt(8)
	s_waitcnt lgkmcnt(0)
	s_barrier
	s_setprio 1
	v_mfma_f32_16x16x32_bf16 v[60:63], v[148:151], v[192:195], v[60:63]
	v_mfma_f32_16x16x32_bf16 v[56:59], v[156:159], v[192:195], v[56:59]
	v_mfma_f32_16x16x32_bf16 v[44:47], v[148:151], v[200:203], v[44:47]
	v_mfma_f32_16x16x32_bf16 v[40:43], v[156:159], v[200:203], v[40:43]
	v_mfma_f32_16x16x32_bf16 v[28:31], v[148:151], v[208:211], v[28:31]
	v_mfma_f32_16x16x32_bf16 v[24:27], v[156:159], v[208:211], v[24:27]
	v_mfma_f32_16x16x32_bf16 v[12:15], v[148:151], v[216:219], v[12:15]
	v_mfma_f32_16x16x32_bf16 v[8:11], v[156:159], v[216:219], v[8:11]
	v_mfma_f32_16x16x32_bf16 v[60:63], v[152:155], v[196:199], v[60:63]
	v_mfma_f32_16x16x32_bf16 v[56:59], v[160:163], v[196:199], v[56:59]
	v_mfma_f32_16x16x32_bf16 v[44:47], v[152:155], v[204:207], v[44:47]
	v_mfma_f32_16x16x32_bf16 v[40:43], v[160:163], v[204:207], v[40:43]
	v_mfma_f32_16x16x32_bf16 v[28:31], v[152:155], v[212:215], v[28:31]
	v_mfma_f32_16x16x32_bf16 v[24:27], v[160:163], v[212:215], v[24:27]
	v_mfma_f32_16x16x32_bf16 v[12:15], v[152:155], v[220:223], v[12:15]
	v_mfma_f32_16x16x32_bf16 v[8:11], v[160:163], v[220:223], v[8:11]
	v_mfma_f32_16x16x32_bf16 v[52:55], v[164:167], v[192:195], v[52:55]
	v_mfma_f32_16x16x32_bf16 v[48:51], v[184:187], v[192:195], v[48:51]
	v_mfma_f32_16x16x32_bf16 v[36:39], v[164:167], v[200:203], v[36:39]
	v_mfma_f32_16x16x32_bf16 v[32:35], v[184:187], v[200:203], v[32:35]
	v_mfma_f32_16x16x32_bf16 v[20:23], v[164:167], v[208:211], v[20:23]
	v_mfma_f32_16x16x32_bf16 v[16:19], v[184:187], v[208:211], v[16:19]
	v_mfma_f32_16x16x32_bf16 v[4:7], v[164:167], v[216:219], v[4:7]
	v_mfma_f32_16x16x32_bf16 v[0:3], v[184:187], v[216:219], v[0:3]
	v_mfma_f32_16x16x32_bf16 v[52:55], v[168:171], v[196:199], v[52:55]
	v_mfma_f32_16x16x32_bf16 v[48:51], v[188:191], v[196:199], v[48:51]
	v_mfma_f32_16x16x32_bf16 v[36:39], v[168:171], v[204:207], v[36:39]
	v_mfma_f32_16x16x32_bf16 v[32:35], v[188:191], v[204:207], v[32:35]
	v_mfma_f32_16x16x32_bf16 v[20:23], v[168:171], v[212:215], v[20:23]
	v_mfma_f32_16x16x32_bf16 v[16:19], v[188:191], v[212:215], v[16:19]
	v_mfma_f32_16x16x32_bf16 v[4:7], v[168:171], v[220:223], v[4:7]
	v_mfma_f32_16x16x32_bf16 v[0:3], v[188:191], v[220:223], v[0:3]
	s_setprio 0
	s_barrier
	s_add_i32 s95, s95, 2
	s_add_u32 s84, s84, 0x100
	s_addc_u32 s85, s85, 0
	s_add_u32 vcc_hi, vcc_hi, 0x100
	s_addc_u32 s97, s97, 0
	s_cmp_gt_u32 s95, 29
	s_cbranch_scc0 .LBB0_2128
	s_and_b64 vcc, exec, s[58:59]
	s_cbranch_vccz .LBB0_2131
	s_barrier

.LBB0_2459:
	ds_read_b128 v[148:151], v163
	ds_read_b128 v[152:155], v163 offset:1024
	ds_read_b128 v[168:171], v163 offset:2048
	ds_read_b128 v[172:175], v163 offset:3072
	ds_read_b128 v[176:179], v164
	ds_read_b128 v[180:183], v164 offset:1024
	ds_read_b128 v[184:187], v164 offset:2048
	ds_read_b128 v[188:191], v164 offset:3072
	s_add_u32 s16, s70, 0x100
	s_addc_u32 s17, s71, 0
	s_cmp_eq_u32 s86, 8
	s_cselect_b32 s75, s23, s17
	s_cselect_b32 s74, s22, s16
	s_cselect_b32 s73, s49, s85
	s_cselect_b32 s72, s48, s84
	v_lshl_add_u64 v[156:157], s[70:71], 0, v[140:141]
	s_add_i32 m0, s12, 0xc000
	ds_read_b128 v[192:195], v165
	ds_read_b128 v[196:199], v165 offset:1024
	ds_read_b128 v[200:203], v165 offset:2048
	ds_read_b128 v[204:207], v165 offset:3072
	ds_read_b128 v[208:211], v165 offset:4096
	ds_read_b128 v[212:215], v165 offset:5120
	ds_read_b128 v[216:219], v165 offset:6144
	ds_read_b128 v[220:223], v165 offset:7168
	global_load_lds_dwordx4 v[156:157], off
	v_lshl_add_u64 v[156:157], s[70:71], 0, v[142:143]
	s_add_i32 m0, s12, 0xe000
	s_nop 0
	global_load_lds_dwordx4 v[156:157], off
	s_waitcnt vmcnt(8)
	s_waitcnt lgkmcnt(0)
	s_barrier
	s_setprio 1
	v_mfma_f32_16x16x32_bf16 v[124:127], v[148:151], v[192:195], v[124:127]
	v_mfma_f32_16x16x32_bf16 v[120:123], v[168:171], v[192:195], v[120:123]
	v_mfma_f32_16x16x32_bf16 v[108:111], v[148:151], v[200:203], v[108:111]
	v_mfma_f32_16x16x32_bf16 v[104:107], v[168:171], v[200:203], v[104:107]
	v_mfma_f32_16x16x32_bf16 v[92:95], v[148:151], v[208:211], v[92:95]
	v_mfma_f32_16x16x32_bf16 v[88:91], v[168:171], v[208:211], v[88:91]
	v_mfma_f32_16x16x32_bf16 v[76:79], v[148:151], v[216:219], v[76:79]
	v_mfma_f32_16x16x32_bf16 v[72:75], v[168:171], v[216:219], v[72:75]
	v_mfma_f32_16x16x32_bf16 v[124:127], v[152:155], v[196:199], v[124:127]
	v_mfma_f32_16x16x32_bf16 v[120:123], v[172:175], v[196:199], v[120:123]
	v_mfma_f32_16x16x32_bf16 v[108:111], v[152:155], v[204:207], v[108:111]
	v_mfma_f32_16x16x32_bf16 v[104:107], v[172:175], v[204:207], v[104:107]
	v_mfma_f32_16x16x32_bf16 v[92:95], v[152:155], v[212:215], v[92:95]
	v_mfma_f32_16x16x32_bf16 v[88:91], v[172:175], v[212:215], v[88:91]
	v_mfma_f32_16x16x32_bf16 v[76:79], v[152:155], v[220:223], v[76:79]
	v_mfma_f32_16x16x32_bf16 v[72:75], v[172:175], v[220:223], v[72:75]
	v_mfma_f32_16x16x32_bf16 v[116:119], v[176:179], v[192:195], v[116:119]
	v_mfma_f32_16x16x32_bf16 v[112:115], v[184:187], v[192:195], v[112:115]
	v_mfma_f32_16x16x32_bf16 v[100:103], v[176:179], v[200:203], v[100:103]
	v_mfma_f32_16x16x32_bf16 v[96:99], v[184:187], v[200:203], v[96:99]
	v_mfma_f32_16x16x32_bf16 v[84:87], v[176:179], v[208:211], v[84:87]
	v_mfma_f32_16x16x32_bf16 v[80:83], v[184:187], v[208:211], v[80:83]
	v_mfma_f32_16x16x32_bf16 v[68:71], v[176:179], v[216:219], v[68:71]
	v_mfma_f32_16x16x32_bf16 v[64:67], v[184:187], v[216:219], v[64:67]
	v_mfma_f32_16x16x32_bf16 v[116:119], v[180:183], v[196:199], v[116:119]
	v_mfma_f32_16x16x32_bf16 v[112:115], v[188:191], v[196:199], v[112:115]
	v_mfma_f32_16x16x32_bf16 v[100:103], v[180:183], v[204:207], v[100:103]
	v_mfma_f32_16x16x32_bf16 v[96:99], v[188:191], v[204:207], v[96:99]
	v_mfma_f32_16x16x32_bf16 v[84:87], v[180:183], v[212:215], v[84:87]
	v_mfma_f32_16x16x32_bf16 v[80:83], v[188:191], v[212:215], v[80:83]
	v_mfma_f32_16x16x32_bf16 v[68:71], v[180:183], v[220:223], v[68:71]
	v_mfma_f32_16x16x32_bf16 v[64:67], v[188:191], v[220:223], v[64:67]
	s_setprio 0
	s_barrier
	s_add_i32 s8, s76, s94
	v_lshl_add_u64 v[156:157], s[72:73], 0, v[130:131]
	s_mov_b32 m0, s8
	ds_read_b128 v[192:195], v165 offset:16384
	ds_read_b128 v[196:199], v165 offset:17408
	ds_read_b128 v[200:203], v165 offset:18432
	ds_read_b128 v[204:207], v165 offset:19456
	ds_read_b128 v[208:211], v165 offset:20480
	ds_read_b128 v[212:215], v165 offset:21504
	ds_read_b128 v[216:219], v165 offset:22528
	ds_read_b128 v[220:223], v165 offset:23552
	global_load_lds_dwordx4 v[156:157], off
	s_add_i32 m0, s8, 0x2000
	s_add_u32 s60, s72, 0x30000
	v_lshl_add_u64 v[224:225], s[72:73], 0, v[134:135]
	s_addc_u32 s61, s73, 0
	s_add_i32 s8, s77, s94
	global_load_lds_dwordx4 v[224:225], off
	v_lshl_add_u64 v[226:227], s[60:61], 0, v[130:131]
	s_mov_b32 m0, s8
	v_lshl_add_u64 v[228:229], s[74:75], 0, v[132:133]
	global_load_lds_dwordx4 v[226:227], off
	v_lshl_add_u64 v[226:227], s[60:61], 0, v[134:135]
	s_add_i32 m0, s8, 0x2000
	s_nop 0
	global_load_lds_dwordx4 v[226:227], off
	v_lshl_add_u64 v[226:227], s[74:75], 0, v[128:129]
	s_mov_b32 m0, s12
	s_nop 0
	global_load_lds_dwordx4 v[226:227], off
	s_mov_b32 m0, s13
	s_nop 0
	global_load_lds_dwordx4 v[228:229], off
	s_waitcnt vmcnt(8)
	s_waitcnt lgkmcnt(0)
	s_barrier
	s_setprio 1
	v_mfma_f32_16x16x32_bf16 v[60:63], v[148:151], v[192:195], v[60:63]
	v_mfma_f32_16x16x32_bf16 v[56:59], v[168:171], v[192:195], v[56:59]
	v_mfma_f32_16x16x32_bf16 v[44:47], v[148:151], v[200:203], v[44:47]
	v_mfma_f32_16x16x32_bf16 v[40:43], v[168:171], v[200:203], v[40:43]
	v_mfma_f32_16x16x32_bf16 v[28:31], v[148:151], v[208:211], v[28:31]
	v_mfma_f32_16x16x32_bf16 v[24:27], v[168:171], v[208:211], v[24:27]
	v_mfma_f32_16x16x32_bf16 v[12:15], v[148:151], v[216:219], v[12:15]
	v_mfma_f32_16x16x32_bf16 v[8:11], v[168:171], v[216:219], v[8:11]
	v_mfma_f32_16x16x32_bf16 v[60:63], v[152:155], v[196:199], v[60:63]
	v_mfma_f32_16x16x32_bf16 v[56:59], v[172:175], v[196:199], v[56:59]
	v_mfma_f32_16x16x32_bf16 v[44:47], v[152:155], v[204:207], v[44:47]
	v_mfma_f32_16x16x32_bf16 v[40:43], v[172:175], v[204:207], v[40:43]
	v_mfma_f32_16x16x32_bf16 v[28:31], v[152:155], v[212:215], v[28:31]
	v_mfma_f32_16x16x32_bf16 v[24:27], v[172:175], v[212:215], v[24:27]
	v_mfma_f32_16x16x32_bf16 v[12:15], v[152:155], v[220:223], v[12:15]
	v_mfma_f32_16x16x32_bf16 v[8:11], v[172:175], v[220:223], v[8:11]
	v_mfma_f32_16x16x32_bf16 v[52:55], v[176:179], v[192:195], v[52:55]
	v_mfma_f32_16x16x32_bf16 v[48:51], v[184:187], v[192:195], v[48:51]
	v_mfma_f32_16x16x32_bf16 v[36:39], v[176:179], v[200:203], v[36:39]
	v_mfma_f32_16x16x32_bf16 v[32:35], v[184:187], v[200:203], v[32:35]
	v_mfma_f32_16x16x32_bf16 v[20:23], v[176:179], v[208:211], v[20:23]
	v_mfma_f32_16x16x32_bf16 v[16:19], v[184:187], v[208:211], v[16:19]
	v_mfma_f32_16x16x32_bf16 v[4:7], v[176:179], v[216:219], v[4:7]
	v_mfma_f32_16x16x32_bf16 v[0:3], v[184:187], v[216:219], v[0:3]
	v_mfma_f32_16x16x32_bf16 v[52:55], v[180:183], v[196:199], v[52:55]
	v_mfma_f32_16x16x32_bf16 v[48:51], v[188:191], v[196:199], v[48:51]
	v_mfma_f32_16x16x32_bf16 v[36:39], v[180:183], v[204:207], v[36:39]
	v_mfma_f32_16x16x32_bf16 v[32:35], v[188:191], v[204:207], v[32:35]
	v_mfma_f32_16x16x32_bf16 v[20:23], v[180:183], v[212:215], v[20:23]
	v_mfma_f32_16x16x32_bf16 v[16:19], v[188:191], v[212:215], v[16:19]
	v_mfma_f32_16x16x32_bf16 v[4:7], v[180:183], v[220:223], v[4:7]
	v_mfma_f32_16x16x32_bf16 v[0:3], v[188:191], v[220:223], v[0:3]
	s_setprio 0
	s_barrier
	s_add_i32 s8, 0, 0x18000
	v_add_u32_e32 v136, s8, v159
	s_add_i32 s9, 0, 0x1c000
	ds_read_b128 v[148:151], v136
	ds_read_b128 v[152:155], v136 offset:1024
	ds_read_b128 v[168:171], v136 offset:2048
	ds_read_b128 v[172:175], v136 offset:3072
	v_add_u32_e32 v136, s9, v159
	ds_read_b128 v[176:179], v136
	ds_read_b128 v[180:183], v136 offset:1024
	ds_read_b128 v[184:187], v136 offset:2048
	ds_read_b128 v[188:191], v136 offset:3072
	s_add_u32 s60, s74, 0x60000
	s_addc_u32 s61, s75, 0
	s_mov_b32 m0, s29
	v_lshl_add_u64 v[230:231], s[60:61], 0, v[128:129]
	ds_read_b128 v[192:195], v165 offset:32768
	ds_read_b128 v[196:199], v165 offset:33792
	ds_read_b128 v[200:203], v165 offset:34816
	ds_read_b128 v[204:207], v165 offset:35840
	ds_read_b128 v[208:211], v165 offset:36864
	ds_read_b128 v[212:215], v165 offset:37888
	ds_read_b128 v[216:219], v165 offset:38912
	ds_read_b128 v[220:223], v165 offset:39936
	global_load_lds_dwordx4 v[230:231], off
	v_lshl_add_u64 v[230:231], s[60:61], 0, v[132:133]
	s_mov_b32 m0, s30
	s_nop 0
	global_load_lds_dwordx4 v[230:231], off
	s_waitcnt vmcnt(8)
	s_waitcnt lgkmcnt(0)
	s_barrier
	s_setprio 1
	v_mfma_f32_16x16x32_bf16 v[124:127], v[148:151], v[192:195], v[124:127]
	v_mfma_f32_16x16x32_bf16 v[120:123], v[168:171], v[192:195], v[120:123]
	v_mfma_f32_16x16x32_bf16 v[108:111], v[148:151], v[200:203], v[108:111]
	v_mfma_f32_16x16x32_bf16 v[104:107], v[168:171], v[200:203], v[104:107]
	v_mfma_f32_16x16x32_bf16 v[92:95], v[148:151], v[208:211], v[92:95]
	v_mfma_f32_16x16x32_bf16 v[88:91], v[168:171], v[208:211], v[88:91]
	v_mfma_f32_16x16x32_bf16 v[76:79], v[148:151], v[216:219], v[76:79]
	v_mfma_f32_16x16x32_bf16 v[72:75], v[168:171], v[216:219], v[72:75]
	v_mfma_f32_16x16x32_bf16 v[124:127], v[152:155], v[196:199], v[124:127]
	v_mfma_f32_16x16x32_bf16 v[120:123], v[172:175], v[196:199], v[120:123]
	v_mfma_f32_16x16x32_bf16 v[108:111], v[152:155], v[204:207], v[108:111]
	v_mfma_f32_16x16x32_bf16 v[104:107], v[172:175], v[204:207], v[104:107]
	v_mfma_f32_16x16x32_bf16 v[92:95], v[152:155], v[212:215], v[92:95]
	v_mfma_f32_16x16x32_bf16 v[88:91], v[172:175], v[212:215], v[88:91]
	v_mfma_f32_16x16x32_bf16 v[76:79], v[152:155], v[220:223], v[76:79]
	v_mfma_f32_16x16x32_bf16 v[72:75], v[172:175], v[220:223], v[72:75]
	v_mfma_f32_16x16x32_bf16 v[116:119], v[176:179], v[192:195], v[116:119]
	v_mfma_f32_16x16x32_bf16 v[112:115], v[184:187], v[192:195], v[112:115]
	v_mfma_f32_16x16x32_bf16 v[100:103], v[176:179], v[200:203], v[100:103]
	v_mfma_f32_16x16x32_bf16 v[96:99], v[184:187], v[200:203], v[96:99]
	v_mfma_f32_16x16x32_bf16 v[84:87], v[176:179], v[208:211], v[84:87]
	v_mfma_f32_16x16x32_bf16 v[80:83], v[184:187], v[208:211], v[80:83]
	v_mfma_f32_16x16x32_bf16 v[68:71], v[176:179], v[216:219], v[68:71]
	v_mfma_f32_16x16x32_bf16 v[64:67], v[184:187], v[216:219], v[64:67]
	v_mfma_f32_16x16x32_bf16 v[116:119], v[180:183], v[196:199], v[116:119]
	v_mfma_f32_16x16x32_bf16 v[112:115], v[188:191], v[196:199], v[112:115]
	v_mfma_f32_16x16x32_bf16 v[100:103], v[180:183], v[204:207], v[100:103]
	v_mfma_f32_16x16x32_bf16 v[96:99], v[188:191], v[204:207], v[96:99]
	v_mfma_f32_16x16x32_bf16 v[84:87], v[180:183], v[212:215], v[84:87]
	v_mfma_f32_16x16x32_bf16 v[80:83], v[188:191], v[212:215], v[80:83]
	v_mfma_f32_16x16x32_bf16 v[68:71], v[180:183], v[220:223], v[68:71]
	v_mfma_f32_16x16x32_bf16 v[64:67], v[188:191], v[220:223], v[64:67]
	s_setprio 0
	s_barrier
	s_add_i32 s8, s8, s94
	v_lshl_add_u64 v[156:157], v[156:157], 0, s[20:21]
	s_mov_b32 m0, s8
	ds_read_b128 v[192:195], v165 offset:49152
	ds_read_b128 v[196:199], v165 offset:50176
	ds_read_b128 v[200:203], v165 offset:51200
	ds_read_b128 v[204:207], v165 offset:52224
	ds_read_b128 v[208:211], v165 offset:53248
	ds_read_b128 v[212:215], v165 offset:54272
	ds_read_b128 v[216:219], v165 offset:55296
	ds_read_b128 v[220:223], v165 offset:56320
	global_load_lds_dwordx4 v[156:157], off
	s_add_i32 m0, s8, 0x2000
	s_add_u32 s60, s72, 0x30080
	v_lshl_add_u64 v[156:157], v[224:225], 0, s[20:21]
	s_addc_u32 s61, s73, 0
	s_add_i32 s8, s9, s94
	global_load_lds_dwordx4 v[156:157], off
	v_lshl_add_u64 v[156:157], s[60:61], 0, v[130:131]
	s_mov_b32 m0, s8
	s_nop 0
	global_load_lds_dwordx4 v[156:157], off
	v_lshl_add_u64 v[156:157], s[60:61], 0, v[134:135]
	s_add_i32 m0, s8, 0x2000
	s_nop 0
	global_load_lds_dwordx4 v[156:157], off
	v_lshl_add_u64 v[156:157], v[226:227], 0, s[20:21]
	s_mov_b32 m0, s46
	s_nop 0
	global_load_lds_dwordx4 v[156:157], off
	v_lshl_add_u64 v[156:157], v[228:229], 0, s[20:21]
	s_mov_b32 m0, s56
	s_nop 0
	global_load_lds_dwordx4 v[156:157], off
	s_waitcnt vmcnt(8)
	s_waitcnt lgkmcnt(0)
	s_barrier
	s_setprio 1
	v_mfma_f32_16x16x32_bf16 v[60:63], v[148:151], v[192:195], v[60:63]
	v_mfma_f32_16x16x32_bf16 v[56:59], v[168:171], v[192:195], v[56:59]
	v_mfma_f32_16x16x32_bf16 v[44:47], v[148:151], v[200:203], v[44:47]
	v_mfma_f32_16x16x32_bf16 v[40:43], v[168:171], v[200:203], v[40:43]
	v_mfma_f32_16x16x32_bf16 v[28:31], v[148:151], v[208:211], v[28:31]
	v_mfma_f32_16x16x32_bf16 v[24:27], v[168:171], v[208:211], v[24:27]
	v_mfma_f32_16x16x32_bf16 v[12:15], v[148:151], v[216:219], v[12:15]
	v_mfma_f32_16x16x32_bf16 v[8:11], v[168:171], v[216:219], v[8:11]
	v_mfma_f32_16x16x32_bf16 v[60:63], v[152:155], v[196:199], v[60:63]
	v_mfma_f32_16x16x32_bf16 v[56:59], v[172:175], v[196:199], v[56:59]
	v_mfma_f32_16x16x32_bf16 v[44:47], v[152:155], v[204:207], v[44:47]
	v_mfma_f32_16x16x32_bf16 v[40:43], v[172:175], v[204:207], v[40:43]
	v_mfma_f32_16x16x32_bf16 v[28:31], v[152:155], v[212:215], v[28:31]
	v_mfma_f32_16x16x32_bf16 v[24:27], v[172:175], v[212:215], v[24:27]
	v_mfma_f32_16x16x32_bf16 v[12:15], v[152:155], v[220:223], v[12:15]
	v_mfma_f32_16x16x32_bf16 v[8:11], v[172:175], v[220:223], v[8:11]
	v_mfma_f32_16x16x32_bf16 v[52:55], v[176:179], v[192:195], v[52:55]
	v_mfma_f32_16x16x32_bf16 v[48:51], v[184:187], v[192:195], v[48:51]
	v_mfma_f32_16x16x32_bf16 v[36:39], v[176:179], v[200:203], v[36:39]
	v_mfma_f32_16x16x32_bf16 v[32:35], v[184:187], v[200:203], v[32:35]
	v_mfma_f32_16x16x32_bf16 v[20:23], v[176:179], v[208:211], v[20:23]
	v_mfma_f32_16x16x32_bf16 v[16:19], v[184:187], v[208:211], v[16:19]
	v_mfma_f32_16x16x32_bf16 v[4:7], v[176:179], v[216:219], v[4:7]
	v_mfma_f32_16x16x32_bf16 v[0:3], v[184:187], v[216:219], v[0:3]
	v_mfma_f32_16x16x32_bf16 v[52:55], v[180:183], v[196:199], v[52:55]
	v_mfma_f32_16x16x32_bf16 v[48:51], v[188:191], v[196:199], v[48:51]
	v_mfma_f32_16x16x32_bf16 v[36:39], v[180:183], v[204:207], v[36:39]
	v_mfma_f32_16x16x32_bf16 v[32:35], v[188:191], v[204:207], v[32:35]
	v_mfma_f32_16x16x32_bf16 v[20:23], v[180:183], v[212:215], v[20:23]
	v_mfma_f32_16x16x32_bf16 v[16:19], v[188:191], v[212:215], v[16:19]
	v_mfma_f32_16x16x32_bf16 v[4:7], v[180:183], v[220:223], v[4:7]
	v_mfma_f32_16x16x32_bf16 v[0:3], v[188:191], v[220:223], v[0:3]
	s_setprio 0
	s_barrier
	s_add_i32 s86, s86, 2
	s_add_u32 s84, s84, 0x100
	s_addc_u32 s85, s85, 0
	s_cmp_gt_u32 s86, 9
	s_mov_b64 s[70:71], s[16:17]
	s_cbranch_scc0 .LBB0_2459
	s_and_b64 vcc, exec, s[58:59]
	s_cbranch_vccz .LBB0_2462
	s_barrier

.LBB0_2535:
	ds_read_b128 v[146:149], v155
	ds_read_b128 v[160:163], v155 offset:1024
	ds_read_b128 v[164:167], v155 offset:2048
	ds_read_b128 v[168:171], v155 offset:3072
	ds_read_b128 v[172:175], v156
	ds_read_b128 v[176:179], v156 offset:1024
	ds_read_b128 v[180:183], v156 offset:2048
	ds_read_b128 v[184:187], v156 offset:3072
	s_add_u32 s16, s68, 0x100
	s_addc_u32 s17, s69, 0
	s_cmp_eq_u32 s80, 4
	s_cselect_b32 s73, s49, s17
	s_cselect_b32 s72, s48, s16
	s_cselect_b32 s71, s43, s79
	s_cselect_b32 s70, s77, s78
	v_lshl_add_u64 v[220:221], s[68:69], 0, v[138:139]
	s_add_i32 m0, s29, 0xc000
	ds_read_b128 v[188:191], v157
	ds_read_b128 v[192:195], v157 offset:1024
	ds_read_b128 v[196:199], v157 offset:2048
	ds_read_b128 v[200:203], v157 offset:3072
	ds_read_b128 v[204:207], v157 offset:4096
	ds_read_b128 v[208:211], v157 offset:5120
	ds_read_b128 v[212:215], v157 offset:6144
	ds_read_b128 v[216:219], v157 offset:7168
	global_load_lds_dwordx4 v[220:221], off
	v_lshl_add_u64 v[220:221], s[68:69], 0, v[140:141]
	s_add_i32 m0, s29, 0xe000
	s_nop 0
	global_load_lds_dwordx4 v[220:221], off
	s_waitcnt vmcnt(8)
	s_waitcnt lgkmcnt(0)
	s_barrier
	s_setprio 1
	v_mfma_f32_16x16x32_bf16 v[124:127], v[146:149], v[188:191], v[124:127]
	v_mfma_f32_16x16x32_bf16 v[120:123], v[164:167], v[188:191], v[120:123]
	v_mfma_f32_16x16x32_bf16 v[108:111], v[146:149], v[196:199], v[108:111]
	v_mfma_f32_16x16x32_bf16 v[104:107], v[164:167], v[196:199], v[104:107]
	v_mfma_f32_16x16x32_bf16 v[92:95], v[146:149], v[204:207], v[92:95]
	v_mfma_f32_16x16x32_bf16 v[88:91], v[164:167], v[204:207], v[88:91]
	v_mfma_f32_16x16x32_bf16 v[76:79], v[146:149], v[212:215], v[76:79]
	v_mfma_f32_16x16x32_bf16 v[72:75], v[164:167], v[212:215], v[72:75]
	v_mfma_f32_16x16x32_bf16 v[124:127], v[160:163], v[192:195], v[124:127]
	v_mfma_f32_16x16x32_bf16 v[120:123], v[168:171], v[192:195], v[120:123]
	v_mfma_f32_16x16x32_bf16 v[108:111], v[160:163], v[200:203], v[108:111]
	v_mfma_f32_16x16x32_bf16 v[104:107], v[168:171], v[200:203], v[104:107]
	v_mfma_f32_16x16x32_bf16 v[92:95], v[160:163], v[208:211], v[92:95]
	v_mfma_f32_16x16x32_bf16 v[88:91], v[168:171], v[208:211], v[88:91]
	v_mfma_f32_16x16x32_bf16 v[76:79], v[160:163], v[216:219], v[76:79]
	v_mfma_f32_16x16x32_bf16 v[72:75], v[168:171], v[216:219], v[72:75]
	v_mfma_f32_16x16x32_bf16 v[116:119], v[172:175], v[188:191], v[116:119]
	v_mfma_f32_16x16x32_bf16 v[112:115], v[180:183], v[188:191], v[112:115]
	v_mfma_f32_16x16x32_bf16 v[100:103], v[172:175], v[196:199], v[100:103]
	v_mfma_f32_16x16x32_bf16 v[96:99], v[180:183], v[196:199], v[96:99]
	v_mfma_f32_16x16x32_bf16 v[84:87], v[172:175], v[204:207], v[84:87]
	v_mfma_f32_16x16x32_bf16 v[80:83], v[180:183], v[204:207], v[80:83]
	v_mfma_f32_16x16x32_bf16 v[68:71], v[172:175], v[212:215], v[68:71]
	v_mfma_f32_16x16x32_bf16 v[64:67], v[180:183], v[212:215], v[64:67]
	v_mfma_f32_16x16x32_bf16 v[116:119], v[176:179], v[192:195], v[116:119]
	v_mfma_f32_16x16x32_bf16 v[112:115], v[184:187], v[192:195], v[112:115]
	v_mfma_f32_16x16x32_bf16 v[100:103], v[176:179], v[200:203], v[100:103]
	v_mfma_f32_16x16x32_bf16 v[96:99], v[184:187], v[200:203], v[96:99]
	v_mfma_f32_16x16x32_bf16 v[84:87], v[176:179], v[208:211], v[84:87]
	v_mfma_f32_16x16x32_bf16 v[80:83], v[184:187], v[208:211], v[80:83]
	v_mfma_f32_16x16x32_bf16 v[68:71], v[176:179], v[216:219], v[68:71]
	v_mfma_f32_16x16x32_bf16 v[64:67], v[184:187], v[216:219], v[64:67]
	s_setprio 0
	s_barrier
	s_add_i32 s8, s67, s94
	v_lshl_add_u64 v[220:221], s[70:71], 0, v[130:131]
	s_mov_b32 m0, s8
	ds_read_b128 v[188:191], v157 offset:16384
	ds_read_b128 v[192:195], v157 offset:17408
	ds_read_b128 v[196:199], v157 offset:18432
	ds_read_b128 v[200:203], v157 offset:19456
	ds_read_b128 v[204:207], v157 offset:20480
	ds_read_b128 v[208:211], v157 offset:21504
	ds_read_b128 v[212:215], v157 offset:22528
	ds_read_b128 v[216:219], v157 offset:23552
	global_load_lds_dwordx4 v[220:221], off
	s_add_i32 m0, s8, 0x2000
	s_add_u32 s60, s70, 0x20000
	v_lshl_add_u64 v[222:223], s[70:71], 0, v[134:135]
	s_addc_u32 s61, s71, 0
	s_add_i32 s8, s74, s94
	global_load_lds_dwordx4 v[222:223], off
	v_lshl_add_u64 v[224:225], s[60:61], 0, v[130:131]
	s_mov_b32 m0, s8
	v_lshl_add_u64 v[226:227], s[72:73], 0, v[132:133]
	global_load_lds_dwordx4 v[224:225], off
	v_lshl_add_u64 v[224:225], s[60:61], 0, v[134:135]
	s_add_i32 m0, s8, 0x2000
	s_nop 0
	global_load_lds_dwordx4 v[224:225], off
	v_lshl_add_u64 v[224:225], s[72:73], 0, v[128:129]
	s_mov_b32 m0, s29
	s_nop 0
	global_load_lds_dwordx4 v[224:225], off
	s_mov_b32 m0, s30
	s_nop 0
	global_load_lds_dwordx4 v[226:227], off
	s_waitcnt vmcnt(8)
	s_waitcnt lgkmcnt(0)
	s_barrier
	s_setprio 1
	v_mfma_f32_16x16x32_bf16 v[60:63], v[146:149], v[188:191], v[60:63]
	v_mfma_f32_16x16x32_bf16 v[56:59], v[164:167], v[188:191], v[56:59]
	v_mfma_f32_16x16x32_bf16 v[44:47], v[146:149], v[196:199], v[44:47]
	v_mfma_f32_16x16x32_bf16 v[40:43], v[164:167], v[196:199], v[40:43]
	v_mfma_f32_16x16x32_bf16 v[28:31], v[146:149], v[204:207], v[28:31]
	v_mfma_f32_16x16x32_bf16 v[24:27], v[164:167], v[204:207], v[24:27]
	v_mfma_f32_16x16x32_bf16 v[12:15], v[146:149], v[212:215], v[12:15]
	v_mfma_f32_16x16x32_bf16 v[8:11], v[164:167], v[212:215], v[8:11]
	v_mfma_f32_16x16x32_bf16 v[60:63], v[160:163], v[192:195], v[60:63]
	v_mfma_f32_16x16x32_bf16 v[56:59], v[168:171], v[192:195], v[56:59]
	v_mfma_f32_16x16x32_bf16 v[44:47], v[160:163], v[200:203], v[44:47]
	v_mfma_f32_16x16x32_bf16 v[40:43], v[168:171], v[200:203], v[40:43]
	v_mfma_f32_16x16x32_bf16 v[28:31], v[160:163], v[208:211], v[28:31]
	v_mfma_f32_16x16x32_bf16 v[24:27], v[168:171], v[208:211], v[24:27]
	v_mfma_f32_16x16x32_bf16 v[12:15], v[160:163], v[216:219], v[12:15]
	v_mfma_f32_16x16x32_bf16 v[8:11], v[168:171], v[216:219], v[8:11]
	v_mfma_f32_16x16x32_bf16 v[52:55], v[172:175], v[188:191], v[52:55]
	v_mfma_f32_16x16x32_bf16 v[48:51], v[180:183], v[188:191], v[48:51]
	v_mfma_f32_16x16x32_bf16 v[36:39], v[172:175], v[196:199], v[36:39]
	v_mfma_f32_16x16x32_bf16 v[32:35], v[180:183], v[196:199], v[32:35]
	v_mfma_f32_16x16x32_bf16 v[20:23], v[172:175], v[204:207], v[20:23]
	v_mfma_f32_16x16x32_bf16 v[16:19], v[180:183], v[204:207], v[16:19]
	v_mfma_f32_16x16x32_bf16 v[4:7], v[172:175], v[212:215], v[4:7]
	v_mfma_f32_16x16x32_bf16 v[0:3], v[180:183], v[212:215], v[0:3]
	v_mfma_f32_16x16x32_bf16 v[52:55], v[176:179], v[192:195], v[52:55]
	v_mfma_f32_16x16x32_bf16 v[48:51], v[184:187], v[192:195], v[48:51]
	v_mfma_f32_16x16x32_bf16 v[36:39], v[176:179], v[200:203], v[36:39]
	v_mfma_f32_16x16x32_bf16 v[32:35], v[184:187], v[200:203], v[32:35]
	v_mfma_f32_16x16x32_bf16 v[20:23], v[176:179], v[208:211], v[20:23]
	v_mfma_f32_16x16x32_bf16 v[16:19], v[184:187], v[208:211], v[16:19]
	v_mfma_f32_16x16x32_bf16 v[4:7], v[176:179], v[216:219], v[4:7]
	v_mfma_f32_16x16x32_bf16 v[0:3], v[184:187], v[216:219], v[0:3]
	s_setprio 0
	s_barrier
	s_add_i32 s8, 0, 0x18000
	v_add_u32_e32 v159, s8, v151
	s_add_i32 s9, 0, 0x1c000
	ds_read_b128 v[146:149], v159
	ds_read_b128 v[160:163], v159 offset:1024
	ds_read_b128 v[164:167], v159 offset:2048
	ds_read_b128 v[168:171], v159 offset:3072
	v_add_u32_e32 v159, s9, v151
	ds_read_b128 v[172:175], v159
	ds_read_b128 v[176:179], v159 offset:1024
	ds_read_b128 v[180:183], v159 offset:2048
	ds_read_b128 v[184:187], v159 offset:3072
	s_add_u32 s60, s72, 0x60000
	s_addc_u32 s61, s73, 0
	s_mov_b32 m0, s34
	v_lshl_add_u64 v[228:229], s[60:61], 0, v[128:129]
	ds_read_b128 v[188:191], v157 offset:32768
	ds_read_b128 v[192:195], v157 offset:33792
	ds_read_b128 v[196:199], v157 offset:34816
	ds_read_b128 v[200:203], v157 offset:35840
	ds_read_b128 v[204:207], v157 offset:36864
	ds_read_b128 v[208:211], v157 offset:37888
	ds_read_b128 v[212:215], v157 offset:38912
	ds_read_b128 v[216:219], v157 offset:39936
	global_load_lds_dwordx4 v[228:229], off
	v_lshl_add_u64 v[228:229], s[60:61], 0, v[132:133]
	s_mov_b32 m0, s35
	s_nop 0
	global_load_lds_dwordx4 v[228:229], off
	s_waitcnt vmcnt(8)
	s_waitcnt lgkmcnt(0)
	s_barrier
	s_setprio 1
	v_mfma_f32_16x16x32_bf16 v[124:127], v[146:149], v[188:191], v[124:127]
	v_mfma_f32_16x16x32_bf16 v[120:123], v[164:167], v[188:191], v[120:123]
	v_mfma_f32_16x16x32_bf16 v[108:111], v[146:149], v[196:199], v[108:111]
	v_mfma_f32_16x16x32_bf16 v[104:107], v[164:167], v[196:199], v[104:107]
	v_mfma_f32_16x16x32_bf16 v[92:95], v[146:149], v[204:207], v[92:95]
	v_mfma_f32_16x16x32_bf16 v[88:91], v[164:167], v[204:207], v[88:91]
	v_mfma_f32_16x16x32_bf16 v[76:79], v[146:149], v[212:215], v[76:79]
	v_mfma_f32_16x16x32_bf16 v[72:75], v[164:167], v[212:215], v[72:75]
	v_mfma_f32_16x16x32_bf16 v[124:127], v[160:163], v[192:195], v[124:127]
	v_mfma_f32_16x16x32_bf16 v[120:123], v[168:171], v[192:195], v[120:123]
	v_mfma_f32_16x16x32_bf16 v[108:111], v[160:163], v[200:203], v[108:111]
	v_mfma_f32_16x16x32_bf16 v[104:107], v[168:171], v[200:203], v[104:107]
	v_mfma_f32_16x16x32_bf16 v[92:95], v[160:163], v[208:211], v[92:95]
	v_mfma_f32_16x16x32_bf16 v[88:91], v[168:171], v[208:211], v[88:91]
	v_mfma_f32_16x16x32_bf16 v[76:79], v[160:163], v[216:219], v[76:79]
	v_mfma_f32_16x16x32_bf16 v[72:75], v[168:171], v[216:219], v[72:75]
	v_mfma_f32_16x16x32_bf16 v[116:119], v[172:175], v[188:191], v[116:119]
	v_mfma_f32_16x16x32_bf16 v[112:115], v[180:183], v[188:191], v[112:115]
	v_mfma_f32_16x16x32_bf16 v[100:103], v[172:175], v[196:199], v[100:103]
	v_mfma_f32_16x16x32_bf16 v[96:99], v[180:183], v[196:199], v[96:99]
	v_mfma_f32_16x16x32_bf16 v[84:87], v[172:175], v[204:207], v[84:87]
	v_mfma_f32_16x16x32_bf16 v[80:83], v[180:183], v[204:207], v[80:83]
	v_mfma_f32_16x16x32_bf16 v[68:71], v[172:175], v[212:215], v[68:71]
	v_mfma_f32_16x16x32_bf16 v[64:67], v[180:183], v[212:215], v[64:67]
	v_mfma_f32_16x16x32_bf16 v[116:119], v[176:179], v[192:195], v[116:119]
	v_mfma_f32_16x16x32_bf16 v[112:115], v[184:187], v[192:195], v[112:115]
	v_mfma_f32_16x16x32_bf16 v[100:103], v[176:179], v[200:203], v[100:103]
	v_mfma_f32_16x16x32_bf16 v[96:99], v[184:187], v[200:203], v[96:99]
	v_mfma_f32_16x16x32_bf16 v[84:87], v[176:179], v[208:211], v[84:87]
	v_mfma_f32_16x16x32_bf16 v[80:83], v[184:187], v[208:211], v[80:83]
	v_mfma_f32_16x16x32_bf16 v[68:71], v[176:179], v[216:219], v[68:71]
	v_mfma_f32_16x16x32_bf16 v[64:67], v[184:187], v[216:219], v[64:67]
	s_setprio 0
	s_barrier
	s_add_i32 s8, s8, s94
	v_lshl_add_u64 v[220:221], v[220:221], 0, s[22:23]
	s_mov_b32 m0, s8
	ds_read_b128 v[188:191], v157 offset:49152
	ds_read_b128 v[192:195], v157 offset:50176
	ds_read_b128 v[196:199], v157 offset:51200
	ds_read_b128 v[200:203], v157 offset:52224
	ds_read_b128 v[204:207], v157 offset:53248
	ds_read_b128 v[208:211], v157 offset:54272
	ds_read_b128 v[212:215], v157 offset:55296
	ds_read_b128 v[216:219], v157 offset:56320
	global_load_lds_dwordx4 v[220:221], off
	s_add_i32 m0, s8, 0x2000
	s_add_u32 s60, s70, 0x20080
	v_lshl_add_u64 v[220:221], v[222:223], 0, s[22:23]
	s_addc_u32 s61, s71, 0
	s_add_i32 s8, s9, s94
	global_load_lds_dwordx4 v[220:221], off
	v_lshl_add_u64 v[220:221], s[60:61], 0, v[130:131]
	s_mov_b32 m0, s8
	s_nop 0
	global_load_lds_dwordx4 v[220:221], off
	v_lshl_add_u64 v[220:221], s[60:61], 0, v[134:135]
	s_add_i32 m0, s8, 0x2000
	s_nop 0
	global_load_lds_dwordx4 v[220:221], off
	v_lshl_add_u64 v[220:221], v[224:225], 0, s[22:23]
	s_mov_b32 m0, s56
	s_nop 0
	global_load_lds_dwordx4 v[220:221], off
	v_lshl_add_u64 v[220:221], v[226:227], 0, s[22:23]
	s_mov_b32 m0, s57
	s_nop 0
	global_load_lds_dwordx4 v[220:221], off
	s_waitcnt vmcnt(8)
	s_waitcnt lgkmcnt(0)
	s_barrier
	s_setprio 1
	v_mfma_f32_16x16x32_bf16 v[60:63], v[146:149], v[188:191], v[60:63]
	v_mfma_f32_16x16x32_bf16 v[56:59], v[164:167], v[188:191], v[56:59]
	v_mfma_f32_16x16x32_bf16 v[44:47], v[146:149], v[196:199], v[44:47]
	v_mfma_f32_16x16x32_bf16 v[40:43], v[164:167], v[196:199], v[40:43]
	v_mfma_f32_16x16x32_bf16 v[28:31], v[146:149], v[204:207], v[28:31]
	v_mfma_f32_16x16x32_bf16 v[24:27], v[164:167], v[204:207], v[24:27]
	v_mfma_f32_16x16x32_bf16 v[12:15], v[146:149], v[212:215], v[12:15]
	v_mfma_f32_16x16x32_bf16 v[8:11], v[164:167], v[212:215], v[8:11]
	v_mfma_f32_16x16x32_bf16 v[60:63], v[160:163], v[192:195], v[60:63]
	v_mfma_f32_16x16x32_bf16 v[56:59], v[168:171], v[192:195], v[56:59]
	v_mfma_f32_16x16x32_bf16 v[44:47], v[160:163], v[200:203], v[44:47]
	v_mfma_f32_16x16x32_bf16 v[40:43], v[168:171], v[200:203], v[40:43]
	v_mfma_f32_16x16x32_bf16 v[28:31], v[160:163], v[208:211], v[28:31]
	v_mfma_f32_16x16x32_bf16 v[24:27], v[168:171], v[208:211], v[24:27]
	v_mfma_f32_16x16x32_bf16 v[12:15], v[160:163], v[216:219], v[12:15]
	v_mfma_f32_16x16x32_bf16 v[8:11], v[168:171], v[216:219], v[8:11]
	v_mfma_f32_16x16x32_bf16 v[52:55], v[172:175], v[188:191], v[52:55]
	v_mfma_f32_16x16x32_bf16 v[48:51], v[180:183], v[188:191], v[48:51]
	v_mfma_f32_16x16x32_bf16 v[36:39], v[172:175], v[196:199], v[36:39]
	v_mfma_f32_16x16x32_bf16 v[32:35], v[180:183], v[196:199], v[32:35]
	v_mfma_f32_16x16x32_bf16 v[20:23], v[172:175], v[204:207], v[20:23]
	v_mfma_f32_16x16x32_bf16 v[16:19], v[180:183], v[204:207], v[16:19]
	v_mfma_f32_16x16x32_bf16 v[4:7], v[172:175], v[212:215], v[4:7]
	v_mfma_f32_16x16x32_bf16 v[0:3], v[180:183], v[212:215], v[0:3]
	v_mfma_f32_16x16x32_bf16 v[52:55], v[176:179], v[192:195], v[52:55]
	v_mfma_f32_16x16x32_bf16 v[48:51], v[184:187], v[192:195], v[48:51]
	v_mfma_f32_16x16x32_bf16 v[36:39], v[176:179], v[200:203], v[36:39]
	v_mfma_f32_16x16x32_bf16 v[32:35], v[184:187], v[200:203], v[32:35]
	v_mfma_f32_16x16x32_bf16 v[20:23], v[176:179], v[208:211], v[20:23]
	v_mfma_f32_16x16x32_bf16 v[16:19], v[184:187], v[208:211], v[16:19]
	v_mfma_f32_16x16x32_bf16 v[4:7], v[176:179], v[216:219], v[4:7]
	v_mfma_f32_16x16x32_bf16 v[0:3], v[184:187], v[216:219], v[0:3]
	s_setprio 0
	s_barrier
	s_add_i32 s80, s80, 2
	s_add_u32 s78, s78, 0x100
	s_addc_u32 s79, s79, 0
	s_cmp_gt_u32 s80, 5
	s_mov_b64 s[68:69], s[16:17]
	s_cbranch_scc0 .LBB0_2535
	s_and_b64 vcc, exec, s[58:59]
	s_cbranch_vccz .LBB0_2538
	s_barrier

.LBB0_2713:
	ds_read_b128 v[140:143], v149
	ds_read_b128 v[152:155], v149 offset:1024
	ds_read_b128 v[156:159], v149 offset:2048
	ds_read_b128 v[160:163], v149 offset:3072
	ds_read_b128 v[164:167], v150
	ds_read_b128 v[168:171], v150 offset:1024
	ds_read_b128 v[172:175], v150 offset:2048
	ds_read_b128 v[176:179], v150 offset:3072
	s_add_u32 s8, s62, 0xfff80080
	s_addc_u32 s9, s63, -1
	s_cmp_eq_u32 s72, 28
	s_cselect_b32 s67, s43, s9
	s_cselect_b32 s66, s57, s8
	s_cselect_b32 s65, s23, s71
	s_cselect_b32 s64, s69, s70
	v_lshl_add_u64 v[212:213], s[62:63], 0, v[132:133]
	s_add_i32 m0, s12, 0xc000
	ds_read_b128 v[180:183], v151
	ds_read_b128 v[184:187], v151 offset:1024
	ds_read_b128 v[188:191], v151 offset:2048
	ds_read_b128 v[192:195], v151 offset:3072
	ds_read_b128 v[196:199], v151 offset:4096
	ds_read_b128 v[200:203], v151 offset:5120
	ds_read_b128 v[204:207], v151 offset:6144
	ds_read_b128 v[208:211], v151 offset:7168
	global_load_lds_dwordx4 v[212:213], off
	v_lshl_add_u64 v[212:213], s[62:63], 0, v[134:135]
	s_add_i32 m0, s12, 0xe000
	s_nop 0
	global_load_lds_dwordx4 v[212:213], off
	s_waitcnt vmcnt(8)
	s_waitcnt lgkmcnt(0)
	s_barrier
	s_setprio 1
	v_mfma_f32_16x16x32_bf16 v[124:127], v[140:143], v[180:183], v[124:127]
	v_mfma_f32_16x16x32_bf16 v[120:123], v[156:159], v[180:183], v[120:123]
	v_mfma_f32_16x16x32_bf16 v[108:111], v[140:143], v[188:191], v[108:111]
	v_mfma_f32_16x16x32_bf16 v[104:107], v[156:159], v[188:191], v[104:107]
	v_mfma_f32_16x16x32_bf16 v[92:95], v[140:143], v[196:199], v[92:95]
	v_mfma_f32_16x16x32_bf16 v[88:91], v[156:159], v[196:199], v[88:91]
	v_mfma_f32_16x16x32_bf16 v[76:79], v[140:143], v[204:207], v[76:79]
	v_mfma_f32_16x16x32_bf16 v[72:75], v[156:159], v[204:207], v[72:75]
	v_mfma_f32_16x16x32_bf16 v[124:127], v[152:155], v[184:187], v[124:127]
	v_mfma_f32_16x16x32_bf16 v[120:123], v[160:163], v[184:187], v[120:123]
	v_mfma_f32_16x16x32_bf16 v[108:111], v[152:155], v[192:195], v[108:111]
	v_mfma_f32_16x16x32_bf16 v[104:107], v[160:163], v[192:195], v[104:107]
	v_mfma_f32_16x16x32_bf16 v[92:95], v[152:155], v[200:203], v[92:95]
	v_mfma_f32_16x16x32_bf16 v[88:91], v[160:163], v[200:203], v[88:91]
	v_mfma_f32_16x16x32_bf16 v[76:79], v[152:155], v[208:211], v[76:79]
	v_mfma_f32_16x16x32_bf16 v[72:75], v[160:163], v[208:211], v[72:75]
	v_mfma_f32_16x16x32_bf16 v[116:119], v[164:167], v[180:183], v[116:119]
	v_mfma_f32_16x16x32_bf16 v[112:115], v[172:175], v[180:183], v[112:115]
	v_mfma_f32_16x16x32_bf16 v[100:103], v[164:167], v[188:191], v[100:103]
	v_mfma_f32_16x16x32_bf16 v[96:99], v[172:175], v[188:191], v[96:99]
	v_mfma_f32_16x16x32_bf16 v[84:87], v[164:167], v[196:199], v[84:87]
	v_mfma_f32_16x16x32_bf16 v[80:83], v[172:175], v[196:199], v[80:83]
	v_mfma_f32_16x16x32_bf16 v[68:71], v[164:167], v[204:207], v[68:71]
	v_mfma_f32_16x16x32_bf16 v[64:67], v[172:175], v[204:207], v[64:67]
	v_mfma_f32_16x16x32_bf16 v[116:119], v[168:171], v[184:187], v[116:119]
	v_mfma_f32_16x16x32_bf16 v[112:115], v[176:179], v[184:187], v[112:115]
	v_mfma_f32_16x16x32_bf16 v[100:103], v[168:171], v[192:195], v[100:103]
	v_mfma_f32_16x16x32_bf16 v[96:99], v[176:179], v[192:195], v[96:99]
	v_mfma_f32_16x16x32_bf16 v[84:87], v[168:171], v[200:203], v[84:87]
	v_mfma_f32_16x16x32_bf16 v[80:83], v[176:179], v[200:203], v[80:83]
	v_mfma_f32_16x16x32_bf16 v[68:71], v[168:171], v[208:211], v[68:71]
	v_mfma_f32_16x16x32_bf16 v[64:67], v[176:179], v[208:211], v[64:67]
	s_setprio 0
	s_barrier
	s_add_i32 s8, s46, s94
	v_lshl_add_u64 v[212:213], s[64:65], 0, v[128:129]
	s_mov_b32 m0, s8
	ds_read_b128 v[180:183], v151 offset:16384
	ds_read_b128 v[184:187], v151 offset:17408
	ds_read_b128 v[188:191], v151 offset:18432
	ds_read_b128 v[192:195], v151 offset:19456
	ds_read_b128 v[196:199], v151 offset:20480
	ds_read_b128 v[200:203], v151 offset:21504
	ds_read_b128 v[204:207], v151 offset:22528
	ds_read_b128 v[208:211], v151 offset:23552
	global_load_lds_dwordx4 v[212:213], off
	s_add_i32 m0, s8, 0x2000
	s_add_u32 s60, s64, 0x80000
	v_lshl_add_u64 v[214:215], s[64:65], 0, v[130:131]
	s_addc_u32 s61, s65, 0
	s_add_i32 s8, s47, s94
	global_load_lds_dwordx4 v[214:215], off
	v_lshl_add_u64 v[216:217], s[60:61], 0, v[128:129]
	s_mov_b32 m0, s8
	v_lshl_add_u64 v[218:219], s[66:67], 0, v[130:131]
	global_load_lds_dwordx4 v[216:217], off
	v_lshl_add_u64 v[216:217], s[60:61], 0, v[130:131]
	s_add_i32 m0, s8, 0x2000
	s_nop 0
	global_load_lds_dwordx4 v[216:217], off
	v_lshl_add_u64 v[216:217], s[66:67], 0, v[128:129]
	s_mov_b32 m0, s12
	s_nop 0
	global_load_lds_dwordx4 v[216:217], off
	s_mov_b32 m0, s13
	s_nop 0
	global_load_lds_dwordx4 v[218:219], off
	s_waitcnt vmcnt(8)
	s_waitcnt lgkmcnt(0)
	s_barrier
	s_setprio 1
	v_mfma_f32_16x16x32_bf16 v[60:63], v[140:143], v[180:183], v[60:63]
	v_mfma_f32_16x16x32_bf16 v[56:59], v[156:159], v[180:183], v[56:59]
	v_mfma_f32_16x16x32_bf16 v[44:47], v[140:143], v[188:191], v[44:47]
	v_mfma_f32_16x16x32_bf16 v[40:43], v[156:159], v[188:191], v[40:43]
	v_mfma_f32_16x16x32_bf16 v[28:31], v[140:143], v[196:199], v[28:31]
	v_mfma_f32_16x16x32_bf16 v[24:27], v[156:159], v[196:199], v[24:27]
	v_mfma_f32_16x16x32_bf16 v[12:15], v[140:143], v[204:207], v[12:15]
	v_mfma_f32_16x16x32_bf16 v[8:11], v[156:159], v[204:207], v[8:11]
	v_mfma_f32_16x16x32_bf16 v[60:63], v[152:155], v[184:187], v[60:63]
	v_mfma_f32_16x16x32_bf16 v[56:59], v[160:163], v[184:187], v[56:59]
	v_mfma_f32_16x16x32_bf16 v[44:47], v[152:155], v[192:195], v[44:47]
	v_mfma_f32_16x16x32_bf16 v[40:43], v[160:163], v[192:195], v[40:43]
	v_mfma_f32_16x16x32_bf16 v[28:31], v[152:155], v[200:203], v[28:31]
	v_mfma_f32_16x16x32_bf16 v[24:27], v[160:163], v[200:203], v[24:27]
	v_mfma_f32_16x16x32_bf16 v[12:15], v[152:155], v[208:211], v[12:15]
	v_mfma_f32_16x16x32_bf16 v[8:11], v[160:163], v[208:211], v[8:11]
	v_mfma_f32_16x16x32_bf16 v[52:55], v[164:167], v[180:183], v[52:55]
	v_mfma_f32_16x16x32_bf16 v[48:51], v[172:175], v[180:183], v[48:51]
	v_mfma_f32_16x16x32_bf16 v[36:39], v[164:167], v[188:191], v[36:39]
	v_mfma_f32_16x16x32_bf16 v[32:35], v[172:175], v[188:191], v[32:35]
	v_mfma_f32_16x16x32_bf16 v[20:23], v[164:167], v[196:199], v[20:23]
	v_mfma_f32_16x16x32_bf16 v[16:19], v[172:175], v[196:199], v[16:19]
	v_mfma_f32_16x16x32_bf16 v[4:7], v[164:167], v[204:207], v[4:7]
	v_mfma_f32_16x16x32_bf16 v[0:3], v[172:175], v[204:207], v[0:3]
	v_mfma_f32_16x16x32_bf16 v[52:55], v[168:171], v[184:187], v[52:55]
	v_mfma_f32_16x16x32_bf16 v[48:51], v[176:179], v[184:187], v[48:51]
	v_mfma_f32_16x16x32_bf16 v[36:39], v[168:171], v[192:195], v[36:39]
	v_mfma_f32_16x16x32_bf16 v[32:35], v[176:179], v[192:195], v[32:35]
	v_mfma_f32_16x16x32_bf16 v[20:23], v[168:171], v[200:203], v[20:23]
	v_mfma_f32_16x16x32_bf16 v[16:19], v[176:179], v[200:203], v[16:19]
	v_mfma_f32_16x16x32_bf16 v[4:7], v[168:171], v[208:211], v[4:7]
	v_mfma_f32_16x16x32_bf16 v[0:3], v[176:179], v[208:211], v[0:3]
	s_setprio 0
	s_barrier
	s_add_i32 s8, 0, 0x18000
	s_add_i32 s9, 0, 0x1c000
	v_add_u32_e32 v160, s8, v145
	v_add_u32_e32 v176, s9, v145
	ds_read_b128 v[140:143], v160
	ds_read_b128 v[152:155], v160 offset:1024
	ds_read_b128 v[156:159], v160 offset:2048
	ds_read_b128 v[160:163], v160 offset:3072
	ds_read_b128 v[164:167], v176
	ds_read_b128 v[168:171], v176 offset:1024
	ds_read_b128 v[172:175], v176 offset:2048
	ds_read_b128 v[176:179], v176 offset:3072
	s_add_u32 s60, s66, 0x80000
	s_addc_u32 s61, s67, 0
	s_mov_b32 m0, s29
	v_lshl_add_u64 v[220:221], s[60:61], 0, v[128:129]
	ds_read_b128 v[180:183], v151 offset:32768
	ds_read_b128 v[184:187], v151 offset:33792
	ds_read_b128 v[188:191], v151 offset:34816
	ds_read_b128 v[192:195], v151 offset:35840
	ds_read_b128 v[196:199], v151 offset:36864
	ds_read_b128 v[200:203], v151 offset:37888
	ds_read_b128 v[204:207], v151 offset:38912
	ds_read_b128 v[208:211], v151 offset:39936
	global_load_lds_dwordx4 v[220:221], off
	v_lshl_add_u64 v[220:221], s[60:61], 0, v[130:131]
	s_mov_b32 m0, s30
	s_nop 0
	global_load_lds_dwordx4 v[220:221], off
	s_waitcnt vmcnt(8)
	s_waitcnt lgkmcnt(0)
	s_barrier
	s_setprio 1
	v_mfma_f32_16x16x32_bf16 v[124:127], v[140:143], v[180:183], v[124:127]
	v_mfma_f32_16x16x32_bf16 v[120:123], v[156:159], v[180:183], v[120:123]
	v_mfma_f32_16x16x32_bf16 v[108:111], v[140:143], v[188:191], v[108:111]
	v_mfma_f32_16x16x32_bf16 v[104:107], v[156:159], v[188:191], v[104:107]
	v_mfma_f32_16x16x32_bf16 v[92:95], v[140:143], v[196:199], v[92:95]
	v_mfma_f32_16x16x32_bf16 v[88:91], v[156:159], v[196:199], v[88:91]
	v_mfma_f32_16x16x32_bf16 v[76:79], v[140:143], v[204:207], v[76:79]
	v_mfma_f32_16x16x32_bf16 v[72:75], v[156:159], v[204:207], v[72:75]
	v_mfma_f32_16x16x32_bf16 v[124:127], v[152:155], v[184:187], v[124:127]
	v_mfma_f32_16x16x32_bf16 v[120:123], v[160:163], v[184:187], v[120:123]
	v_mfma_f32_16x16x32_bf16 v[108:111], v[152:155], v[192:195], v[108:111]
	v_mfma_f32_16x16x32_bf16 v[104:107], v[160:163], v[192:195], v[104:107]
	v_mfma_f32_16x16x32_bf16 v[92:95], v[152:155], v[200:203], v[92:95]
	v_mfma_f32_16x16x32_bf16 v[88:91], v[160:163], v[200:203], v[88:91]
	v_mfma_f32_16x16x32_bf16 v[76:79], v[152:155], v[208:211], v[76:79]
	v_mfma_f32_16x16x32_bf16 v[72:75], v[160:163], v[208:211], v[72:75]
	v_mfma_f32_16x16x32_bf16 v[116:119], v[164:167], v[180:183], v[116:119]
	v_mfma_f32_16x16x32_bf16 v[112:115], v[172:175], v[180:183], v[112:115]
	v_mfma_f32_16x16x32_bf16 v[100:103], v[164:167], v[188:191], v[100:103]
	v_mfma_f32_16x16x32_bf16 v[96:99], v[172:175], v[188:191], v[96:99]
	v_mfma_f32_16x16x32_bf16 v[84:87], v[164:167], v[196:199], v[84:87]
	v_mfma_f32_16x16x32_bf16 v[80:83], v[172:175], v[196:199], v[80:83]
	v_mfma_f32_16x16x32_bf16 v[68:71], v[164:167], v[204:207], v[68:71]
	v_mfma_f32_16x16x32_bf16 v[64:67], v[172:175], v[204:207], v[64:67]
	v_mfma_f32_16x16x32_bf16 v[116:119], v[168:171], v[184:187], v[116:119]
	v_mfma_f32_16x16x32_bf16 v[112:115], v[176:179], v[184:187], v[112:115]
	v_mfma_f32_16x16x32_bf16 v[100:103], v[168:171], v[192:195], v[100:103]
	v_mfma_f32_16x16x32_bf16 v[96:99], v[176:179], v[192:195], v[96:99]
	v_mfma_f32_16x16x32_bf16 v[84:87], v[168:171], v[200:203], v[84:87]
	v_mfma_f32_16x16x32_bf16 v[80:83], v[176:179], v[200:203], v[80:83]
	v_mfma_f32_16x16x32_bf16 v[68:71], v[168:171], v[208:211], v[68:71]
	v_mfma_f32_16x16x32_bf16 v[64:67], v[176:179], v[208:211], v[64:67]
	s_setprio 0
	s_barrier
	s_add_i32 s8, s8, s94
	v_lshl_add_u64 v[212:213], v[212:213], 0, s[20:21]
	s_mov_b32 m0, s8
	ds_read_b128 v[180:183], v151 offset:49152
	ds_read_b128 v[184:187], v151 offset:50176
	ds_read_b128 v[188:191], v151 offset:51200
	ds_read_b128 v[192:195], v151 offset:52224
	ds_read_b128 v[196:199], v151 offset:53248
	ds_read_b128 v[200:203], v151 offset:54272
	ds_read_b128 v[204:207], v151 offset:55296
	ds_read_b128 v[208:211], v151 offset:56320
	global_load_lds_dwordx4 v[212:213], off
	s_add_i32 m0, s8, 0x2000
	s_add_u32 s60, s64, 0x80080
	v_lshl_add_u64 v[212:213], v[214:215], 0, s[20:21]
	s_addc_u32 s61, s65, 0
	s_add_i32 s8, s9, s94
	global_load_lds_dwordx4 v[212:213], off
	v_lshl_add_u64 v[212:213], s[60:61], 0, v[128:129]
	s_mov_b32 m0, s8
	s_nop 0
	global_load_lds_dwordx4 v[212:213], off
	v_lshl_add_u64 v[212:213], s[60:61], 0, v[130:131]
	s_add_i32 m0, s8, 0x2000
	s_nop 0
	global_load_lds_dwordx4 v[212:213], off
	v_lshl_add_u64 v[212:213], v[216:217], 0, s[20:21]
	s_mov_b32 m0, s34
	s_nop 0
	global_load_lds_dwordx4 v[212:213], off
	v_lshl_add_u64 v[212:213], v[218:219], 0, s[20:21]
	s_mov_b32 m0, s35
	s_nop 0
	global_load_lds_dwordx4 v[212:213], off
	s_waitcnt vmcnt(8)
	s_waitcnt lgkmcnt(0)
	s_barrier
	s_setprio 1
	v_mfma_f32_16x16x32_bf16 v[60:63], v[140:143], v[180:183], v[60:63]
	v_mfma_f32_16x16x32_bf16 v[56:59], v[156:159], v[180:183], v[56:59]
	v_mfma_f32_16x16x32_bf16 v[44:47], v[140:143], v[188:191], v[44:47]
	v_mfma_f32_16x16x32_bf16 v[40:43], v[156:159], v[188:191], v[40:43]
	v_mfma_f32_16x16x32_bf16 v[28:31], v[140:143], v[196:199], v[28:31]
	v_mfma_f32_16x16x32_bf16 v[24:27], v[156:159], v[196:199], v[24:27]
	v_mfma_f32_16x16x32_bf16 v[12:15], v[140:143], v[204:207], v[12:15]
	v_mfma_f32_16x16x32_bf16 v[8:11], v[156:159], v[204:207], v[8:11]
	v_mfma_f32_16x16x32_bf16 v[60:63], v[152:155], v[184:187], v[60:63]
	v_mfma_f32_16x16x32_bf16 v[56:59], v[160:163], v[184:187], v[56:59]
	v_mfma_f32_16x16x32_bf16 v[44:47], v[152:155], v[192:195], v[44:47]
	v_mfma_f32_16x16x32_bf16 v[40:43], v[160:163], v[192:195], v[40:43]
	v_mfma_f32_16x16x32_bf16 v[28:31], v[152:155], v[200:203], v[28:31]
	v_mfma_f32_16x16x32_bf16 v[24:27], v[160:163], v[200:203], v[24:27]
	v_mfma_f32_16x16x32_bf16 v[12:15], v[152:155], v[208:211], v[12:15]
	v_mfma_f32_16x16x32_bf16 v[8:11], v[160:163], v[208:211], v[8:11]
	v_mfma_f32_16x16x32_bf16 v[52:55], v[164:167], v[180:183], v[52:55]
	v_mfma_f32_16x16x32_bf16 v[48:51], v[172:175], v[180:183], v[48:51]
	v_mfma_f32_16x16x32_bf16 v[36:39], v[164:167], v[188:191], v[36:39]
	v_mfma_f32_16x16x32_bf16 v[32:35], v[172:175], v[188:191], v[32:35]
	v_mfma_f32_16x16x32_bf16 v[20:23], v[164:167], v[196:199], v[20:23]
	v_mfma_f32_16x16x32_bf16 v[16:19], v[172:175], v[196:199], v[16:19]
	v_mfma_f32_16x16x32_bf16 v[4:7], v[164:167], v[204:207], v[4:7]
	v_mfma_f32_16x16x32_bf16 v[0:3], v[172:175], v[204:207], v[0:3]
	v_mfma_f32_16x16x32_bf16 v[52:55], v[168:171], v[184:187], v[52:55]
	v_mfma_f32_16x16x32_bf16 v[48:51], v[176:179], v[184:187], v[48:51]
	v_mfma_f32_16x16x32_bf16 v[36:39], v[168:171], v[192:195], v[36:39]
	v_mfma_f32_16x16x32_bf16 v[32:35], v[176:179], v[192:195], v[32:35]
	v_mfma_f32_16x16x32_bf16 v[20:23], v[168:171], v[200:203], v[20:23]
	v_mfma_f32_16x16x32_bf16 v[16:19], v[176:179], v[200:203], v[16:19]
	v_mfma_f32_16x16x32_bf16 v[4:7], v[168:171], v[208:211], v[4:7]
	v_mfma_f32_16x16x32_bf16 v[0:3], v[176:179], v[208:211], v[0:3]
	s_setprio 0
	s_barrier
	s_add_i32 s72, s72, 2
	s_add_u32 s62, s62, 0x100
	s_addc_u32 s63, s63, 0
	s_add_u32 s70, s70, 0x100
	s_addc_u32 s71, s71, 0
	s_cmp_gt_u32 s72, 29
	s_cbranch_scc0 .LBB0_2713
	s_and_b64 vcc, exec, s[58:59]
	s_cbranch_vccz .LBB0_2716
	s_barrier

.LBB0_2805:
	ds_read_b128 v[146:149], v155
	ds_read_b128 v[160:163], v155 offset:1024
	ds_read_b128 v[164:167], v155 offset:2048
	ds_read_b128 v[168:171], v155 offset:3072
	ds_read_b128 v[172:175], v156
	ds_read_b128 v[176:179], v156 offset:1024
	ds_read_b128 v[180:183], v156 offset:2048
	ds_read_b128 v[184:187], v156 offset:3072
	s_add_u32 s8, s48, 0xfff80080
	s_addc_u32 s9, s49, -1
	s_cmp_eq_u32 s67, 28
	s_cselect_b32 s61, s21, s9
	s_cselect_b32 s60, s43, s8
	s_cselect_b32 s57, s19, s66
	s_cselect_b32 s56, s45, s65
	v_lshl_add_u64 v[220:221], s[48:49], 0, v[138:139]
	s_add_i32 m0, s29, 0xc000
	ds_read_b128 v[188:191], v157
	ds_read_b128 v[192:195], v157 offset:1024
	ds_read_b128 v[196:199], v157 offset:2048
	ds_read_b128 v[200:203], v157 offset:3072
	ds_read_b128 v[204:207], v157 offset:4096
	ds_read_b128 v[208:211], v157 offset:5120
	ds_read_b128 v[212:215], v157 offset:6144
	ds_read_b128 v[216:219], v157 offset:7168
	global_load_lds_dwordx4 v[220:221], off
	v_lshl_add_u64 v[220:221], s[48:49], 0, v[140:141]
	s_add_i32 m0, s29, 0xe000
	s_nop 0
	global_load_lds_dwordx4 v[220:221], off
	s_waitcnt vmcnt(8)
	s_waitcnt lgkmcnt(0)
	s_barrier
	s_setprio 1
	v_mfma_f32_16x16x32_bf16 v[124:127], v[146:149], v[188:191], v[124:127]
	v_mfma_f32_16x16x32_bf16 v[120:123], v[164:167], v[188:191], v[120:123]
	v_mfma_f32_16x16x32_bf16 v[108:111], v[146:149], v[196:199], v[108:111]
	v_mfma_f32_16x16x32_bf16 v[104:107], v[164:167], v[196:199], v[104:107]
	v_mfma_f32_16x16x32_bf16 v[92:95], v[146:149], v[204:207], v[92:95]
	v_mfma_f32_16x16x32_bf16 v[88:91], v[164:167], v[204:207], v[88:91]
	v_mfma_f32_16x16x32_bf16 v[76:79], v[146:149], v[212:215], v[76:79]
	v_mfma_f32_16x16x32_bf16 v[72:75], v[164:167], v[212:215], v[72:75]
	v_mfma_f32_16x16x32_bf16 v[124:127], v[160:163], v[192:195], v[124:127]
	v_mfma_f32_16x16x32_bf16 v[120:123], v[168:171], v[192:195], v[120:123]
	v_mfma_f32_16x16x32_bf16 v[108:111], v[160:163], v[200:203], v[108:111]
	v_mfma_f32_16x16x32_bf16 v[104:107], v[168:171], v[200:203], v[104:107]
	v_mfma_f32_16x16x32_bf16 v[92:95], v[160:163], v[208:211], v[92:95]
	v_mfma_f32_16x16x32_bf16 v[88:91], v[168:171], v[208:211], v[88:91]
	v_mfma_f32_16x16x32_bf16 v[76:79], v[160:163], v[216:219], v[76:79]
	v_mfma_f32_16x16x32_bf16 v[72:75], v[168:171], v[216:219], v[72:75]
	v_mfma_f32_16x16x32_bf16 v[116:119], v[172:175], v[188:191], v[116:119]
	v_mfma_f32_16x16x32_bf16 v[112:115], v[180:183], v[188:191], v[112:115]
	v_mfma_f32_16x16x32_bf16 v[100:103], v[172:175], v[196:199], v[100:103]
	v_mfma_f32_16x16x32_bf16 v[96:99], v[180:183], v[196:199], v[96:99]
	v_mfma_f32_16x16x32_bf16 v[84:87], v[172:175], v[204:207], v[84:87]
	v_mfma_f32_16x16x32_bf16 v[80:83], v[180:183], v[204:207], v[80:83]
	v_mfma_f32_16x16x32_bf16 v[68:71], v[172:175], v[212:215], v[68:71]
	v_mfma_f32_16x16x32_bf16 v[64:67], v[180:183], v[212:215], v[64:67]
	v_mfma_f32_16x16x32_bf16 v[116:119], v[176:179], v[192:195], v[116:119]
	v_mfma_f32_16x16x32_bf16 v[112:115], v[184:187], v[192:195], v[112:115]
	v_mfma_f32_16x16x32_bf16 v[100:103], v[176:179], v[200:203], v[100:103]
	v_mfma_f32_16x16x32_bf16 v[96:99], v[184:187], v[200:203], v[96:99]
	v_mfma_f32_16x16x32_bf16 v[84:87], v[176:179], v[208:211], v[84:87]
	v_mfma_f32_16x16x32_bf16 v[80:83], v[184:187], v[208:211], v[80:83]
	v_mfma_f32_16x16x32_bf16 v[68:71], v[176:179], v[216:219], v[68:71]
	v_mfma_f32_16x16x32_bf16 v[64:67], v[184:187], v[216:219], v[64:67]
	s_setprio 0
	s_barrier
	s_add_i32 s8, s63, s94
	v_lshl_add_u64 v[220:221], s[56:57], 0, v[130:131]
	s_mov_b32 m0, s8
	ds_read_b128 v[188:191], v157 offset:16384
	ds_read_b128 v[192:195], v157 offset:17408
	ds_read_b128 v[196:199], v157 offset:18432
	ds_read_b128 v[200:203], v157 offset:19456
	ds_read_b128 v[204:207], v157 offset:20480
	ds_read_b128 v[208:211], v157 offset:21504
	ds_read_b128 v[212:215], v157 offset:22528
	ds_read_b128 v[216:219], v157 offset:23552
	global_load_lds_dwordx4 v[220:221], off
	s_add_i32 m0, s8, 0x2000
	s_add_u32 s68, s56, 0x80000
	v_lshl_add_u64 v[222:223], s[56:57], 0, v[134:135]
	s_addc_u32 s69, s57, 0
	s_add_i32 s8, s64, s94
	global_load_lds_dwordx4 v[222:223], off
	v_lshl_add_u64 v[224:225], s[68:69], 0, v[130:131]
	s_mov_b32 m0, s8
	v_lshl_add_u64 v[226:227], s[60:61], 0, v[132:133]
	global_load_lds_dwordx4 v[224:225], off
	v_lshl_add_u64 v[224:225], s[68:69], 0, v[134:135]
	s_add_i32 m0, s8, 0x2000
	s_nop 0
	global_load_lds_dwordx4 v[224:225], off
	v_lshl_add_u64 v[224:225], s[60:61], 0, v[128:129]
	s_mov_b32 m0, s29
	s_nop 0
	global_load_lds_dwordx4 v[224:225], off
	s_mov_b32 m0, s30
	s_nop 0
	global_load_lds_dwordx4 v[226:227], off
	s_waitcnt vmcnt(8)
	s_waitcnt lgkmcnt(0)
	s_barrier
	s_setprio 1
	v_mfma_f32_16x16x32_bf16 v[60:63], v[146:149], v[188:191], v[60:63]
	v_mfma_f32_16x16x32_bf16 v[56:59], v[164:167], v[188:191], v[56:59]
	v_mfma_f32_16x16x32_bf16 v[44:47], v[146:149], v[196:199], v[44:47]
	v_mfma_f32_16x16x32_bf16 v[40:43], v[164:167], v[196:199], v[40:43]
	v_mfma_f32_16x16x32_bf16 v[28:31], v[146:149], v[204:207], v[28:31]
	v_mfma_f32_16x16x32_bf16 v[24:27], v[164:167], v[204:207], v[24:27]
	v_mfma_f32_16x16x32_bf16 v[12:15], v[146:149], v[212:215], v[12:15]
	v_mfma_f32_16x16x32_bf16 v[8:11], v[164:167], v[212:215], v[8:11]
	v_mfma_f32_16x16x32_bf16 v[60:63], v[160:163], v[192:195], v[60:63]
	v_mfma_f32_16x16x32_bf16 v[56:59], v[168:171], v[192:195], v[56:59]
	v_mfma_f32_16x16x32_bf16 v[44:47], v[160:163], v[200:203], v[44:47]
	v_mfma_f32_16x16x32_bf16 v[40:43], v[168:171], v[200:203], v[40:43]
	v_mfma_f32_16x16x32_bf16 v[28:31], v[160:163], v[208:211], v[28:31]
	v_mfma_f32_16x16x32_bf16 v[24:27], v[168:171], v[208:211], v[24:27]
	v_mfma_f32_16x16x32_bf16 v[12:15], v[160:163], v[216:219], v[12:15]
	v_mfma_f32_16x16x32_bf16 v[8:11], v[168:171], v[216:219], v[8:11]
	v_mfma_f32_16x16x32_bf16 v[52:55], v[172:175], v[188:191], v[52:55]
	v_mfma_f32_16x16x32_bf16 v[48:51], v[180:183], v[188:191], v[48:51]
	v_mfma_f32_16x16x32_bf16 v[36:39], v[172:175], v[196:199], v[36:39]
	v_mfma_f32_16x16x32_bf16 v[32:35], v[180:183], v[196:199], v[32:35]
	v_mfma_f32_16x16x32_bf16 v[20:23], v[172:175], v[204:207], v[20:23]
	v_mfma_f32_16x16x32_bf16 v[16:19], v[180:183], v[204:207], v[16:19]
	v_mfma_f32_16x16x32_bf16 v[4:7], v[172:175], v[212:215], v[4:7]
	v_mfma_f32_16x16x32_bf16 v[0:3], v[180:183], v[212:215], v[0:3]
	v_mfma_f32_16x16x32_bf16 v[52:55], v[176:179], v[192:195], v[52:55]
	v_mfma_f32_16x16x32_bf16 v[48:51], v[184:187], v[192:195], v[48:51]
	v_mfma_f32_16x16x32_bf16 v[36:39], v[176:179], v[200:203], v[36:39]
	v_mfma_f32_16x16x32_bf16 v[32:35], v[184:187], v[200:203], v[32:35]
	v_mfma_f32_16x16x32_bf16 v[20:23], v[176:179], v[208:211], v[20:23]
	v_mfma_f32_16x16x32_bf16 v[16:19], v[184:187], v[208:211], v[16:19]
	v_mfma_f32_16x16x32_bf16 v[4:7], v[176:179], v[216:219], v[4:7]
	v_mfma_f32_16x16x32_bf16 v[0:3], v[184:187], v[216:219], v[0:3]
	s_setprio 0
	s_barrier
	s_add_i32 s8, 0, 0x18000
	v_add_u32_e32 v159, s8, v151
	s_add_i32 s9, 0, 0x1c000
	ds_read_b128 v[146:149], v159
	ds_read_b128 v[160:163], v159 offset:1024
	ds_read_b128 v[164:167], v159 offset:2048
	ds_read_b128 v[168:171], v159 offset:3072
	v_add_u32_e32 v159, s9, v151
	ds_read_b128 v[172:175], v159
	ds_read_b128 v[176:179], v159 offset:1024
	ds_read_b128 v[180:183], v159 offset:2048
	ds_read_b128 v[184:187], v159 offset:3072
	s_add_u32 s60, s60, 0x80000
	s_addc_u32 s61, s61, 0
	s_mov_b32 m0, s34
	v_lshl_add_u64 v[228:229], s[60:61], 0, v[128:129]
	ds_read_b128 v[188:191], v157 offset:32768
	ds_read_b128 v[192:195], v157 offset:33792
	ds_read_b128 v[196:199], v157 offset:34816
	ds_read_b128 v[200:203], v157 offset:35840
	ds_read_b128 v[204:207], v157 offset:36864
	ds_read_b128 v[208:211], v157 offset:37888
	ds_read_b128 v[212:215], v157 offset:38912
	ds_read_b128 v[216:219], v157 offset:39936
	global_load_lds_dwordx4 v[228:229], off
	v_lshl_add_u64 v[228:229], s[60:61], 0, v[132:133]
	s_mov_b32 m0, s35
	s_nop 0
	global_load_lds_dwordx4 v[228:229], off
	s_waitcnt vmcnt(8)
	s_waitcnt lgkmcnt(0)
	s_barrier
	s_setprio 1
	v_mfma_f32_16x16x32_bf16 v[124:127], v[146:149], v[188:191], v[124:127]
	v_mfma_f32_16x16x32_bf16 v[120:123], v[164:167], v[188:191], v[120:123]
	v_mfma_f32_16x16x32_bf16 v[108:111], v[146:149], v[196:199], v[108:111]
	v_mfma_f32_16x16x32_bf16 v[104:107], v[164:167], v[196:199], v[104:107]
	v_mfma_f32_16x16x32_bf16 v[92:95], v[146:149], v[204:207], v[92:95]
	v_mfma_f32_16x16x32_bf16 v[88:91], v[164:167], v[204:207], v[88:91]
	v_mfma_f32_16x16x32_bf16 v[76:79], v[146:149], v[212:215], v[76:79]
	v_mfma_f32_16x16x32_bf16 v[72:75], v[164:167], v[212:215], v[72:75]
	v_mfma_f32_16x16x32_bf16 v[124:127], v[160:163], v[192:195], v[124:127]
	v_mfma_f32_16x16x32_bf16 v[120:123], v[168:171], v[192:195], v[120:123]
	v_mfma_f32_16x16x32_bf16 v[108:111], v[160:163], v[200:203], v[108:111]
	v_mfma_f32_16x16x32_bf16 v[104:107], v[168:171], v[200:203], v[104:107]
	v_mfma_f32_16x16x32_bf16 v[92:95], v[160:163], v[208:211], v[92:95]
	v_mfma_f32_16x16x32_bf16 v[88:91], v[168:171], v[208:211], v[88:91]
	v_mfma_f32_16x16x32_bf16 v[76:79], v[160:163], v[216:219], v[76:79]
	v_mfma_f32_16x16x32_bf16 v[72:75], v[168:171], v[216:219], v[72:75]
	v_mfma_f32_16x16x32_bf16 v[116:119], v[172:175], v[188:191], v[116:119]
	v_mfma_f32_16x16x32_bf16 v[112:115], v[180:183], v[188:191], v[112:115]
	v_mfma_f32_16x16x32_bf16 v[100:103], v[172:175], v[196:199], v[100:103]
	v_mfma_f32_16x16x32_bf16 v[96:99], v[180:183], v[196:199], v[96:99]
	v_mfma_f32_16x16x32_bf16 v[84:87], v[172:175], v[204:207], v[84:87]
	v_mfma_f32_16x16x32_bf16 v[80:83], v[180:183], v[204:207], v[80:83]
	v_mfma_f32_16x16x32_bf16 v[68:71], v[172:175], v[212:215], v[68:71]
	v_mfma_f32_16x16x32_bf16 v[64:67], v[180:183], v[212:215], v[64:67]
	v_mfma_f32_16x16x32_bf16 v[116:119], v[176:179], v[192:195], v[116:119]
	v_mfma_f32_16x16x32_bf16 v[112:115], v[184:187], v[192:195], v[112:115]
	v_mfma_f32_16x16x32_bf16 v[100:103], v[176:179], v[200:203], v[100:103]
	v_mfma_f32_16x16x32_bf16 v[96:99], v[184:187], v[200:203], v[96:99]
	v_mfma_f32_16x16x32_bf16 v[84:87], v[176:179], v[208:211], v[84:87]
	v_mfma_f32_16x16x32_bf16 v[80:83], v[184:187], v[208:211], v[80:83]
	v_mfma_f32_16x16x32_bf16 v[68:71], v[176:179], v[216:219], v[68:71]
	v_mfma_f32_16x16x32_bf16 v[64:67], v[184:187], v[216:219], v[64:67]
	s_setprio 0
	s_barrier
	s_add_i32 s8, s8, s94
	v_lshl_add_u64 v[220:221], v[220:221], 0, s[16:17]
	s_mov_b32 m0, s8
	ds_read_b128 v[188:191], v157 offset:49152
	ds_read_b128 v[192:195], v157 offset:50176
	ds_read_b128 v[196:199], v157 offset:51200
	ds_read_b128 v[200:203], v157 offset:52224
	ds_read_b128 v[204:207], v157 offset:53248
	ds_read_b128 v[208:211], v157 offset:54272
	ds_read_b128 v[212:215], v157 offset:55296
	ds_read_b128 v[216:219], v157 offset:56320
	global_load_lds_dwordx4 v[220:221], off
	s_add_i32 m0, s8, 0x2000
	s_add_u32 s56, s56, 0x80080
	v_lshl_add_u64 v[220:221], v[222:223], 0, s[16:17]
	s_addc_u32 s57, s57, 0
	s_add_i32 s8, s9, s94
	global_load_lds_dwordx4 v[220:221], off
	v_lshl_add_u64 v[220:221], s[56:57], 0, v[130:131]
	s_mov_b32 m0, s8
	s_nop 0
	global_load_lds_dwordx4 v[220:221], off
	v_lshl_add_u64 v[220:221], s[56:57], 0, v[134:135]
	s_add_i32 m0, s8, 0x2000
	s_nop 0
	global_load_lds_dwordx4 v[220:221], off
	v_lshl_add_u64 v[220:221], v[224:225], 0, s[16:17]
	s_mov_b32 m0, s47
	s_nop 0
	global_load_lds_dwordx4 v[220:221], off
	v_lshl_add_u64 v[220:221], v[226:227], 0, s[16:17]
	s_mov_b32 m0, s62
	s_nop 0
	global_load_lds_dwordx4 v[220:221], off
	s_waitcnt vmcnt(8)
	s_waitcnt lgkmcnt(0)
	s_barrier
	s_setprio 1
	v_mfma_f32_16x16x32_bf16 v[60:63], v[146:149], v[188:191], v[60:63]
	v_mfma_f32_16x16x32_bf16 v[56:59], v[164:167], v[188:191], v[56:59]
	v_mfma_f32_16x16x32_bf16 v[44:47], v[146:149], v[196:199], v[44:47]
	v_mfma_f32_16x16x32_bf16 v[40:43], v[164:167], v[196:199], v[40:43]
	v_mfma_f32_16x16x32_bf16 v[28:31], v[146:149], v[204:207], v[28:31]
	v_mfma_f32_16x16x32_bf16 v[24:27], v[164:167], v[204:207], v[24:27]
	v_mfma_f32_16x16x32_bf16 v[12:15], v[146:149], v[212:215], v[12:15]
	v_mfma_f32_16x16x32_bf16 v[8:11], v[164:167], v[212:215], v[8:11]
	v_mfma_f32_16x16x32_bf16 v[60:63], v[160:163], v[192:195], v[60:63]
	v_mfma_f32_16x16x32_bf16 v[56:59], v[168:171], v[192:195], v[56:59]
	v_mfma_f32_16x16x32_bf16 v[44:47], v[160:163], v[200:203], v[44:47]
	v_mfma_f32_16x16x32_bf16 v[40:43], v[168:171], v[200:203], v[40:43]
	v_mfma_f32_16x16x32_bf16 v[28:31], v[160:163], v[208:211], v[28:31]
	v_mfma_f32_16x16x32_bf16 v[24:27], v[168:171], v[208:211], v[24:27]
	v_mfma_f32_16x16x32_bf16 v[12:15], v[160:163], v[216:219], v[12:15]
	v_mfma_f32_16x16x32_bf16 v[8:11], v[168:171], v[216:219], v[8:11]
	v_mfma_f32_16x16x32_bf16 v[52:55], v[172:175], v[188:191], v[52:55]
	v_mfma_f32_16x16x32_bf16 v[48:51], v[180:183], v[188:191], v[48:51]
	v_mfma_f32_16x16x32_bf16 v[36:39], v[172:175], v[196:199], v[36:39]
	v_mfma_f32_16x16x32_bf16 v[32:35], v[180:183], v[196:199], v[32:35]
	v_mfma_f32_16x16x32_bf16 v[20:23], v[172:175], v[204:207], v[20:23]
	v_mfma_f32_16x16x32_bf16 v[16:19], v[180:183], v[204:207], v[16:19]
	v_mfma_f32_16x16x32_bf16 v[4:7], v[172:175], v[212:215], v[4:7]
	v_mfma_f32_16x16x32_bf16 v[0:3], v[180:183], v[212:215], v[0:3]
	v_mfma_f32_16x16x32_bf16 v[52:55], v[176:179], v[192:195], v[52:55]
	v_mfma_f32_16x16x32_bf16 v[48:51], v[184:187], v[192:195], v[48:51]
	v_mfma_f32_16x16x32_bf16 v[36:39], v[176:179], v[200:203], v[36:39]
	v_mfma_f32_16x16x32_bf16 v[32:35], v[184:187], v[200:203], v[32:35]
	v_mfma_f32_16x16x32_bf16 v[20:23], v[176:179], v[208:211], v[20:23]
	v_mfma_f32_16x16x32_bf16 v[16:19], v[184:187], v[208:211], v[16:19]
	v_mfma_f32_16x16x32_bf16 v[4:7], v[176:179], v[216:219], v[4:7]
	v_mfma_f32_16x16x32_bf16 v[0:3], v[184:187], v[216:219], v[0:3]
	s_setprio 0
	s_barrier
	s_add_i32 s67, s67, 2
	s_add_u32 s48, s48, 0x100
	s_addc_u32 s49, s49, 0
	s_add_u32 s65, s65, 0x100
	s_addc_u32 s66, s66, 0
	s_cmp_gt_u32 s67, 29
	s_cbranch_scc0 .LBB0_2805
	s_and_b64 vcc, exec, s[58:59]
	s_cbranch_vccz .LBB0_2808
	s_barrier

.LBB0_2917:
	ds_read_b128 v[140:143], v149
	ds_read_b128 v[152:155], v149 offset:1024
	ds_read_b128 v[156:159], v149 offset:2048
	ds_read_b128 v[160:163], v149 offset:3072
	ds_read_b128 v[164:167], v150
	ds_read_b128 v[168:171], v150 offset:1024
	ds_read_b128 v[172:175], v150 offset:2048
	ds_read_b128 v[176:179], v150 offset:3072
	s_add_u32 s42, s40, 0xffe00080
	s_addc_u32 s43, s41, -1
	s_cmpk_eq_i32 s64, 0x7c
	s_cselect_b32 s45, s21, s43
	s_cselect_b32 s44, s39, s42
	s_cselect_b32 s43, s19, s63
	s_cselect_b32 s42, s61, s62
	v_lshl_add_u64 v[212:213], s[40:41], 0, v[132:133]
	s_add_i32 m0, s29, 0xc000
	ds_read_b128 v[180:183], v151
	ds_read_b128 v[184:187], v151 offset:1024
	ds_read_b128 v[188:191], v151 offset:2048
	ds_read_b128 v[192:195], v151 offset:3072
	ds_read_b128 v[196:199], v151 offset:4096
	ds_read_b128 v[200:203], v151 offset:5120
	ds_read_b128 v[204:207], v151 offset:6144
	ds_read_b128 v[208:211], v151 offset:7168
	global_load_lds_dwordx4 v[212:213], off
	v_lshl_add_u64 v[212:213], s[40:41], 0, v[134:135]
	s_add_i32 m0, s29, 0xe000
	s_nop 0
	global_load_lds_dwordx4 v[212:213], off
	s_waitcnt vmcnt(8)
	s_waitcnt lgkmcnt(0)
	s_barrier
	s_setprio 1
	v_mfma_f32_16x16x32_bf16 v[124:127], v[140:143], v[180:183], v[124:127]
	v_mfma_f32_16x16x32_bf16 v[120:123], v[156:159], v[180:183], v[120:123]
	v_mfma_f32_16x16x32_bf16 v[108:111], v[140:143], v[188:191], v[108:111]
	v_mfma_f32_16x16x32_bf16 v[104:107], v[156:159], v[188:191], v[104:107]
	v_mfma_f32_16x16x32_bf16 v[92:95], v[140:143], v[196:199], v[92:95]
	v_mfma_f32_16x16x32_bf16 v[88:91], v[156:159], v[196:199], v[88:91]
	v_mfma_f32_16x16x32_bf16 v[76:79], v[140:143], v[204:207], v[76:79]
	v_mfma_f32_16x16x32_bf16 v[72:75], v[156:159], v[204:207], v[72:75]
	v_mfma_f32_16x16x32_bf16 v[124:127], v[152:155], v[184:187], v[124:127]
	v_mfma_f32_16x16x32_bf16 v[120:123], v[160:163], v[184:187], v[120:123]
	v_mfma_f32_16x16x32_bf16 v[108:111], v[152:155], v[192:195], v[108:111]
	v_mfma_f32_16x16x32_bf16 v[104:107], v[160:163], v[192:195], v[104:107]
	v_mfma_f32_16x16x32_bf16 v[92:95], v[152:155], v[200:203], v[92:95]
	v_mfma_f32_16x16x32_bf16 v[88:91], v[160:163], v[200:203], v[88:91]
	v_mfma_f32_16x16x32_bf16 v[76:79], v[152:155], v[208:211], v[76:79]
	v_mfma_f32_16x16x32_bf16 v[72:75], v[160:163], v[208:211], v[72:75]
	v_mfma_f32_16x16x32_bf16 v[116:119], v[164:167], v[180:183], v[116:119]
	v_mfma_f32_16x16x32_bf16 v[112:115], v[172:175], v[180:183], v[112:115]
	v_mfma_f32_16x16x32_bf16 v[100:103], v[164:167], v[188:191], v[100:103]
	v_mfma_f32_16x16x32_bf16 v[96:99], v[172:175], v[188:191], v[96:99]
	v_mfma_f32_16x16x32_bf16 v[84:87], v[164:167], v[196:199], v[84:87]
	v_mfma_f32_16x16x32_bf16 v[80:83], v[172:175], v[196:199], v[80:83]
	v_mfma_f32_16x16x32_bf16 v[68:71], v[164:167], v[204:207], v[68:71]
	v_mfma_f32_16x16x32_bf16 v[64:67], v[172:175], v[204:207], v[64:67]
	v_mfma_f32_16x16x32_bf16 v[116:119], v[168:171], v[184:187], v[116:119]
	v_mfma_f32_16x16x32_bf16 v[112:115], v[176:179], v[184:187], v[112:115]
	v_mfma_f32_16x16x32_bf16 v[100:103], v[168:171], v[192:195], v[100:103]
	v_mfma_f32_16x16x32_bf16 v[96:99], v[176:179], v[192:195], v[96:99]
	v_mfma_f32_16x16x32_bf16 v[84:87], v[168:171], v[200:203], v[84:87]
	v_mfma_f32_16x16x32_bf16 v[80:83], v[176:179], v[200:203], v[80:83]
	v_mfma_f32_16x16x32_bf16 v[68:71], v[168:171], v[208:211], v[68:71]
	v_mfma_f32_16x16x32_bf16 v[64:67], v[176:179], v[208:211], v[64:67]
	s_setprio 0
	s_barrier
	s_add_i32 s65, s56, s94
	v_lshl_add_u64 v[212:213], s[42:43], 0, v[128:129]
	s_mov_b32 m0, s65
	ds_read_b128 v[180:183], v151 offset:16384
	ds_read_b128 v[184:187], v151 offset:17408
	ds_read_b128 v[188:191], v151 offset:18432
	ds_read_b128 v[192:195], v151 offset:19456
	ds_read_b128 v[196:199], v151 offset:20480
	ds_read_b128 v[200:203], v151 offset:21504
	ds_read_b128 v[204:207], v151 offset:22528
	ds_read_b128 v[208:211], v151 offset:23552
	global_load_lds_dwordx4 v[212:213], off
	s_add_i32 m0, s65, 0x2000
	s_add_u32 s66, s42, 0x200000
	v_lshl_add_u64 v[214:215], s[42:43], 0, v[130:131]
	s_addc_u32 s67, s43, 0
	s_add_i32 s65, s57, s94
	global_load_lds_dwordx4 v[214:215], off
	v_lshl_add_u64 v[216:217], s[66:67], 0, v[128:129]
	s_mov_b32 m0, s65
	v_lshl_add_u64 v[218:219], s[44:45], 0, v[130:131]
	global_load_lds_dwordx4 v[216:217], off
	v_lshl_add_u64 v[216:217], s[66:67], 0, v[130:131]
	s_add_i32 m0, s65, 0x2000
	s_nop 0
	global_load_lds_dwordx4 v[216:217], off
	v_lshl_add_u64 v[216:217], s[44:45], 0, v[128:129]
	s_mov_b32 m0, s29
	s_nop 0
	global_load_lds_dwordx4 v[216:217], off
	s_mov_b32 m0, s30
	s_nop 0
	global_load_lds_dwordx4 v[218:219], off
	s_waitcnt vmcnt(8)
	s_waitcnt lgkmcnt(0)
	s_barrier
	s_setprio 1
	v_mfma_f32_16x16x32_bf16 v[60:63], v[140:143], v[180:183], v[60:63]
	v_mfma_f32_16x16x32_bf16 v[56:59], v[156:159], v[180:183], v[56:59]
	v_mfma_f32_16x16x32_bf16 v[44:47], v[140:143], v[188:191], v[44:47]
	v_mfma_f32_16x16x32_bf16 v[40:43], v[156:159], v[188:191], v[40:43]
	v_mfma_f32_16x16x32_bf16 v[28:31], v[140:143], v[196:199], v[28:31]
	v_mfma_f32_16x16x32_bf16 v[24:27], v[156:159], v[196:199], v[24:27]
	v_mfma_f32_16x16x32_bf16 v[12:15], v[140:143], v[204:207], v[12:15]
	v_mfma_f32_16x16x32_bf16 v[8:11], v[156:159], v[204:207], v[8:11]
	v_mfma_f32_16x16x32_bf16 v[60:63], v[152:155], v[184:187], v[60:63]
	v_mfma_f32_16x16x32_bf16 v[56:59], v[160:163], v[184:187], v[56:59]
	v_mfma_f32_16x16x32_bf16 v[44:47], v[152:155], v[192:195], v[44:47]
	v_mfma_f32_16x16x32_bf16 v[40:43], v[160:163], v[192:195], v[40:43]
	v_mfma_f32_16x16x32_bf16 v[28:31], v[152:155], v[200:203], v[28:31]
	v_mfma_f32_16x16x32_bf16 v[24:27], v[160:163], v[200:203], v[24:27]
	v_mfma_f32_16x16x32_bf16 v[12:15], v[152:155], v[208:211], v[12:15]
	v_mfma_f32_16x16x32_bf16 v[8:11], v[160:163], v[208:211], v[8:11]
	v_mfma_f32_16x16x32_bf16 v[52:55], v[164:167], v[180:183], v[52:55]
	v_mfma_f32_16x16x32_bf16 v[48:51], v[172:175], v[180:183], v[48:51]
	v_mfma_f32_16x16x32_bf16 v[36:39], v[164:167], v[188:191], v[36:39]
	v_mfma_f32_16x16x32_bf16 v[32:35], v[172:175], v[188:191], v[32:35]
	v_mfma_f32_16x16x32_bf16 v[20:23], v[164:167], v[196:199], v[20:23]
	v_mfma_f32_16x16x32_bf16 v[16:19], v[172:175], v[196:199], v[16:19]
	v_mfma_f32_16x16x32_bf16 v[4:7], v[164:167], v[204:207], v[4:7]
	v_mfma_f32_16x16x32_bf16 v[0:3], v[172:175], v[204:207], v[0:3]
	v_mfma_f32_16x16x32_bf16 v[52:55], v[168:171], v[184:187], v[52:55]
	v_mfma_f32_16x16x32_bf16 v[48:51], v[176:179], v[184:187], v[48:51]
	v_mfma_f32_16x16x32_bf16 v[36:39], v[168:171], v[192:195], v[36:39]
	v_mfma_f32_16x16x32_bf16 v[32:35], v[176:179], v[192:195], v[32:35]
	v_mfma_f32_16x16x32_bf16 v[20:23], v[168:171], v[200:203], v[20:23]
	v_mfma_f32_16x16x32_bf16 v[16:19], v[176:179], v[200:203], v[16:19]
	v_mfma_f32_16x16x32_bf16 v[4:7], v[168:171], v[208:211], v[4:7]
	v_mfma_f32_16x16x32_bf16 v[0:3], v[176:179], v[208:211], v[0:3]
	s_setprio 0
	s_barrier
	s_add_i32 s65, 0, 0x18000
	s_add_i32 s66, 0, 0x1c000
	v_add_u32_e32 v160, s65, v145
	v_add_u32_e32 v176, s66, v145
	ds_read_b128 v[140:143], v160
	ds_read_b128 v[152:155], v160 offset:1024
	ds_read_b128 v[156:159], v160 offset:2048
	ds_read_b128 v[160:163], v160 offset:3072
	ds_read_b128 v[164:167], v176
	ds_read_b128 v[168:171], v176 offset:1024
	ds_read_b128 v[172:175], v176 offset:2048
	ds_read_b128 v[176:179], v176 offset:3072
	s_add_u32 s44, s44, 0x200000
	s_addc_u32 s45, s45, 0
	s_mov_b32 m0, s46
	v_lshl_add_u64 v[220:221], s[44:45], 0, v[128:129]
	ds_read_b128 v[180:183], v151 offset:32768
	ds_read_b128 v[184:187], v151 offset:33792
	ds_read_b128 v[188:191], v151 offset:34816
	ds_read_b128 v[192:195], v151 offset:35840
	ds_read_b128 v[196:199], v151 offset:36864
	ds_read_b128 v[200:203], v151 offset:37888
	ds_read_b128 v[204:207], v151 offset:38912
	ds_read_b128 v[208:211], v151 offset:39936
	global_load_lds_dwordx4 v[220:221], off
	v_lshl_add_u64 v[220:221], s[44:45], 0, v[130:131]
	s_mov_b32 m0, s47
	s_nop 0
	global_load_lds_dwordx4 v[220:221], off
	s_waitcnt vmcnt(8)
	s_waitcnt lgkmcnt(0)
	s_barrier
	s_setprio 1
	v_mfma_f32_16x16x32_bf16 v[124:127], v[140:143], v[180:183], v[124:127]
	v_mfma_f32_16x16x32_bf16 v[120:123], v[156:159], v[180:183], v[120:123]
	v_mfma_f32_16x16x32_bf16 v[108:111], v[140:143], v[188:191], v[108:111]
	v_mfma_f32_16x16x32_bf16 v[104:107], v[156:159], v[188:191], v[104:107]
	v_mfma_f32_16x16x32_bf16 v[92:95], v[140:143], v[196:199], v[92:95]
	v_mfma_f32_16x16x32_bf16 v[88:91], v[156:159], v[196:199], v[88:91]
	v_mfma_f32_16x16x32_bf16 v[76:79], v[140:143], v[204:207], v[76:79]
	v_mfma_f32_16x16x32_bf16 v[72:75], v[156:159], v[204:207], v[72:75]
	v_mfma_f32_16x16x32_bf16 v[124:127], v[152:155], v[184:187], v[124:127]
	v_mfma_f32_16x16x32_bf16 v[120:123], v[160:163], v[184:187], v[120:123]
	v_mfma_f32_16x16x32_bf16 v[108:111], v[152:155], v[192:195], v[108:111]
	v_mfma_f32_16x16x32_bf16 v[104:107], v[160:163], v[192:195], v[104:107]
	v_mfma_f32_16x16x32_bf16 v[92:95], v[152:155], v[200:203], v[92:95]
	v_mfma_f32_16x16x32_bf16 v[88:91], v[160:163], v[200:203], v[88:91]
	v_mfma_f32_16x16x32_bf16 v[76:79], v[152:155], v[208:211], v[76:79]
	v_mfma_f32_16x16x32_bf16 v[72:75], v[160:163], v[208:211], v[72:75]
	v_mfma_f32_16x16x32_bf16 v[116:119], v[164:167], v[180:183], v[116:119]
	v_mfma_f32_16x16x32_bf16 v[112:115], v[172:175], v[180:183], v[112:115]
	v_mfma_f32_16x16x32_bf16 v[100:103], v[164:167], v[188:191], v[100:103]
	v_mfma_f32_16x16x32_bf16 v[96:99], v[172:175], v[188:191], v[96:99]
	v_mfma_f32_16x16x32_bf16 v[84:87], v[164:167], v[196:199], v[84:87]
	v_mfma_f32_16x16x32_bf16 v[80:83], v[172:175], v[196:199], v[80:83]
	v_mfma_f32_16x16x32_bf16 v[68:71], v[164:167], v[204:207], v[68:71]
	v_mfma_f32_16x16x32_bf16 v[64:67], v[172:175], v[204:207], v[64:67]
	v_mfma_f32_16x16x32_bf16 v[116:119], v[168:171], v[184:187], v[116:119]
	v_mfma_f32_16x16x32_bf16 v[112:115], v[176:179], v[184:187], v[112:115]
	v_mfma_f32_16x16x32_bf16 v[100:103], v[168:171], v[192:195], v[100:103]
	v_mfma_f32_16x16x32_bf16 v[96:99], v[176:179], v[192:195], v[96:99]
	v_mfma_f32_16x16x32_bf16 v[84:87], v[168:171], v[200:203], v[84:87]
	v_mfma_f32_16x16x32_bf16 v[80:83], v[176:179], v[200:203], v[80:83]
	v_mfma_f32_16x16x32_bf16 v[68:71], v[168:171], v[208:211], v[68:71]
	v_mfma_f32_16x16x32_bf16 v[64:67], v[176:179], v[208:211], v[64:67]
	s_setprio 0
	s_barrier
	s_add_i32 s44, s65, s94
	v_lshl_add_u64 v[212:213], v[212:213], 0, s[16:17]
	s_mov_b32 m0, s44
	ds_read_b128 v[180:183], v151 offset:49152
	ds_read_b128 v[184:187], v151 offset:50176
	ds_read_b128 v[188:191], v151 offset:51200
	ds_read_b128 v[192:195], v151 offset:52224
	ds_read_b128 v[196:199], v151 offset:53248
	ds_read_b128 v[200:203], v151 offset:54272
	ds_read_b128 v[204:207], v151 offset:55296
	ds_read_b128 v[208:211], v151 offset:56320
	global_load_lds_dwordx4 v[212:213], off
	s_add_i32 m0, s44, 0x2000
	s_add_u32 s42, s42, 0x200080
	v_lshl_add_u64 v[212:213], v[214:215], 0, s[16:17]
	s_addc_u32 s43, s43, 0
	s_add_i32 s44, s66, s94
	global_load_lds_dwordx4 v[212:213], off
	v_lshl_add_u64 v[212:213], s[42:43], 0, v[128:129]
	s_mov_b32 m0, s44
	s_nop 0
	global_load_lds_dwordx4 v[212:213], off
	v_lshl_add_u64 v[212:213], s[42:43], 0, v[130:131]
	s_add_i32 m0, s44, 0x2000
	s_nop 0
	global_load_lds_dwordx4 v[212:213], off
	v_lshl_add_u64 v[212:213], v[216:217], 0, s[16:17]
	s_mov_b32 m0, s48
	s_nop 0
	global_load_lds_dwordx4 v[212:213], off
	v_lshl_add_u64 v[212:213], v[218:219], 0, s[16:17]
	s_mov_b32 m0, s49
	s_nop 0
	global_load_lds_dwordx4 v[212:213], off
	s_waitcnt vmcnt(8)
	s_waitcnt lgkmcnt(0)
	s_barrier
	s_setprio 1
	v_mfma_f32_16x16x32_bf16 v[60:63], v[140:143], v[180:183], v[60:63]
	v_mfma_f32_16x16x32_bf16 v[56:59], v[156:159], v[180:183], v[56:59]
	v_mfma_f32_16x16x32_bf16 v[44:47], v[140:143], v[188:191], v[44:47]
	v_mfma_f32_16x16x32_bf16 v[40:43], v[156:159], v[188:191], v[40:43]
	v_mfma_f32_16x16x32_bf16 v[28:31], v[140:143], v[196:199], v[28:31]
	v_mfma_f32_16x16x32_bf16 v[24:27], v[156:159], v[196:199], v[24:27]
	v_mfma_f32_16x16x32_bf16 v[12:15], v[140:143], v[204:207], v[12:15]
	v_mfma_f32_16x16x32_bf16 v[8:11], v[156:159], v[204:207], v[8:11]
	v_mfma_f32_16x16x32_bf16 v[60:63], v[152:155], v[184:187], v[60:63]
	v_mfma_f32_16x16x32_bf16 v[56:59], v[160:163], v[184:187], v[56:59]
	v_mfma_f32_16x16x32_bf16 v[44:47], v[152:155], v[192:195], v[44:47]
	v_mfma_f32_16x16x32_bf16 v[40:43], v[160:163], v[192:195], v[40:43]
	v_mfma_f32_16x16x32_bf16 v[28:31], v[152:155], v[200:203], v[28:31]
	v_mfma_f32_16x16x32_bf16 v[24:27], v[160:163], v[200:203], v[24:27]
	v_mfma_f32_16x16x32_bf16 v[12:15], v[152:155], v[208:211], v[12:15]
	v_mfma_f32_16x16x32_bf16 v[8:11], v[160:163], v[208:211], v[8:11]
	v_mfma_f32_16x16x32_bf16 v[52:55], v[164:167], v[180:183], v[52:55]
	v_mfma_f32_16x16x32_bf16 v[48:51], v[172:175], v[180:183], v[48:51]
	v_mfma_f32_16x16x32_bf16 v[36:39], v[164:167], v[188:191], v[36:39]
	v_mfma_f32_16x16x32_bf16 v[32:35], v[172:175], v[188:191], v[32:35]
	v_mfma_f32_16x16x32_bf16 v[20:23], v[164:167], v[196:199], v[20:23]
	v_mfma_f32_16x16x32_bf16 v[16:19], v[172:175], v[196:199], v[16:19]
	v_mfma_f32_16x16x32_bf16 v[4:7], v[164:167], v[204:207], v[4:7]
	v_mfma_f32_16x16x32_bf16 v[0:3], v[172:175], v[204:207], v[0:3]
	v_mfma_f32_16x16x32_bf16 v[52:55], v[168:171], v[184:187], v[52:55]
	v_mfma_f32_16x16x32_bf16 v[48:51], v[176:179], v[184:187], v[48:51]
	v_mfma_f32_16x16x32_bf16 v[36:39], v[168:171], v[192:195], v[36:39]
	v_mfma_f32_16x16x32_bf16 v[32:35], v[176:179], v[192:195], v[32:35]
	v_mfma_f32_16x16x32_bf16 v[20:23], v[168:171], v[200:203], v[20:23]
	v_mfma_f32_16x16x32_bf16 v[16:19], v[176:179], v[200:203], v[16:19]
	v_mfma_f32_16x16x32_bf16 v[4:7], v[168:171], v[208:211], v[4:7]
	v_mfma_f32_16x16x32_bf16 v[0:3], v[176:179], v[208:211], v[0:3]
	s_setprio 0
	s_barrier
	s_add_i32 s64, s64, 2
	s_add_u32 s40, s40, 0x100
	s_addc_u32 s41, s41, 0
	s_add_u32 s62, s62, 0x100
	s_addc_u32 s63, s63, 0
	s_cmpk_gt_u32 s64, 0x7d
	s_cbranch_scc0 .LBB0_2917
	s_and_b64 vcc, exec, s[58:59]
	s_cbranch_vccz .LBB0_2920
	s_barrier
